# GEMM k-loops: first MFMA group issued before the LDS-DMA block (DMA issue overlaps MFMA execution)
# baseline (speedup 1.0000x reference)
.LBB0_30:
	s_mul_i32 s44, s43, 0x6000
	s_add_i32 s45, s44, 0xffffa000
	s_cmp_gt_i32 s43, 0
	s_waitcnt vmcnt(6)
	s_cselect_b32 s45, s45, 0xc000
	s_waitcnt lgkmcnt(0)
	s_barrier
	s_setprio 2
	v_add3_u32 v0, s44, v177, v176
	v_add_u32_e32 v0, s55, v0
	v_add3_u32 v212, s44, v178, v176
	ds_read_b128 v[196:199], v212 offset:8192
	ds_read_b128 v[180:183], v0
	ds_read_b128 v[184:187], v0 offset:1024
	ds_read_b128 v[188:191], v0 offset:2048
	ds_read_b128 v[192:195], v0 offset:3072
	ds_read_b128 v[200:203], v212 offset:9216
	ds_read_b128 v[204:207], v212 offset:10240
	ds_read_b128 v[208:211], v212 offset:11264
	ds_read_b128 v[216:219], v212 offset:12288
	ds_read_b128 v[226:229], v212 offset:13312
	ds_read_b128 v[230:233], v212 offset:14336
	ds_read_b128 v[234:237], v212 offset:15360
	s_waitcnt lgkmcnt(10)
	v_mfma_f32_16x16x32_bf16 v[34:37], v[196:199], v[180:183], v[34:37]
	s_waitcnt lgkmcnt(9)
	v_mfma_f32_16x16x32_bf16 v[38:41], v[196:199], v[184:187], v[38:41]
	s_waitcnt lgkmcnt(8)
	v_mfma_f32_16x16x32_bf16 v[42:45], v[196:199], v[188:191], v[42:45]
	s_waitcnt lgkmcnt(7)
	v_mfma_f32_16x16x32_bf16 v[46:49], v[196:199], v[192:195], v[46:49]
	v_lshl_add_u64 v[212:213], v[174:175], 0, s[12:13]
	v_lshl_add_u64 v[212:213], v[162:163], 1, v[212:213]
	s_add_i32 s68, s45, s42
	s_mov_b32 m0, s68
	s_nop 0
	global_load_lds_dwordx4 v[212:213], off
	v_lshl_add_u64 v[212:213], v[174:175], 0, s[12:13]
	v_lshl_add_u64 v[212:213], v[164:165], 1, v[212:213]
	s_add_i32 s68, s45, s40
	s_mov_b32 m0, s68
	s_nop 0
	global_load_lds_dwordx4 v[212:213], off
	s_add_i32 s45, s41, s45
	v_lshl_add_u64 v[212:213], v[172:173], 0, s[12:13]
	s_mov_b32 m0, s45
	s_nop 0
	global_load_lds_dwordx4 v[212:213], off
	v_lshl_add_u64 v[212:213], v[170:171], 0, s[12:13]
	s_add_i32 s68, s45, 0x400
	s_mov_b32 m0, s68
	s_nop 0
	global_load_lds_dwordx4 v[212:213], off
	v_lshl_add_u64 v[212:213], v[168:169], 0, s[12:13]
	s_add_i32 s68, s45, 0x800
	s_mov_b32 m0, s68
	s_nop 0
	global_load_lds_dwordx4 v[212:213], off
	s_addk_i32 s45, 0xc00
	v_lshl_add_u64 v[212:213], v[166:167], 0, s[12:13]
	s_mov_b32 m0, s45
	s_nop 0
	global_load_lds_dwordx4 v[212:213], off
	s_setprio 0
	s_waitcnt lgkmcnt(6)
	v_mfma_f32_16x16x32_bf16 v[50:53], v[200:203], v[180:183], v[50:53]
	v_mfma_f32_16x16x32_bf16 v[54:57], v[200:203], v[184:187], v[54:57]
	v_mfma_f32_16x16x32_bf16 v[58:61], v[200:203], v[188:191], v[58:61]
	v_mfma_f32_16x16x32_bf16 v[62:65], v[200:203], v[192:195], v[62:65]
	s_waitcnt lgkmcnt(5)
	v_mfma_f32_16x16x32_bf16 v[66:69], v[204:207], v[180:183], v[66:69]
	v_mfma_f32_16x16x32_bf16 v[70:73], v[204:207], v[184:187], v[70:73]
	v_mfma_f32_16x16x32_bf16 v[74:77], v[204:207], v[188:191], v[74:77]
	v_mfma_f32_16x16x32_bf16 v[78:81], v[204:207], v[192:195], v[78:81]
	s_waitcnt lgkmcnt(4)
	v_mfma_f32_16x16x32_bf16 v[82:85], v[208:211], v[180:183], v[82:85]
	v_mfma_f32_16x16x32_bf16 v[86:89], v[208:211], v[184:187], v[86:89]
	v_mfma_f32_16x16x32_bf16 v[90:93], v[208:211], v[188:191], v[90:93]
	v_mfma_f32_16x16x32_bf16 v[94:97], v[208:211], v[192:195], v[94:97]
	s_waitcnt lgkmcnt(3)
	v_mfma_f32_16x16x32_bf16 v[98:101], v[216:219], v[180:183], v[98:101]
	v_mfma_f32_16x16x32_bf16 v[102:105], v[216:219], v[184:187], v[102:105]
	v_mfma_f32_16x16x32_bf16 v[106:109], v[216:219], v[188:191], v[106:109]
	v_mfma_f32_16x16x32_bf16 v[110:113], v[216:219], v[192:195], v[110:113]
	s_waitcnt lgkmcnt(2)
	v_mfma_f32_16x16x32_bf16 v[114:117], v[226:229], v[180:183], v[114:117]
	v_mfma_f32_16x16x32_bf16 v[118:121], v[226:229], v[184:187], v[118:121]
	v_mfma_f32_16x16x32_bf16 v[122:125], v[226:229], v[188:191], v[122:125]
	v_mfma_f32_16x16x32_bf16 v[126:129], v[226:229], v[192:195], v[126:129]
	s_waitcnt lgkmcnt(1)
	v_mfma_f32_16x16x32_bf16 v[130:133], v[230:233], v[180:183], v[130:133]
	v_mfma_f32_16x16x32_bf16 v[134:137], v[230:233], v[184:187], v[134:137]
	v_mfma_f32_16x16x32_bf16 v[138:141], v[230:233], v[188:191], v[138:141]
	v_mfma_f32_16x16x32_bf16 v[142:145], v[230:233], v[192:195], v[142:145]
	s_waitcnt lgkmcnt(0)
	v_mfma_f32_16x16x32_bf16 v[146:149], v[234:237], v[180:183], v[146:149]
	v_mfma_f32_16x16x32_bf16 v[150:153], v[234:237], v[184:187], v[150:153]
	v_mfma_f32_16x16x32_bf16 v[154:157], v[234:237], v[188:191], v[154:157]
	v_mfma_f32_16x16x32_bf16 v[158:161], v[234:237], v[192:195], v[158:161]
	s_add_i32 s44, s43, 1
	s_cmp_lg_u32 s43, 2
	s_cselect_b32 s43, s44, 0
	s_add_u32 s12, s12, 64
	s_addc_u32 s13, s13, 0
	s_cmpk_eq_i32 s12, 0x780
	s_cbranch_scc0 .LBB0_30
	s_waitcnt vmcnt(6)
	v_mov_b32_e32 v162, v23
	v_mov_b32_e32 v163, v24
	v_mov_b32_e32 v23, v25
	v_mov_b32_e32 v164, v7
	v_mov_b32_e32 v165, v8
	v_pk_add_f32 v[22:23], v[162:163], v[22:23]
	v_mov_b32_e32 v7, v9
	v_pk_add_f32 v[6:7], v[164:165], v[6:7]
	v_add_f32_e32 v0, v22, v23
	v_add_f32_e32 v0, v0, v6
	v_add_f32_e32 v0, v0, v7
	v_fmamk_f32 v0, v0, 0x3a800000, v250
	s_mov_b32 s12, 0x800000
	s_waitcnt vmcnt(4)
	v_mov_b32_e32 v166, v19
	v_mov_b32_e32 v167, v20
	v_mov_b32_e32 v168, v3
	v_mul_f32_e32 v3, 0x4b800000, v0
	v_cmp_gt_f32_e32 vcc, s12, v0
	v_mov_b32_e32 v19, v21
	v_mov_b32_e32 v169, v4
	v_cndmask_b32_e32 v0, v0, v3, vcc
	v_pk_add_f32 v[6:7], v[166:167], v[18:19]
	v_mov_b32_e32 v3, v5
	v_pk_add_f32 v[2:3], v[168:169], v[2:3]
	v_add_f32_e32 v4, v6, v7
	v_add_f32_e32 v2, v4, v2
	v_add_f32_e32 v2, v2, v3
	v_fmamk_f32 v2, v2, 0x3a800000, v250
	v_mul_f32_e32 v3, 0x4b800000, v2
	v_cmp_gt_f32_e64 s[40:41], s12, v2
	s_waitcnt vmcnt(2)
	v_mov_b32_e32 v170, v27
	v_mov_b32_e32 v171, v28
	v_cndmask_b32_e64 v2, v2, v3, s[40:41]
	v_mov_b32_e32 v27, v29
	v_mov_b32_e32 v172, v11
	v_mov_b32_e32 v173, v12
	v_rsq_f32_e32 v179, v2
	v_pk_add_f32 v[2:3], v[170:171], v[26:27]
	v_mov_b32_e32 v11, v13
	v_pk_add_f32 v[4:5], v[172:173], v[10:11]
	v_add_f32_e32 v2, v2, v3
	v_add_f32_e32 v2, v2, v4
	v_add_f32_e32 v2, v2, v5
	v_fmamk_f32 v2, v2, 0x3a800000, v250
	v_mul_f32_e32 v3, 0x4b800000, v2
	v_cmp_gt_f32_e64 s[42:43], s12, v2
	s_waitcnt vmcnt(0)
	v_mov_b32_e32 v174, v31
	v_mov_b32_e32 v175, v32
	v_cndmask_b32_e64 v2, v2, v3, s[42:43]
	v_mov_b32_e32 v31, v33
	v_mov_b32_e32 v180, v15
	v_mov_b32_e32 v181, v16
	v_rsq_f32_e32 v182, v2
	v_pk_add_f32 v[2:3], v[174:175], v[30:31]
	v_mov_b32_e32 v15, v17
	v_pk_add_f32 v[4:5], v[180:181], v[14:15]
	v_add_f32_e32 v2, v2, v3
	v_add_f32_e32 v2, v2, v4
	v_add_f32_e32 v2, v2, v5
	v_fmamk_f32 v2, v2, 0x3a800000, v250
	v_mul_f32_e32 v3, 0x4b800000, v2
	v_cmp_gt_f32_e64 s[44:45], s12, v2
	s_waitcnt vmcnt(6)
	v_add_u32_e32 v183, v178, v176
	s_waitcnt lgkmcnt(0)
	s_barrier
	v_cndmask_b32_e64 v2, v2, v3, s[44:45]
	v_rsq_f32_e32 v180, v2
	ds_read_b128 v[2:5], v183 offset:15360
	ds_read_b128 v[6:9], v183 offset:14336
	ds_read_b128 v[10:13], v183 offset:13312
	ds_read_b128 v[14:17], v183 offset:12288
	ds_read_b128 v[18:21], v183 offset:11264
	ds_read_b128 v[22:25], v183 offset:10240
	ds_read_b128 v[26:29], v183 offset:9216
	ds_read_b128 v[30:33], v183 offset:8192
	v_add3_u32 v178, s55, v177, v176
	ds_read_b128 v[162:165], v178 offset:3072
	ds_read_b128 v[166:169], v178 offset:2048
	ds_read_b128 v[170:173], v178 offset:1024
	ds_read_b128 v[174:177], v178
	v_rsq_f32_e32 v0, v0
	v_mul_f32_e32 v184, 0x45800000, v179
	v_mul_f32_e32 v185, 0x45800000, v182
	v_mul_f32_e32 v186, 0x45800000, v180
	v_mul_f32_e32 v181, 0x45800000, v0
	s_waitcnt lgkmcnt(0)
	v_mfma_f32_16x16x32_bf16 v[34:37], v[30:33], v[174:177], v[34:37]
	v_mfma_f32_16x16x32_bf16 v[38:41], v[30:33], v[170:173], v[38:41]
	v_mfma_f32_16x16x32_bf16 v[42:45], v[30:33], v[166:169], v[42:45]
	v_mfma_f32_16x16x32_bf16 v[30:33], v[30:33], v[162:165], v[46:49]
	v_mfma_f32_16x16x32_bf16 v[46:49], v[26:29], v[174:177], v[50:53]
	v_mfma_f32_16x16x32_bf16 v[50:53], v[26:29], v[170:173], v[54:57]
	v_mfma_f32_16x16x32_bf16 v[54:57], v[26:29], v[166:169], v[58:61]
	v_mfma_f32_16x16x32_bf16 v[58:61], v[26:29], v[162:165], v[62:65]
	v_mfma_f32_16x16x32_bf16 v[62:65], v[22:25], v[174:177], v[66:69]
	v_mfma_f32_16x16x32_bf16 v[66:69], v[22:25], v[170:173], v[70:73]
	v_mfma_f32_16x16x32_bf16 v[70:73], v[22:25], v[166:169], v[74:77]
	v_mfma_f32_16x16x32_bf16 v[74:77], v[22:25], v[162:165], v[78:81]
	v_mfma_f32_16x16x32_bf16 v[78:81], v[18:21], v[174:177], v[82:85]
	v_mfma_f32_16x16x32_bf16 v[82:85], v[18:21], v[170:173], v[86:89]
	v_mfma_f32_16x16x32_bf16 v[86:89], v[18:21], v[166:169], v[90:93]
	v_mfma_f32_16x16x32_bf16 v[18:21], v[18:21], v[162:165], v[94:97]
	v_mfma_f32_16x16x32_bf16 v[90:93], v[14:17], v[174:177], v[98:101]
	v_mfma_f32_16x16x32_bf16 v[94:97], v[14:17], v[170:173], v[102:105]
	v_mfma_f32_16x16x32_bf16 v[98:101], v[14:17], v[166:169], v[106:109]
	v_mfma_f32_16x16x32_bf16 v[14:17], v[14:17], v[162:165], v[110:113]
	v_mfma_f32_16x16x32_bf16 v[102:105], v[10:13], v[174:177], v[114:117]
	v_mfma_f32_16x16x32_bf16 v[106:109], v[10:13], v[170:173], v[118:121]
	v_mfma_f32_16x16x32_bf16 v[110:113], v[10:13], v[166:169], v[122:125]
	v_mfma_f32_16x16x32_bf16 v[10:13], v[10:13], v[162:165], v[126:129]
	v_mfma_f32_16x16x32_bf16 v[114:117], v[6:9], v[174:177], v[130:133]
	v_mfma_f32_16x16x32_bf16 v[118:121], v[6:9], v[170:173], v[134:137]
	v_mfma_f32_16x16x32_bf16 v[122:125], v[6:9], v[166:169], v[138:141]
	v_mfma_f32_16x16x32_bf16 v[6:9], v[6:9], v[162:165], v[142:145]
	v_mfma_f32_16x16x32_bf16 v[126:129], v[2:5], v[174:177], v[146:149]
	v_mfma_f32_16x16x32_bf16 v[130:133], v[2:5], v[170:173], v[150:153]
	v_mfma_f32_16x16x32_bf16 v[134:137], v[2:5], v[166:169], v[154:157]
	v_mfma_f32_16x16x32_bf16 v[2:5], v[2:5], v[162:165], v[158:161]
	s_waitcnt vmcnt(0)
	v_cndmask_b32_e32 v26, v0, v181, vcc
	v_cndmask_b32_e64 v24, v179, v184, s[40:41]
	v_cndmask_b32_e64 v22, v182, v185, s[42:43]
	v_cndmask_b32_e64 v0, v180, v186, s[44:45]
	s_waitcnt lgkmcnt(0)
	s_barrier
	ds_read_b128 v[138:141], v178 offset:24576
	ds_read_b128 v[142:145], v178 offset:25600
	ds_read_b128 v[146:149], v178 offset:26624
	ds_read_b128 v[150:153], v178 offset:27648
	ds_read_b128 v[154:157], v183 offset:32768
	ds_read_b128 v[158:161], v183 offset:33792
	ds_read_b128 v[162:165], v183 offset:34816
	ds_read_b128 v[166:169], v183 offset:35840
	ds_read_b128 v[170:173], v183 offset:36864
	ds_read_b128 v[174:177], v183 offset:37888
	ds_read_b128 v[178:181], v183 offset:38912
	ds_read_b128 v[182:185], v183 offset:39936
	s_waitcnt lgkmcnt(7)
	v_mfma_f32_16x16x32_bf16 v[34:37], v[154:157], v[138:141], v[34:37]
	v_mfma_f32_16x16x32_bf16 v[38:41], v[154:157], v[142:145], v[38:41]
	v_mfma_f32_16x16x32_bf16 v[42:45], v[154:157], v[146:149], v[42:45]
	v_mfma_f32_16x16x32_bf16 v[28:31], v[154:157], v[150:153], v[30:33]
	s_waitcnt lgkmcnt(6)
	v_mfma_f32_16x16x32_bf16 v[46:49], v[158:161], v[138:141], v[46:49]
	v_mfma_f32_16x16x32_bf16 v[50:53], v[158:161], v[142:145], v[50:53]
	v_mfma_f32_16x16x32_bf16 v[54:57], v[158:161], v[146:149], v[54:57]
	v_mfma_f32_16x16x32_bf16 v[58:61], v[158:161], v[150:153], v[58:61]
	s_waitcnt lgkmcnt(5)
	v_mfma_f32_16x16x32_bf16 v[62:65], v[162:165], v[138:141], v[62:65]
	v_mfma_f32_16x16x32_bf16 v[66:69], v[162:165], v[142:145], v[66:69]
	v_mfma_f32_16x16x32_bf16 v[70:73], v[162:165], v[146:149], v[70:73]
	v_mfma_f32_16x16x32_bf16 v[74:77], v[162:165], v[150:153], v[74:77]
	s_waitcnt lgkmcnt(4)
	v_mfma_f32_16x16x32_bf16 v[78:81], v[166:169], v[138:141], v[78:81]
	v_mfma_f32_16x16x32_bf16 v[82:85], v[166:169], v[142:145], v[82:85]
	v_mfma_f32_16x16x32_bf16 v[86:89], v[166:169], v[146:149], v[86:89]
	v_mfma_f32_16x16x32_bf16 v[154:157], v[166:169], v[150:153], v[18:21]
	s_waitcnt lgkmcnt(3)
	v_mfma_f32_16x16x32_bf16 v[90:93], v[170:173], v[138:141], v[90:93]
	v_mfma_f32_16x16x32_bf16 v[94:97], v[170:173], v[142:145], v[94:97]
	v_mfma_f32_16x16x32_bf16 v[98:101], v[170:173], v[146:149], v[98:101]
	v_mfma_f32_16x16x32_bf16 v[158:161], v[170:173], v[150:153], v[14:17]
	s_waitcnt lgkmcnt(2)
	v_mfma_f32_16x16x32_bf16 v[102:105], v[174:177], v[138:141], v[102:105]
	v_mfma_f32_16x16x32_bf16 v[106:109], v[174:177], v[142:145], v[106:109]
	v_mfma_f32_16x16x32_bf16 v[110:113], v[174:177], v[146:149], v[110:113]
	v_mfma_f32_16x16x32_bf16 v[162:165], v[174:177], v[150:153], v[10:13]
	s_waitcnt lgkmcnt(1)
	v_mfma_f32_16x16x32_bf16 v[114:117], v[178:181], v[138:141], v[114:117]
	v_mfma_f32_16x16x32_bf16 v[118:121], v[178:181], v[142:145], v[118:121]
	v_mfma_f32_16x16x32_bf16 v[122:125], v[178:181], v[146:149], v[122:125]
	v_mfma_f32_16x16x32_bf16 v[18:21], v[178:181], v[150:153], v[6:9]
	s_waitcnt lgkmcnt(0)
	v_mfma_f32_16x16x32_bf16 v[14:17], v[182:185], v[138:141], v[126:129]
	v_mfma_f32_16x16x32_bf16 v[10:13], v[182:185], v[142:145], v[130:133]
	v_mfma_f32_16x16x32_bf16 v[6:9], v[182:185], v[146:149], v[134:137]
	v_mfma_f32_16x16x32_bf16 v[2:5], v[182:185], v[150:153], v[2:5]
	v_mov_b32_e32 v23, v224
	s_movk_i32 s12, 0x210
	v_lshrrev_b32_e32 v32, 1, v23
	v_and_b32_e32 v27, 0x7fffff80, v23
	v_and_b32_e32 v32, 24, v32
	v_and_b32_e32 v25, 0x4f, v23
	v_lshl_or_b32 v27, v27, 1, v32
	v_pk_mul_f32 v[32:33], v[26:27], v[34:35] op_sel_hi:[0,1]
	v_pk_mul_f32 v[34:35], v[26:27], v[36:37] op_sel_hi:[0,1]
	v_mad_u32_u24 v25, v25, s12, v27
	v_cvt_pk_bf16_f32 v32, v32, v33
	v_cvt_pk_bf16_f32 v33, v34, v35
	v_pk_mul_f32 v[34:35], v[24:25], v[38:39] op_sel_hi:[0,1]
	v_pk_mul_f32 v[36:37], v[24:25], v[40:41] op_sel_hi:[0,1]
	v_cvt_pk_bf16_f32 v34, v34, v35
	v_cvt_pk_bf16_f32 v35, v36, v37
	v_pk_mul_f32 v[36:37], v[22:23], v[42:43] op_sel_hi:[0,1]
	v_pk_mul_f32 v[38:39], v[22:23], v[44:45] op_sel_hi:[0,1]
	v_pk_mul_f32 v[28:29], v[0:1], v[28:29] op_sel_hi:[0,1]
	v_pk_mul_f32 v[30:31], v[0:1], v[30:31] op_sel_hi:[0,1]
	v_cvt_pk_bf16_f32 v36, v36, v37
	v_cvt_pk_bf16_f32 v37, v38, v39
	v_cvt_pk_bf16_f32 v28, v28, v29
	v_cvt_pk_bf16_f32 v29, v30, v31
	v_pk_mul_f32 v[30:31], v[26:27], v[46:47] op_sel_hi:[0,1]
	v_pk_mul_f32 v[38:39], v[26:27], v[48:49] op_sel_hi:[0,1]
	v_cvt_pk_bf16_f32 v30, v30, v31
	v_cvt_pk_bf16_f32 v31, v38, v39
	s_barrier
	ds_write2_b64 v25, v[32:33], v[30:31] offset1:4
	v_pk_mul_f32 v[30:31], v[24:25], v[50:51] op_sel_hi:[0,1]
	v_pk_mul_f32 v[32:33], v[24:25], v[52:53] op_sel_hi:[0,1]
	v_cvt_pk_bf16_f32 v30, v30, v31
	v_cvt_pk_bf16_f32 v31, v32, v33
	v_add_u32_e32 v27, 0x2000, v25
	ds_write2_b64 v27, v[34:35], v[30:31] offset0:32 offset1:36
	v_pk_mul_f32 v[30:31], v[22:23], v[54:55] op_sel_hi:[0,1]
	v_pk_mul_f32 v[32:33], v[22:23], v[56:57] op_sel_hi:[0,1]
	v_cvt_pk_bf16_f32 v30, v30, v31
	v_cvt_pk_bf16_f32 v31, v32, v33
	v_add_u32_e32 v40, 0x4000, v25
	ds_write2_b64 v40, v[36:37], v[30:31] offset0:64 offset1:68
	v_pk_mul_f32 v[30:31], v[0:1], v[58:59] op_sel_hi:[0,1]
	v_pk_mul_f32 v[32:33], v[0:1], v[60:61] op_sel_hi:[0,1]
	v_cvt_pk_bf16_f32 v30, v30, v31
	v_cvt_pk_bf16_f32 v31, v32, v33
	v_add_u32_e32 v41, 0x6000, v25
	ds_write2_b64 v41, v[28:29], v[30:31] offset0:96 offset1:100
	v_pk_mul_f32 v[28:29], v[26:27], v[62:63] op_sel_hi:[0,1]
	v_pk_mul_f32 v[30:31], v[26:27], v[64:65] op_sel_hi:[0,1]
	v_cvt_pk_bf16_f32 v28, v28, v29
	v_cvt_pk_bf16_f32 v29, v30, v31
	v_pk_mul_f32 v[30:31], v[24:25], v[66:67] op_sel_hi:[0,1]
	v_pk_mul_f32 v[32:33], v[24:25], v[68:69] op_sel_hi:[0,1]
	v_cvt_pk_bf16_f32 v30, v30, v31
	v_cvt_pk_bf16_f32 v31, v32, v33
	v_pk_mul_f32 v[32:33], v[22:23], v[70:71] op_sel_hi:[0,1]
	v_pk_mul_f32 v[34:35], v[22:23], v[72:73] op_sel_hi:[0,1]
	v_cvt_pk_bf16_f32 v32, v32, v33
	v_cvt_pk_bf16_f32 v33, v34, v35
	v_pk_mul_f32 v[34:35], v[0:1], v[74:75] op_sel_hi:[0,1]
	v_pk_mul_f32 v[36:37], v[0:1], v[76:77] op_sel_hi:[0,1]
	v_cvt_pk_bf16_f32 v34, v34, v35
	v_cvt_pk_bf16_f32 v35, v36, v37
	v_pk_mul_f32 v[36:37], v[26:27], v[78:79] op_sel_hi:[0,1]
	v_pk_mul_f32 v[38:39], v[26:27], v[80:81] op_sel_hi:[0,1]
	v_cvt_pk_bf16_f32 v36, v36, v37
	v_cvt_pk_bf16_f32 v37, v38, v39
	ds_write2_b64 v25, v[28:29], v[36:37] offset0:8 offset1:12
	v_pk_mul_f32 v[28:29], v[24:25], v[82:83] op_sel_hi:[0,1]
	v_pk_mul_f32 v[36:37], v[24:25], v[84:85] op_sel_hi:[0,1]
	v_cvt_pk_bf16_f32 v28, v28, v29
	v_cvt_pk_bf16_f32 v29, v36, v37
	ds_write2_b64 v27, v[30:31], v[28:29] offset0:40 offset1:44
	v_pk_mul_f32 v[28:29], v[22:23], v[86:87] op_sel_hi:[0,1]
	v_pk_mul_f32 v[30:31], v[22:23], v[88:89] op_sel_hi:[0,1]
	v_cvt_pk_bf16_f32 v28, v28, v29
	v_cvt_pk_bf16_f32 v29, v30, v31
	ds_write2_b64 v40, v[32:33], v[28:29] offset0:72 offset1:76
	v_pk_mul_f32 v[28:29], v[0:1], v[154:155] op_sel_hi:[0,1]
	v_pk_mul_f32 v[30:31], v[0:1], v[156:157] op_sel_hi:[0,1]
	v_cvt_pk_bf16_f32 v28, v28, v29
	v_cvt_pk_bf16_f32 v29, v30, v31
	ds_write2_b64 v41, v[34:35], v[28:29] offset0:104 offset1:108
	v_pk_mul_f32 v[28:29], v[26:27], v[90:91] op_sel_hi:[0,1]
	v_pk_mul_f32 v[30:31], v[26:27], v[92:93] op_sel_hi:[0,1]
	v_cvt_pk_bf16_f32 v28, v28, v29
	v_cvt_pk_bf16_f32 v29, v30, v31
	v_pk_mul_f32 v[30:31], v[24:25], v[94:95] op_sel_hi:[0,1]
	v_pk_mul_f32 v[32:33], v[24:25], v[96:97] op_sel_hi:[0,1]
	v_cvt_pk_bf16_f32 v30, v30, v31
	v_cvt_pk_bf16_f32 v31, v32, v33
	v_pk_mul_f32 v[32:33], v[22:23], v[98:99] op_sel_hi:[0,1]
	v_pk_mul_f32 v[34:35], v[22:23], v[100:101] op_sel_hi:[0,1]
	v_cvt_pk_bf16_f32 v32, v32, v33
	v_cvt_pk_bf16_f32 v33, v34, v35
	v_pk_mul_f32 v[34:35], v[0:1], v[158:159] op_sel_hi:[0,1]
	v_pk_mul_f32 v[36:37], v[0:1], v[160:161] op_sel_hi:[0,1]
	v_cvt_pk_bf16_f32 v34, v34, v35
	v_cvt_pk_bf16_f32 v35, v36, v37
	v_pk_mul_f32 v[36:37], v[26:27], v[102:103] op_sel_hi:[0,1]
	v_pk_mul_f32 v[38:39], v[26:27], v[104:105] op_sel_hi:[0,1]
	v_cvt_pk_bf16_f32 v36, v36, v37
	v_cvt_pk_bf16_f32 v37, v38, v39
	ds_write2_b64 v25, v[28:29], v[36:37] offset0:16 offset1:20
	v_pk_mul_f32 v[28:29], v[24:25], v[106:107] op_sel_hi:[0,1]
	v_pk_mul_f32 v[36:37], v[24:25], v[108:109] op_sel_hi:[0,1]
	v_cvt_pk_bf16_f32 v28, v28, v29
	v_cvt_pk_bf16_f32 v29, v36, v37
	ds_write2_b64 v27, v[30:31], v[28:29] offset0:48 offset1:52
	v_pk_mul_f32 v[28:29], v[22:23], v[110:111] op_sel_hi:[0,1]
	v_pk_mul_f32 v[30:31], v[22:23], v[112:113] op_sel_hi:[0,1]
	v_cvt_pk_bf16_f32 v28, v28, v29
	v_cvt_pk_bf16_f32 v29, v30, v31
	ds_write2_b64 v40, v[32:33], v[28:29] offset0:80 offset1:84
	v_pk_mul_f32 v[28:29], v[0:1], v[162:163] op_sel_hi:[0,1]
	v_pk_mul_f32 v[30:31], v[0:1], v[164:165] op_sel_hi:[0,1]
	v_cvt_pk_bf16_f32 v28, v28, v29
	v_cvt_pk_bf16_f32 v29, v30, v31
	ds_write2_b64 v41, v[34:35], v[28:29] offset0:112 offset1:116
	v_pk_mul_f32 v[28:29], v[26:27], v[114:115] op_sel_hi:[0,1]
	v_pk_mul_f32 v[30:31], v[26:27], v[116:117] op_sel_hi:[0,1]
	v_pk_mul_f32 v[18:19], v[0:1], v[18:19] op_sel_hi:[0,1]
	v_pk_mul_f32 v[20:21], v[0:1], v[20:21] op_sel_hi:[0,1]
	v_pk_mul_f32 v[2:3], v[0:1], v[2:3] op_sel_hi:[0,1]
	v_pk_mul_f32 v[4:5], v[0:1], v[4:5] op_sel_hi:[0,1]
	v_lshlrev_b32_e32 v0, 3, v23
	v_cvt_pk_bf16_f32 v28, v28, v29
	v_cvt_pk_bf16_f32 v29, v30, v31
	v_pk_mul_f32 v[30:31], v[24:25], v[118:119] op_sel_hi:[0,1]
	v_pk_mul_f32 v[32:33], v[24:25], v[120:121] op_sel_hi:[0,1]
	v_cvt_pk_bf16_f32 v18, v18, v19
	v_cvt_pk_bf16_f32 v19, v20, v21
	v_cvt_pk_bf16_f32 v2, v2, v3
	v_cvt_pk_bf16_f32 v3, v4, v5
	v_and_b32_e32 v0, 0xf8, v0
	v_cvt_pk_bf16_f32 v30, v30, v31
	v_cvt_pk_bf16_f32 v31, v32, v33
	v_pk_mul_f32 v[32:33], v[22:23], v[122:123] op_sel_hi:[0,1]
	v_pk_mul_f32 v[34:35], v[22:23], v[124:125] op_sel_hi:[0,1]
	v_pk_mul_f32 v[14:15], v[26:27], v[14:15] op_sel_hi:[0,1]
	v_pk_mul_f32 v[16:17], v[26:27], v[16:17] op_sel_hi:[0,1]
	v_pk_mul_f32 v[10:11], v[24:25], v[10:11] op_sel_hi:[0,1]
	v_pk_mul_f32 v[12:13], v[24:25], v[12:13] op_sel_hi:[0,1]
	v_pk_mul_f32 v[6:7], v[22:23], v[6:7] op_sel_hi:[0,1]
	v_pk_mul_f32 v[8:9], v[22:23], v[8:9] op_sel_hi:[0,1]
	ds_write2_b64 v41, v[18:19], v[2:3] offset0:120 offset1:124
	v_or_b32_e32 v2, s54, v0
	s_movk_i32 s12, 0x400
	v_cvt_pk_bf16_f32 v32, v32, v33
	v_cvt_pk_bf16_f32 v33, v34, v35
	v_cvt_pk_bf16_f32 v14, v14, v15
	v_cvt_pk_bf16_f32 v15, v16, v17
	v_cvt_pk_bf16_f32 v10, v10, v11
	v_cvt_pk_bf16_f32 v11, v12, v13
	v_cvt_pk_bf16_f32 v6, v6, v7
	v_cvt_pk_bf16_f32 v7, v8, v9
	v_cmp_gt_i32_e32 vcc, s12, v2
	ds_write2_b64 v25, v[28:29], v[14:15] offset0:24 offset1:28
	ds_write2_b64 v27, v[30:31], v[10:11] offset0:56 offset1:60
	ds_write2_b64 v40, v[32:33], v[6:7] offset0:88 offset1:92
	s_waitcnt lgkmcnt(0)
	s_barrier
	s_and_saveexec_b64 s[12:13], vcc
	s_cbranch_execz .LBB0_28
	v_ashrrev_i32_e32 v8, 5, v23
	v_lshlrev_b32_e32 v0, 1, v0
	s_movk_i32 s40, 0x210
	v_mad_u64_u32 v[6:7], s[40:41], v8, s40, v[0:1]
	v_add_u32_e32 v8, s57, v8
	ds_read_b128 v[2:5], v6
	v_ashrrev_i32_e32 v9, 31, v8
	s_ashr_i32 s55, s54, 31
	v_lshlrev_b64 v[10:11], 11, v[8:9]
	v_lshl_add_u64 v[10:11], s[4:5], 0, v[10:11]
	s_lshl_b64 s[40:41], s[54:55], 1
	v_lshl_add_u64 v[10:11], v[10:11], 0, s[40:41]
	v_lshl_add_u64 v[10:11], v[10:11], 0, v[0:1]
	s_waitcnt lgkmcnt(0)
	global_store_dwordx4 v[10:11], v[2:5], off
	v_add_u32_e32 v10, 8, v8
	ds_read_b128 v[2:5], v6 offset:4224
	v_ashrrev_i32_e32 v11, 31, v10
	v_lshlrev_b64 v[10:11], 11, v[10:11]
	v_lshl_add_u64 v[10:11], s[4:5], 0, v[10:11]
	v_lshl_add_u64 v[10:11], v[10:11], 0, s[40:41]
	v_lshl_add_u64 v[10:11], v[10:11], 0, v[0:1]
	s_waitcnt lgkmcnt(0)
	global_store_dwordx4 v[10:11], v[2:5], off
	v_add_u32_e32 v10, 16, v8
	ds_read_b128 v[2:5], v6 offset:8448
	v_ashrrev_i32_e32 v11, 31, v10
	v_lshlrev_b64 v[10:11], 11, v[10:11]
	v_lshl_add_u64 v[10:11], s[4:5], 0, v[10:11]
	v_lshl_add_u64 v[10:11], v[10:11], 0, s[40:41]
	v_lshl_add_u64 v[10:11], v[10:11], 0, v[0:1]
	s_waitcnt lgkmcnt(0)
	global_store_dwordx4 v[10:11], v[2:5], off
	v_add_u32_e32 v10, 24, v8
	ds_read_b128 v[2:5], v6 offset:12672
	v_ashrrev_i32_e32 v11, 31, v10
	v_lshlrev_b64 v[10:11], 11, v[10:11]
	v_lshl_add_u64 v[10:11], s[4:5], 0, v[10:11]
	v_lshl_add_u64 v[10:11], v[10:11], 0, s[40:41]
	v_lshl_add_u64 v[10:11], v[10:11], 0, v[0:1]
	s_waitcnt lgkmcnt(0)
	global_store_dwordx4 v[10:11], v[2:5], off
	v_add_u32_e32 v10, 32, v8
	ds_read_b128 v[2:5], v6 offset:16896
	v_ashrrev_i32_e32 v11, 31, v10
	v_lshlrev_b64 v[10:11], 11, v[10:11]
	v_lshl_add_u64 v[10:11], s[4:5], 0, v[10:11]
	v_lshl_add_u64 v[10:11], v[10:11], 0, s[40:41]
	v_lshl_add_u64 v[10:11], v[10:11], 0, v[0:1]
	s_waitcnt lgkmcnt(0)
	global_store_dwordx4 v[10:11], v[2:5], off
	v_add_u32_e32 v10, 40, v8
	ds_read_b128 v[2:5], v6 offset:21120
	v_ashrrev_i32_e32 v11, 31, v10
	v_lshlrev_b64 v[10:11], 11, v[10:11]
	v_lshl_add_u64 v[10:11], s[4:5], 0, v[10:11]
	v_lshl_add_u64 v[10:11], v[10:11], 0, s[40:41]
	v_lshl_add_u64 v[10:11], v[10:11], 0, v[0:1]
	s_waitcnt lgkmcnt(0)
	global_store_dwordx4 v[10:11], v[2:5], off
	v_add_u32_e32 v10, 48, v8
	ds_read_b128 v[2:5], v6 offset:25344
	v_ashrrev_i32_e32 v11, 31, v10
	v_lshlrev_b64 v[10:11], 11, v[10:11]
	v_lshl_add_u64 v[10:11], s[4:5], 0, v[10:11]
	v_lshl_add_u64 v[10:11], v[10:11], 0, s[40:41]
	v_lshl_add_u64 v[10:11], v[10:11], 0, v[0:1]
	s_waitcnt lgkmcnt(0)
	global_store_dwordx4 v[10:11], v[2:5], off
	v_add_u32_e32 v10, 56, v8
	ds_read_b128 v[2:5], v6 offset:29568
	v_ashrrev_i32_e32 v11, 31, v10
	v_lshlrev_b64 v[10:11], 11, v[10:11]
	v_lshl_add_u64 v[10:11], s[4:5], 0, v[10:11]
	v_lshl_add_u64 v[10:11], v[10:11], 0, s[40:41]
	v_lshl_add_u64 v[10:11], v[10:11], 0, v[0:1]
	s_waitcnt lgkmcnt(0)
	global_store_dwordx4 v[10:11], v[2:5], off
	v_add_u32_e32 v10, 64, v8
	ds_read_b128 v[2:5], v6 offset:33792
	v_ashrrev_i32_e32 v11, 31, v10
	v_lshlrev_b64 v[10:11], 11, v[10:11]
	v_lshl_add_u64 v[10:11], s[4:5], 0, v[10:11]
	v_lshl_add_u64 v[10:11], v[10:11], 0, s[40:41]
	v_lshl_add_u64 v[10:11], v[10:11], 0, v[0:1]
	s_waitcnt lgkmcnt(0)
	global_store_dwordx4 v[10:11], v[2:5], off
	v_add_u32_e32 v10, 0x48, v8
	ds_read_b128 v[2:5], v6 offset:38016
	v_ashrrev_i32_e32 v11, 31, v10
	v_lshlrev_b64 v[10:11], 11, v[10:11]
	v_lshl_add_u64 v[10:11], s[4:5], 0, v[10:11]
	v_lshl_add_u64 v[10:11], v[10:11], 0, s[40:41]
	v_lshl_add_u64 v[10:11], v[10:11], 0, v[0:1]
	s_waitcnt lgkmcnt(0)
	global_store_dwordx4 v[10:11], v[2:5], off
	v_add_u32_e32 v10, 0x50, v8
	ds_read_b128 v[2:5], v6 offset:42240
	v_ashrrev_i32_e32 v11, 31, v10
	v_lshlrev_b64 v[10:11], 11, v[10:11]
	v_lshl_add_u64 v[10:11], s[4:5], 0, v[10:11]
	v_lshl_add_u64 v[10:11], v[10:11], 0, s[40:41]
	v_lshl_add_u64 v[10:11], v[10:11], 0, v[0:1]
	s_waitcnt lgkmcnt(0)
	global_store_dwordx4 v[10:11], v[2:5], off
	v_add_u32_e32 v10, 0x58, v8
	ds_read_b128 v[2:5], v6 offset:46464
	v_ashrrev_i32_e32 v11, 31, v10
	v_lshlrev_b64 v[10:11], 11, v[10:11]
	v_lshl_add_u64 v[10:11], s[4:5], 0, v[10:11]
	v_lshl_add_u64 v[10:11], v[10:11], 0, s[40:41]
	v_lshl_add_u64 v[10:11], v[10:11], 0, v[0:1]
	s_waitcnt lgkmcnt(0)
	global_store_dwordx4 v[10:11], v[2:5], off
	v_add_u32_e32 v10, 0x60, v8
	ds_read_b128 v[2:5], v6 offset:50688
	v_ashrrev_i32_e32 v11, 31, v10
	v_lshlrev_b64 v[10:11], 11, v[10:11]
	v_lshl_add_u64 v[10:11], s[4:5], 0, v[10:11]
	v_lshl_add_u64 v[10:11], v[10:11], 0, s[40:41]
	v_lshl_add_u64 v[10:11], v[10:11], 0, v[0:1]
	s_waitcnt lgkmcnt(0)
	global_store_dwordx4 v[10:11], v[2:5], off
	v_add_u32_e32 v10, 0x68, v8
	ds_read_b128 v[2:5], v6 offset:54912
	v_ashrrev_i32_e32 v11, 31, v10
	v_lshlrev_b64 v[10:11], 11, v[10:11]
	v_lshl_add_u64 v[10:11], s[4:5], 0, v[10:11]
	v_lshl_add_u64 v[10:11], v[10:11], 0, s[40:41]
	v_lshl_add_u64 v[10:11], v[10:11], 0, v[0:1]
	s_waitcnt lgkmcnt(0)
	global_store_dwordx4 v[10:11], v[2:5], off
	v_add_u32_e32 v10, 0x70, v8
	ds_read_b128 v[2:5], v6 offset:59136
	v_ashrrev_i32_e32 v11, 31, v10
	v_lshlrev_b64 v[10:11], 11, v[10:11]
	v_lshl_add_u64 v[10:11], s[4:5], 0, v[10:11]
	v_lshl_add_u64 v[10:11], v[10:11], 0, s[40:41]
	v_lshl_add_u64 v[10:11], v[10:11], 0, v[0:1]
	s_waitcnt lgkmcnt(0)
	global_store_dwordx4 v[10:11], v[2:5], off
	ds_read_b128 v[2:5], v6 offset:63360
	v_add_u32_e32 v6, 0x78, v8
	v_ashrrev_i32_e32 v7, 31, v6
	v_lshlrev_b64 v[6:7], 11, v[6:7]
	v_lshl_add_u64 v[6:7], s[4:5], 0, v[6:7]
	v_lshl_add_u64 v[6:7], v[6:7], 0, s[40:41]
	v_lshl_add_u64 v[6:7], v[6:7], 0, v[0:1]
	s_waitcnt lgkmcnt(0)
	global_store_dwordx4 v[6:7], v[2:5], off
	s_branch .LBB0_28

.LBB0_72:
	s_mul_i32 s42, s1, 0x6000
	s_add_i32 s43, s42, 0xffffa000
	s_cmp_gt_i32 s1, 0
	s_waitcnt vmcnt(6)
	s_cselect_b32 s43, s43, 0xc000
	s_waitcnt lgkmcnt(0)
	s_barrier
	s_setprio 2
	v_add3_u32 v0, s42, v177, v176
	v_add_u32_e32 v0, s14, v0
	v_add3_u32 v212, s42, v178, v176
	ds_read_b128 v[196:199], v212 offset:8192
	ds_read_b128 v[180:183], v0
	ds_read_b128 v[184:187], v0 offset:1024
	ds_read_b128 v[188:191], v0 offset:2048
	ds_read_b128 v[192:195], v0 offset:3072
	ds_read_b128 v[200:203], v212 offset:9216
	ds_read_b128 v[204:207], v212 offset:10240
	ds_read_b128 v[208:211], v212 offset:11264
	ds_read_b128 v[216:219], v212 offset:12288
	ds_read_b128 v[226:229], v212 offset:13312
	ds_read_b128 v[230:233], v212 offset:14336
	ds_read_b128 v[234:237], v212 offset:15360
	s_waitcnt lgkmcnt(10)
	v_mfma_f32_16x16x32_bf16 v[34:37], v[196:199], v[180:183], v[34:37]
	s_waitcnt lgkmcnt(9)
	v_mfma_f32_16x16x32_bf16 v[38:41], v[196:199], v[184:187], v[38:41]
	s_waitcnt lgkmcnt(8)
	v_mfma_f32_16x16x32_bf16 v[42:45], v[196:199], v[188:191], v[42:45]
	s_waitcnt lgkmcnt(7)
	v_mfma_f32_16x16x32_bf16 v[46:49], v[196:199], v[192:195], v[46:49]
	v_lshl_add_u64 v[212:213], v[174:175], 0, s[12:13]
	v_lshl_add_u64 v[212:213], v[162:163], 1, v[212:213]
	s_add_i32 s44, s43, s41
	s_mov_b32 m0, s44
	s_nop 0
	global_load_lds_dwordx4 v[212:213], off
	v_lshl_add_u64 v[212:213], v[174:175], 0, s[12:13]
	v_lshl_add_u64 v[212:213], v[164:165], 1, v[212:213]
	s_add_i32 s44, s43, s15
	s_mov_b32 m0, s44
	s_nop 0
	global_load_lds_dwordx4 v[212:213], off
	s_add_i32 s43, s40, s43
	v_lshl_add_u64 v[212:213], v[172:173], 0, s[12:13]
	s_mov_b32 m0, s43
	s_nop 0
	global_load_lds_dwordx4 v[212:213], off
	v_lshl_add_u64 v[212:213], v[170:171], 0, s[12:13]
	s_add_i32 s44, s43, 0x400
	s_mov_b32 m0, s44
	s_nop 0
	global_load_lds_dwordx4 v[212:213], off
	v_lshl_add_u64 v[212:213], v[168:169], 0, s[12:13]
	s_add_i32 s44, s43, 0x800
	s_mov_b32 m0, s44
	s_nop 0
	global_load_lds_dwordx4 v[212:213], off
	s_addk_i32 s43, 0xc00
	v_lshl_add_u64 v[212:213], v[166:167], 0, s[12:13]
	s_mov_b32 m0, s43
	s_nop 0
	global_load_lds_dwordx4 v[212:213], off
	s_setprio 0
	s_waitcnt lgkmcnt(6)
	v_mfma_f32_16x16x32_bf16 v[50:53], v[200:203], v[180:183], v[50:53]
	v_mfma_f32_16x16x32_bf16 v[54:57], v[200:203], v[184:187], v[54:57]
	v_mfma_f32_16x16x32_bf16 v[58:61], v[200:203], v[188:191], v[58:61]
	v_mfma_f32_16x16x32_bf16 v[62:65], v[200:203], v[192:195], v[62:65]
	s_waitcnt lgkmcnt(5)
	v_mfma_f32_16x16x32_bf16 v[66:69], v[204:207], v[180:183], v[66:69]
	v_mfma_f32_16x16x32_bf16 v[70:73], v[204:207], v[184:187], v[70:73]
	v_mfma_f32_16x16x32_bf16 v[74:77], v[204:207], v[188:191], v[74:77]
	v_mfma_f32_16x16x32_bf16 v[78:81], v[204:207], v[192:195], v[78:81]
	s_waitcnt lgkmcnt(4)
	v_mfma_f32_16x16x32_bf16 v[82:85], v[208:211], v[180:183], v[82:85]
	v_mfma_f32_16x16x32_bf16 v[86:89], v[208:211], v[184:187], v[86:89]
	v_mfma_f32_16x16x32_bf16 v[90:93], v[208:211], v[188:191], v[90:93]
	v_mfma_f32_16x16x32_bf16 v[94:97], v[208:211], v[192:195], v[94:97]
	s_waitcnt lgkmcnt(3)
	v_mfma_f32_16x16x32_bf16 v[98:101], v[216:219], v[180:183], v[98:101]
	v_mfma_f32_16x16x32_bf16 v[102:105], v[216:219], v[184:187], v[102:105]
	v_mfma_f32_16x16x32_bf16 v[106:109], v[216:219], v[188:191], v[106:109]
	v_mfma_f32_16x16x32_bf16 v[110:113], v[216:219], v[192:195], v[110:113]
	s_waitcnt lgkmcnt(2)
	v_mfma_f32_16x16x32_bf16 v[114:117], v[226:229], v[180:183], v[114:117]
	v_mfma_f32_16x16x32_bf16 v[118:121], v[226:229], v[184:187], v[118:121]
	v_mfma_f32_16x16x32_bf16 v[122:125], v[226:229], v[188:191], v[122:125]
	v_mfma_f32_16x16x32_bf16 v[126:129], v[226:229], v[192:195], v[126:129]
	s_waitcnt lgkmcnt(1)
	v_mfma_f32_16x16x32_bf16 v[130:133], v[230:233], v[180:183], v[130:133]
	v_mfma_f32_16x16x32_bf16 v[134:137], v[230:233], v[184:187], v[134:137]
	v_mfma_f32_16x16x32_bf16 v[138:141], v[230:233], v[188:191], v[138:141]
	v_mfma_f32_16x16x32_bf16 v[142:145], v[230:233], v[192:195], v[142:145]
	s_waitcnt lgkmcnt(0)
	v_mfma_f32_16x16x32_bf16 v[146:149], v[234:237], v[180:183], v[146:149]
	v_mfma_f32_16x16x32_bf16 v[150:153], v[234:237], v[184:187], v[150:153]
	v_mfma_f32_16x16x32_bf16 v[154:157], v[234:237], v[188:191], v[154:157]
	v_mfma_f32_16x16x32_bf16 v[158:161], v[234:237], v[192:195], v[158:161]
	s_add_i32 s42, s1, 1
	s_cmp_lg_u32 s1, 2
	s_cselect_b32 s1, s42, 0
	s_add_u32 s12, s12, 64
	s_addc_u32 s13, s13, 0
	s_cmpk_eq_i32 s12, 0x780
	s_cbranch_scc0 .LBB0_72
	s_waitcnt vmcnt(6)
	v_mov_b32_e32 v162, v31
	v_mov_b32_e32 v163, v32
	v_mov_b32_e32 v31, v33
	v_mov_b32_e32 v164, v15
	v_mov_b32_e32 v165, v16
	v_pk_add_f32 v[30:31], v[162:163], v[30:31]
	v_mov_b32_e32 v15, v17
	v_pk_add_f32 v[14:15], v[164:165], v[14:15]
	v_add_f32_e32 v0, v30, v31
	v_add_f32_e32 v0, v0, v14
	v_add_f32_e32 v0, v0, v15
	s_waitcnt vmcnt(4)
	v_mov_b32_e32 v166, v27
	v_mov_b32_e32 v167, v28
	v_fmamk_f32 v0, v0, 0x3a800000, v250
	s_mov_b32 s1, 0x800000
	v_mov_b32_e32 v27, v29
	v_mov_b32_e32 v168, v11
	v_mov_b32_e32 v169, v12
	s_waitcnt vmcnt(1)
	v_mov_b32_e32 v180, v3
	v_mul_f32_e32 v3, 0x4b800000, v0
	v_cmp_gt_f32_e32 vcc, s1, v0
	v_pk_add_f32 v[14:15], v[166:167], v[26:27]
	v_mov_b32_e32 v11, v13
	v_cndmask_b32_e32 v0, v0, v3, vcc
	v_pk_add_f32 v[10:11], v[168:169], v[10:11]
	v_add_f32_e32 v3, v14, v15
	v_add_f32_e32 v3, v3, v10
	v_add_f32_e32 v3, v3, v11
	v_fmamk_f32 v3, v3, 0x3a800000, v250
	v_mov_b32_e32 v170, v23
	v_mov_b32_e32 v171, v24
	v_mov_b32_e32 v181, v4
	v_mul_f32_e32 v4, 0x4b800000, v3
	v_cmp_gt_f32_e64 s[40:41], s1, v3
	v_mov_b32_e32 v23, v25
	v_mov_b32_e32 v172, v7
	v_mov_b32_e32 v173, v8
	v_cndmask_b32_e64 v3, v3, v4, s[40:41]
	v_pk_add_f32 v[10:11], v[170:171], v[22:23]
	v_mov_b32_e32 v7, v9
	v_rsq_f32_e32 v179, v3
	v_pk_add_f32 v[6:7], v[172:173], v[6:7]
	v_add_f32_e32 v3, v10, v11
	v_add_f32_e32 v3, v3, v6
	v_add_f32_e32 v3, v3, v7
	v_fmamk_f32 v3, v3, 0x3a800000, v250
	v_mul_f32_e32 v4, 0x4b800000, v3
	v_cmp_gt_f32_e64 s[42:43], s1, v3
	s_waitcnt vmcnt(0)
	v_mov_b32_e32 v174, v19
	v_mov_b32_e32 v175, v20
	v_cndmask_b32_e64 v3, v3, v4, s[42:43]
	v_mov_b32_e32 v19, v21
	v_rsq_f32_e32 v182, v3
	v_pk_add_f32 v[6:7], v[174:175], v[18:19]
	v_mov_b32_e32 v3, v5
	v_pk_add_f32 v[2:3], v[180:181], v[2:3]
	v_add_f32_e32 v4, v6, v7
	v_add_f32_e32 v2, v4, v2
	v_add_f32_e32 v2, v2, v3
	v_fmamk_f32 v2, v2, 0x3a800000, v250
	v_mul_f32_e32 v3, 0x4b800000, v2
	v_cmp_gt_f32_e64 s[44:45], s1, v2
	s_waitcnt vmcnt(6)
	v_add_u32_e32 v183, v178, v176
	s_waitcnt lgkmcnt(0)
	s_barrier
	v_cndmask_b32_e64 v2, v2, v3, s[44:45]
	v_rsq_f32_e32 v180, v2
	ds_read_b128 v[2:5], v183 offset:15360
	ds_read_b128 v[6:9], v183 offset:14336
	ds_read_b128 v[10:13], v183 offset:13312
	ds_read_b128 v[14:17], v183 offset:12288
	ds_read_b128 v[18:21], v183 offset:11264
	ds_read_b128 v[22:25], v183 offset:10240
	ds_read_b128 v[26:29], v183 offset:9216
	ds_read_b128 v[30:33], v183 offset:8192
	v_add3_u32 v178, s14, v177, v176
	ds_read_b128 v[162:165], v178 offset:3072
	ds_read_b128 v[166:169], v178 offset:2048
	ds_read_b128 v[170:173], v178 offset:1024
	ds_read_b128 v[174:177], v178
	v_rsq_f32_e32 v0, v0
	v_mul_f32_e32 v184, 0x45800000, v179
	v_mul_f32_e32 v185, 0x45800000, v182
	v_mul_f32_e32 v186, 0x45800000, v180
	v_mul_f32_e32 v181, 0x45800000, v0
	s_waitcnt lgkmcnt(0)
	v_mfma_f32_16x16x32_bf16 v[34:37], v[30:33], v[174:177], v[34:37]
	v_mfma_f32_16x16x32_bf16 v[38:41], v[30:33], v[170:173], v[38:41]
	v_mfma_f32_16x16x32_bf16 v[42:45], v[30:33], v[166:169], v[42:45]
	v_mfma_f32_16x16x32_bf16 v[46:49], v[30:33], v[162:165], v[46:49]
	v_mfma_f32_16x16x32_bf16 v[50:53], v[26:29], v[174:177], v[50:53]
	v_mfma_f32_16x16x32_bf16 v[54:57], v[26:29], v[170:173], v[54:57]
	v_mfma_f32_16x16x32_bf16 v[58:61], v[26:29], v[166:169], v[58:61]
	v_mfma_f32_16x16x32_bf16 v[62:65], v[26:29], v[162:165], v[62:65]
	v_mfma_f32_16x16x32_bf16 v[66:69], v[22:25], v[174:177], v[66:69]
	v_mfma_f32_16x16x32_bf16 v[70:73], v[22:25], v[170:173], v[70:73]
	v_mfma_f32_16x16x32_bf16 v[74:77], v[22:25], v[166:169], v[74:77]
	v_mfma_f32_16x16x32_bf16 v[22:25], v[22:25], v[162:165], v[78:81]
	v_mfma_f32_16x16x32_bf16 v[78:81], v[18:21], v[174:177], v[82:85]
	v_mfma_f32_16x16x32_bf16 v[82:85], v[18:21], v[170:173], v[86:89]
	v_mfma_f32_16x16x32_bf16 v[86:89], v[18:21], v[166:169], v[90:93]
	v_mfma_f32_16x16x32_bf16 v[18:21], v[18:21], v[162:165], v[94:97]
	v_mfma_f32_16x16x32_bf16 v[90:93], v[14:17], v[174:177], v[98:101]
	v_mfma_f32_16x16x32_bf16 v[94:97], v[14:17], v[170:173], v[102:105]
	v_mfma_f32_16x16x32_bf16 v[98:101], v[14:17], v[166:169], v[106:109]
	v_mfma_f32_16x16x32_bf16 v[14:17], v[14:17], v[162:165], v[110:113]
	v_mfma_f32_16x16x32_bf16 v[102:105], v[10:13], v[174:177], v[114:117]
	v_mfma_f32_16x16x32_bf16 v[106:109], v[10:13], v[170:173], v[118:121]
	v_mfma_f32_16x16x32_bf16 v[110:113], v[10:13], v[166:169], v[122:125]
	v_mfma_f32_16x16x32_bf16 v[10:13], v[10:13], v[162:165], v[126:129]
	v_mfma_f32_16x16x32_bf16 v[114:117], v[6:9], v[174:177], v[130:133]
	v_mfma_f32_16x16x32_bf16 v[118:121], v[6:9], v[170:173], v[134:137]
	v_mfma_f32_16x16x32_bf16 v[122:125], v[6:9], v[166:169], v[138:141]
	v_mfma_f32_16x16x32_bf16 v[6:9], v[6:9], v[162:165], v[142:145]
	v_mfma_f32_16x16x32_bf16 v[126:129], v[2:5], v[174:177], v[146:149]
	v_mfma_f32_16x16x32_bf16 v[130:133], v[2:5], v[170:173], v[150:153]
	v_mfma_f32_16x16x32_bf16 v[134:137], v[2:5], v[166:169], v[154:157]
	v_mfma_f32_16x16x32_bf16 v[2:5], v[2:5], v[162:165], v[158:161]
	s_waitcnt vmcnt(0)
	v_cndmask_b32_e32 v30, v0, v181, vcc
	v_cndmask_b32_e64 v28, v179, v184, s[40:41]
	v_cndmask_b32_e64 v26, v182, v185, s[42:43]
	v_cndmask_b32_e64 v0, v180, v186, s[44:45]
	s_waitcnt lgkmcnt(0)
	s_barrier
	ds_read_b128 v[138:141], v178 offset:24576
	ds_read_b128 v[142:145], v178 offset:25600
	ds_read_b128 v[146:149], v178 offset:26624
	ds_read_b128 v[150:153], v178 offset:27648
	ds_read_b128 v[154:157], v183 offset:32768
	ds_read_b128 v[158:161], v183 offset:33792
	ds_read_b128 v[162:165], v183 offset:34816
	ds_read_b128 v[166:169], v183 offset:35840
	ds_read_b128 v[170:173], v183 offset:36864
	ds_read_b128 v[174:177], v183 offset:37888
	ds_read_b128 v[178:181], v183 offset:38912
	ds_read_b128 v[182:185], v183 offset:39936
	s_waitcnt lgkmcnt(7)
	v_mfma_f32_16x16x32_bf16 v[32:35], v[154:157], v[138:141], v[34:37]
	v_mfma_f32_16x16x32_bf16 v[36:39], v[154:157], v[142:145], v[38:41]
	v_mfma_f32_16x16x32_bf16 v[40:43], v[154:157], v[146:149], v[42:45]
	v_mfma_f32_16x16x32_bf16 v[44:47], v[154:157], v[150:153], v[46:49]
	s_waitcnt lgkmcnt(6)
	v_mfma_f32_16x16x32_bf16 v[48:51], v[158:161], v[138:141], v[50:53]
	v_mfma_f32_16x16x32_bf16 v[52:55], v[158:161], v[142:145], v[54:57]
	v_mfma_f32_16x16x32_bf16 v[56:59], v[158:161], v[146:149], v[58:61]
	v_mfma_f32_16x16x32_bf16 v[60:63], v[158:161], v[150:153], v[62:65]
	s_waitcnt lgkmcnt(5)
	v_mfma_f32_16x16x32_bf16 v[64:67], v[162:165], v[138:141], v[66:69]
	v_mfma_f32_16x16x32_bf16 v[68:71], v[162:165], v[142:145], v[70:73]
	v_mfma_f32_16x16x32_bf16 v[72:75], v[162:165], v[146:149], v[74:77]
	v_mfma_f32_16x16x32_bf16 v[154:157], v[162:165], v[150:153], v[22:25]
	s_waitcnt lgkmcnt(4)
	v_mfma_f32_16x16x32_bf16 v[76:79], v[166:169], v[138:141], v[78:81]
	v_mfma_f32_16x16x32_bf16 v[80:83], v[166:169], v[142:145], v[82:85]
	v_mfma_f32_16x16x32_bf16 v[84:87], v[166:169], v[146:149], v[86:89]
	v_mfma_f32_16x16x32_bf16 v[158:161], v[166:169], v[150:153], v[18:21]
	s_waitcnt lgkmcnt(3)
	v_mfma_f32_16x16x32_bf16 v[88:91], v[170:173], v[138:141], v[90:93]
	v_mfma_f32_16x16x32_bf16 v[92:95], v[170:173], v[142:145], v[94:97]
	v_mfma_f32_16x16x32_bf16 v[96:99], v[170:173], v[146:149], v[98:101]
	v_mfma_f32_16x16x32_bf16 v[162:165], v[170:173], v[150:153], v[14:17]
	s_waitcnt lgkmcnt(2)
	v_mfma_f32_16x16x32_bf16 v[100:103], v[174:177], v[138:141], v[102:105]
	v_mfma_f32_16x16x32_bf16 v[104:107], v[174:177], v[142:145], v[106:109]
	v_mfma_f32_16x16x32_bf16 v[108:111], v[174:177], v[146:149], v[110:113]
	v_mfma_f32_16x16x32_bf16 v[166:169], v[174:177], v[150:153], v[10:13]
	s_waitcnt lgkmcnt(1)
	v_mfma_f32_16x16x32_bf16 v[112:115], v[178:181], v[138:141], v[114:117]
	v_mfma_f32_16x16x32_bf16 v[116:119], v[178:181], v[142:145], v[118:121]
	v_mfma_f32_16x16x32_bf16 v[22:25], v[178:181], v[146:149], v[122:125]
	v_mfma_f32_16x16x32_bf16 v[18:21], v[178:181], v[150:153], v[6:9]
	s_waitcnt lgkmcnt(0)
	v_mfma_f32_16x16x32_bf16 v[14:17], v[182:185], v[138:141], v[126:129]
	v_mfma_f32_16x16x32_bf16 v[10:13], v[182:185], v[142:145], v[130:133]
	v_mfma_f32_16x16x32_bf16 v[6:9], v[182:185], v[146:149], v[134:137]
	v_mfma_f32_16x16x32_bf16 v[2:5], v[182:185], v[150:153], v[2:5]
	v_mov_b32_e32 v27, v224
	s_movk_i32 s1, 0x210
	v_lshrrev_b32_e32 v120, 1, v27
	v_and_b32_e32 v31, 0x7fffff80, v27
	v_and_b32_e32 v120, 24, v120
	v_and_b32_e32 v29, 0x4f, v27
	v_lshl_or_b32 v31, v31, 1, v120
	v_pk_mul_f32 v[32:33], v[30:31], v[32:33] op_sel_hi:[0,1]
	v_pk_mul_f32 v[34:35], v[30:31], v[34:35] op_sel_hi:[0,1]
	v_mad_u32_u24 v29, v29, s1, v31
	v_cvt_pk_bf16_f32 v32, v32, v33
	v_cvt_pk_bf16_f32 v33, v34, v35
	v_pk_mul_f32 v[34:35], v[28:29], v[36:37] op_sel_hi:[0,1]
	v_pk_mul_f32 v[36:37], v[28:29], v[38:39] op_sel_hi:[0,1]
	v_cvt_pk_bf16_f32 v34, v34, v35
	v_cvt_pk_bf16_f32 v35, v36, v37
	v_pk_mul_f32 v[36:37], v[26:27], v[40:41] op_sel_hi:[0,1]
	v_pk_mul_f32 v[38:39], v[26:27], v[42:43] op_sel_hi:[0,1]
	v_cvt_pk_bf16_f32 v36, v36, v37
	v_cvt_pk_bf16_f32 v37, v38, v39
	v_pk_mul_f32 v[38:39], v[0:1], v[44:45] op_sel_hi:[0,1]
	v_pk_mul_f32 v[40:41], v[0:1], v[46:47] op_sel_hi:[0,1]
	v_cvt_pk_bf16_f32 v38, v38, v39
	v_cvt_pk_bf16_f32 v39, v40, v41
	v_pk_mul_f32 v[40:41], v[30:31], v[48:49] op_sel_hi:[0,1]
	v_pk_mul_f32 v[42:43], v[30:31], v[50:51] op_sel_hi:[0,1]
	v_cvt_pk_bf16_f32 v40, v40, v41
	v_cvt_pk_bf16_f32 v41, v42, v43
	s_barrier
	ds_write2_b64 v29, v[32:33], v[40:41] offset1:4
	v_pk_mul_f32 v[32:33], v[28:29], v[52:53] op_sel_hi:[0,1]
	v_pk_mul_f32 v[40:41], v[28:29], v[54:55] op_sel_hi:[0,1]
	v_cvt_pk_bf16_f32 v32, v32, v33
	v_cvt_pk_bf16_f32 v33, v40, v41
	v_add_u32_e32 v31, 0x2000, v29
	ds_write2_b64 v31, v[34:35], v[32:33] offset0:32 offset1:36
	v_pk_mul_f32 v[32:33], v[26:27], v[56:57] op_sel_hi:[0,1]
	v_pk_mul_f32 v[34:35], v[26:27], v[58:59] op_sel_hi:[0,1]
	v_cvt_pk_bf16_f32 v32, v32, v33
	v_cvt_pk_bf16_f32 v33, v34, v35
	v_add_u32_e32 v44, 0x4000, v29
	ds_write2_b64 v44, v[36:37], v[32:33] offset0:64 offset1:68
	v_pk_mul_f32 v[32:33], v[0:1], v[60:61] op_sel_hi:[0,1]
	v_pk_mul_f32 v[34:35], v[0:1], v[62:63] op_sel_hi:[0,1]
	v_cvt_pk_bf16_f32 v32, v32, v33
	v_cvt_pk_bf16_f32 v33, v34, v35
	v_add_u32_e32 v45, 0x6000, v29
	ds_write2_b64 v45, v[38:39], v[32:33] offset0:96 offset1:100
	v_pk_mul_f32 v[32:33], v[30:31], v[64:65] op_sel_hi:[0,1]
	v_pk_mul_f32 v[34:35], v[30:31], v[66:67] op_sel_hi:[0,1]
	v_cvt_pk_bf16_f32 v32, v32, v33
	v_cvt_pk_bf16_f32 v33, v34, v35
	v_pk_mul_f32 v[34:35], v[28:29], v[68:69] op_sel_hi:[0,1]
	v_pk_mul_f32 v[36:37], v[28:29], v[70:71] op_sel_hi:[0,1]
	v_cvt_pk_bf16_f32 v34, v34, v35
	v_cvt_pk_bf16_f32 v35, v36, v37
	v_pk_mul_f32 v[36:37], v[26:27], v[72:73] op_sel_hi:[0,1]
	v_pk_mul_f32 v[38:39], v[26:27], v[74:75] op_sel_hi:[0,1]
	v_cvt_pk_bf16_f32 v36, v36, v37
	v_cvt_pk_bf16_f32 v37, v38, v39
	v_pk_mul_f32 v[38:39], v[0:1], v[154:155] op_sel_hi:[0,1]
	v_pk_mul_f32 v[40:41], v[0:1], v[156:157] op_sel_hi:[0,1]
	v_cvt_pk_bf16_f32 v38, v38, v39
	v_cvt_pk_bf16_f32 v39, v40, v41
	v_pk_mul_f32 v[40:41], v[30:31], v[76:77] op_sel_hi:[0,1]
	v_pk_mul_f32 v[42:43], v[30:31], v[78:79] op_sel_hi:[0,1]
	v_cvt_pk_bf16_f32 v40, v40, v41
	v_cvt_pk_bf16_f32 v41, v42, v43
	ds_write2_b64 v29, v[32:33], v[40:41] offset0:8 offset1:12
	v_pk_mul_f32 v[32:33], v[28:29], v[80:81] op_sel_hi:[0,1]
	v_pk_mul_f32 v[40:41], v[28:29], v[82:83] op_sel_hi:[0,1]
	v_cvt_pk_bf16_f32 v32, v32, v33
	v_cvt_pk_bf16_f32 v33, v40, v41
	ds_write2_b64 v31, v[34:35], v[32:33] offset0:40 offset1:44
	v_pk_mul_f32 v[32:33], v[26:27], v[84:85] op_sel_hi:[0,1]
	v_pk_mul_f32 v[34:35], v[26:27], v[86:87] op_sel_hi:[0,1]
	v_cvt_pk_bf16_f32 v32, v32, v33
	v_cvt_pk_bf16_f32 v33, v34, v35
	ds_write2_b64 v44, v[36:37], v[32:33] offset0:72 offset1:76
	v_pk_mul_f32 v[32:33], v[0:1], v[158:159] op_sel_hi:[0,1]
	v_pk_mul_f32 v[34:35], v[0:1], v[160:161] op_sel_hi:[0,1]
	v_cvt_pk_bf16_f32 v32, v32, v33
	v_cvt_pk_bf16_f32 v33, v34, v35
	ds_write2_b64 v45, v[38:39], v[32:33] offset0:104 offset1:108
	v_pk_mul_f32 v[32:33], v[30:31], v[88:89] op_sel_hi:[0,1]
	v_pk_mul_f32 v[34:35], v[30:31], v[90:91] op_sel_hi:[0,1]
	v_cvt_pk_bf16_f32 v32, v32, v33
	v_cvt_pk_bf16_f32 v33, v34, v35
	v_pk_mul_f32 v[34:35], v[28:29], v[92:93] op_sel_hi:[0,1]
	v_pk_mul_f32 v[36:37], v[28:29], v[94:95] op_sel_hi:[0,1]
	v_cvt_pk_bf16_f32 v34, v34, v35
	v_cvt_pk_bf16_f32 v35, v36, v37
	v_pk_mul_f32 v[36:37], v[26:27], v[96:97] op_sel_hi:[0,1]
	v_pk_mul_f32 v[38:39], v[26:27], v[98:99] op_sel_hi:[0,1]
	v_cvt_pk_bf16_f32 v36, v36, v37
	v_cvt_pk_bf16_f32 v37, v38, v39
	v_pk_mul_f32 v[38:39], v[0:1], v[162:163] op_sel_hi:[0,1]
	v_pk_mul_f32 v[40:41], v[0:1], v[164:165] op_sel_hi:[0,1]
	v_cvt_pk_bf16_f32 v38, v38, v39
	v_cvt_pk_bf16_f32 v39, v40, v41
	v_pk_mul_f32 v[40:41], v[30:31], v[100:101] op_sel_hi:[0,1]
	v_pk_mul_f32 v[42:43], v[30:31], v[102:103] op_sel_hi:[0,1]
	v_cvt_pk_bf16_f32 v40, v40, v41
	v_cvt_pk_bf16_f32 v41, v42, v43
	ds_write2_b64 v29, v[32:33], v[40:41] offset0:16 offset1:20
	v_pk_mul_f32 v[32:33], v[28:29], v[104:105] op_sel_hi:[0,1]
	v_pk_mul_f32 v[40:41], v[28:29], v[106:107] op_sel_hi:[0,1]
	v_cvt_pk_bf16_f32 v32, v32, v33
	v_cvt_pk_bf16_f32 v33, v40, v41
	ds_write2_b64 v31, v[34:35], v[32:33] offset0:48 offset1:52
	v_pk_mul_f32 v[32:33], v[26:27], v[108:109] op_sel_hi:[0,1]
	v_pk_mul_f32 v[34:35], v[26:27], v[110:111] op_sel_hi:[0,1]
	v_cvt_pk_bf16_f32 v32, v32, v33
	v_cvt_pk_bf16_f32 v33, v34, v35
	ds_write2_b64 v44, v[36:37], v[32:33] offset0:80 offset1:84
	v_pk_mul_f32 v[32:33], v[0:1], v[166:167] op_sel_hi:[0,1]
	v_pk_mul_f32 v[34:35], v[0:1], v[168:169] op_sel_hi:[0,1]
	v_cvt_pk_bf16_f32 v32, v32, v33
	v_cvt_pk_bf16_f32 v33, v34, v35
	v_pk_mul_f32 v[18:19], v[0:1], v[18:19] op_sel_hi:[0,1]
	v_pk_mul_f32 v[20:21], v[0:1], v[20:21] op_sel_hi:[0,1]
	v_pk_mul_f32 v[2:3], v[0:1], v[2:3] op_sel_hi:[0,1]
	v_pk_mul_f32 v[4:5], v[0:1], v[4:5] op_sel_hi:[0,1]
	v_lshlrev_b32_e32 v0, 3, v27
	ds_write2_b64 v45, v[38:39], v[32:33] offset0:112 offset1:116
	v_pk_mul_f32 v[32:33], v[30:31], v[112:113] op_sel_hi:[0,1]
	v_pk_mul_f32 v[34:35], v[30:31], v[114:115] op_sel_hi:[0,1]
	v_cvt_pk_bf16_f32 v18, v18, v19
	v_cvt_pk_bf16_f32 v19, v20, v21
	v_cvt_pk_bf16_f32 v2, v2, v3
	v_cvt_pk_bf16_f32 v3, v4, v5
	v_and_b32_e32 v0, 0xf8, v0
	v_cvt_pk_bf16_f32 v32, v32, v33
	v_cvt_pk_bf16_f32 v33, v34, v35
	v_pk_mul_f32 v[34:35], v[28:29], v[116:117] op_sel_hi:[0,1]
	v_pk_mul_f32 v[36:37], v[28:29], v[118:119] op_sel_hi:[0,1]
	v_pk_mul_f32 v[22:23], v[26:27], v[22:23] op_sel_hi:[0,1]
	v_pk_mul_f32 v[24:25], v[26:27], v[24:25] op_sel_hi:[0,1]
	v_pk_mul_f32 v[14:15], v[30:31], v[14:15] op_sel_hi:[0,1]
	v_pk_mul_f32 v[16:17], v[30:31], v[16:17] op_sel_hi:[0,1]
	v_pk_mul_f32 v[10:11], v[28:29], v[10:11] op_sel_hi:[0,1]
	v_pk_mul_f32 v[12:13], v[28:29], v[12:13] op_sel_hi:[0,1]
	v_pk_mul_f32 v[6:7], v[26:27], v[6:7] op_sel_hi:[0,1]
	v_pk_mul_f32 v[8:9], v[26:27], v[8:9] op_sel_hi:[0,1]
	ds_write2_b64 v45, v[18:19], v[2:3] offset0:120 offset1:124
	v_or_b32_e32 v2, s0, v0
	s_movk_i32 s1, 0x400
	v_cvt_pk_bf16_f32 v34, v34, v35
	v_cvt_pk_bf16_f32 v35, v36, v37
	v_cvt_pk_bf16_f32 v22, v22, v23
	v_cvt_pk_bf16_f32 v23, v24, v25
	v_cvt_pk_bf16_f32 v14, v14, v15
	v_cvt_pk_bf16_f32 v15, v16, v17
	v_cvt_pk_bf16_f32 v10, v10, v11
	v_cvt_pk_bf16_f32 v11, v12, v13
	v_cvt_pk_bf16_f32 v6, v6, v7
	v_cvt_pk_bf16_f32 v7, v8, v9
	v_cmp_gt_i32_e64 s[44:45], s1, v2
	ds_write2_b64 v29, v[32:33], v[14:15] offset0:24 offset1:28
	ds_write2_b64 v31, v[34:35], v[10:11] offset0:56 offset1:60
	ds_write2_b64 v44, v[22:23], v[6:7] offset0:88 offset1:92
	s_waitcnt lgkmcnt(0)
	s_barrier
	s_mov_b64 s[12:13], 11
	s_mov_b64 s[40:41], s[46:47]
	s_branch .LBB0_78

.LBB0_76:
	s_mul_i32 s41, s12, 0x6000
	s_add_i32 s42, s41, 0xffffa000
	s_cmp_gt_i32 s12, 0
	s_waitcnt vmcnt(6)
	s_cselect_b32 s42, s42, 0xc000
	s_waitcnt lgkmcnt(0)
	s_barrier
	s_setprio 2
	v_add3_u32 v0, s41, v177, v176
	v_add_u32_e32 v0, s13, v0
	v_add3_u32 v212, s41, v178, v176
	ds_read_b128 v[196:199], v212 offset:8192
	ds_read_b128 v[180:183], v0
	ds_read_b128 v[184:187], v0 offset:1024
	ds_read_b128 v[188:191], v0 offset:2048
	ds_read_b128 v[192:195], v0 offset:3072
	ds_read_b128 v[200:203], v212 offset:9216
	ds_read_b128 v[204:207], v212 offset:10240
	ds_read_b128 v[208:211], v212 offset:11264
	ds_read_b128 v[216:219], v212 offset:12288
	ds_read_b128 v[226:229], v212 offset:13312
	ds_read_b128 v[230:233], v212 offset:14336
	ds_read_b128 v[234:237], v212 offset:15360
	s_waitcnt lgkmcnt(10)
	v_mfma_f32_16x16x32_bf16 v[34:37], v[196:199], v[180:183], v[34:37]
	s_waitcnt lgkmcnt(9)
	v_mfma_f32_16x16x32_bf16 v[38:41], v[196:199], v[184:187], v[38:41]
	s_waitcnt lgkmcnt(8)
	v_mfma_f32_16x16x32_bf16 v[42:45], v[196:199], v[188:191], v[42:45]
	s_waitcnt lgkmcnt(7)
	v_mfma_f32_16x16x32_bf16 v[46:49], v[196:199], v[192:195], v[46:49]
	v_lshl_add_u64 v[212:213], v[174:175], 0, s[0:1]
	v_lshl_add_u64 v[212:213], v[162:163], 1, v[212:213]
	s_add_i32 s43, s42, s40
	s_mov_b32 m0, s43
	s_nop 0
	global_load_lds_dwordx4 v[212:213], off
	v_lshl_add_u64 v[212:213], v[174:175], 0, s[0:1]
	v_lshl_add_u64 v[212:213], v[164:165], 1, v[212:213]
	s_add_i32 s43, s42, s14
	s_mov_b32 m0, s43
	s_nop 0
	global_load_lds_dwordx4 v[212:213], off
	s_add_i32 s42, s15, s42
	v_lshl_add_u64 v[212:213], v[172:173], 0, s[0:1]
	s_mov_b32 m0, s42
	s_nop 0
	global_load_lds_dwordx4 v[212:213], off
	v_lshl_add_u64 v[212:213], v[170:171], 0, s[0:1]
	s_add_i32 s43, s42, 0x400
	s_mov_b32 m0, s43
	s_nop 0
	global_load_lds_dwordx4 v[212:213], off
	v_lshl_add_u64 v[212:213], v[168:169], 0, s[0:1]
	s_add_i32 s43, s42, 0x800
	s_mov_b32 m0, s43
	s_nop 0
	global_load_lds_dwordx4 v[212:213], off
	s_addk_i32 s42, 0xc00
	v_lshl_add_u64 v[212:213], v[166:167], 0, s[0:1]
	s_mov_b32 m0, s42
	s_nop 0
	global_load_lds_dwordx4 v[212:213], off
	s_setprio 0
	s_waitcnt lgkmcnt(6)
	v_mfma_f32_16x16x32_bf16 v[50:53], v[200:203], v[180:183], v[50:53]
	v_mfma_f32_16x16x32_bf16 v[54:57], v[200:203], v[184:187], v[54:57]
	v_mfma_f32_16x16x32_bf16 v[58:61], v[200:203], v[188:191], v[58:61]
	v_mfma_f32_16x16x32_bf16 v[62:65], v[200:203], v[192:195], v[62:65]
	s_waitcnt lgkmcnt(5)
	v_mfma_f32_16x16x32_bf16 v[66:69], v[204:207], v[180:183], v[66:69]
	v_mfma_f32_16x16x32_bf16 v[70:73], v[204:207], v[184:187], v[70:73]
	v_mfma_f32_16x16x32_bf16 v[74:77], v[204:207], v[188:191], v[74:77]
	v_mfma_f32_16x16x32_bf16 v[78:81], v[204:207], v[192:195], v[78:81]
	s_waitcnt lgkmcnt(4)
	v_mfma_f32_16x16x32_bf16 v[82:85], v[208:211], v[180:183], v[82:85]
	v_mfma_f32_16x16x32_bf16 v[86:89], v[208:211], v[184:187], v[86:89]
	v_mfma_f32_16x16x32_bf16 v[90:93], v[208:211], v[188:191], v[90:93]
	v_mfma_f32_16x16x32_bf16 v[94:97], v[208:211], v[192:195], v[94:97]
	s_waitcnt lgkmcnt(3)
	v_mfma_f32_16x16x32_bf16 v[98:101], v[216:219], v[180:183], v[98:101]
	v_mfma_f32_16x16x32_bf16 v[102:105], v[216:219], v[184:187], v[102:105]
	v_mfma_f32_16x16x32_bf16 v[106:109], v[216:219], v[188:191], v[106:109]
	v_mfma_f32_16x16x32_bf16 v[110:113], v[216:219], v[192:195], v[110:113]
	s_waitcnt lgkmcnt(2)
	v_mfma_f32_16x16x32_bf16 v[114:117], v[226:229], v[180:183], v[114:117]
	v_mfma_f32_16x16x32_bf16 v[118:121], v[226:229], v[184:187], v[118:121]
	v_mfma_f32_16x16x32_bf16 v[122:125], v[226:229], v[188:191], v[122:125]
	v_mfma_f32_16x16x32_bf16 v[126:129], v[226:229], v[192:195], v[126:129]
	s_waitcnt lgkmcnt(1)
	v_mfma_f32_16x16x32_bf16 v[130:133], v[230:233], v[180:183], v[130:133]
	v_mfma_f32_16x16x32_bf16 v[134:137], v[230:233], v[184:187], v[134:137]
	v_mfma_f32_16x16x32_bf16 v[138:141], v[230:233], v[188:191], v[138:141]
	v_mfma_f32_16x16x32_bf16 v[142:145], v[230:233], v[192:195], v[142:145]
	s_waitcnt lgkmcnt(0)
	v_mfma_f32_16x16x32_bf16 v[146:149], v[234:237], v[180:183], v[146:149]
	v_mfma_f32_16x16x32_bf16 v[150:153], v[234:237], v[184:187], v[150:153]
	v_mfma_f32_16x16x32_bf16 v[154:157], v[234:237], v[188:191], v[154:157]
	v_mfma_f32_16x16x32_bf16 v[158:161], v[234:237], v[192:195], v[158:161]
	s_add_i32 s41, s12, 1
	s_cmp_lg_u32 s12, 2
	s_cselect_b32 s12, s41, 0
	s_add_u32 s0, s0, 64
	s_addc_u32 s1, s1, 0
	s_cmpk_eq_i32 s0, 0x780
	s_cbranch_scc0 .LBB0_76
	s_waitcnt vmcnt(6)
	v_mov_b32_e32 v162, v23
	v_mov_b32_e32 v163, v24
	v_mov_b32_e32 v23, v25
	v_mov_b32_e32 v164, v7
	v_mov_b32_e32 v165, v8
	v_pk_add_f32 v[22:23], v[162:163], v[22:23]
	v_mov_b32_e32 v7, v9
	v_pk_add_f32 v[6:7], v[164:165], v[6:7]
	v_add_f32_e32 v0, v22, v23
	v_add_f32_e32 v0, v0, v6
	v_add_f32_e32 v0, v0, v7
	v_fmamk_f32 v0, v0, 0x3a800000, v250
	s_mov_b32 s0, 0x800000
	s_waitcnt vmcnt(4)
	v_mov_b32_e32 v166, v19
	v_mov_b32_e32 v167, v20
	v_mov_b32_e32 v168, v3
	v_mul_f32_e32 v3, 0x4b800000, v0
	v_cmp_gt_f32_e32 vcc, s0, v0
	v_mov_b32_e32 v19, v21
	v_mov_b32_e32 v169, v4
	v_cndmask_b32_e32 v0, v0, v3, vcc
	v_pk_add_f32 v[6:7], v[166:167], v[18:19]
	v_mov_b32_e32 v3, v5
	v_pk_add_f32 v[2:3], v[168:169], v[2:3]
	v_add_f32_e32 v4, v6, v7
	v_add_f32_e32 v2, v4, v2
	v_add_f32_e32 v2, v2, v3
	v_fmamk_f32 v2, v2, 0x3a800000, v250
	v_mul_f32_e32 v3, 0x4b800000, v2
	v_cmp_gt_f32_e64 s[40:41], s0, v2
	s_waitcnt vmcnt(2)
	v_mov_b32_e32 v170, v27
	v_mov_b32_e32 v171, v28
	v_cndmask_b32_e64 v2, v2, v3, s[40:41]
	v_mov_b32_e32 v27, v29
	v_mov_b32_e32 v172, v11
	v_mov_b32_e32 v173, v12
	v_rsq_f32_e32 v179, v2
	v_pk_add_f32 v[2:3], v[170:171], v[26:27]
	v_mov_b32_e32 v11, v13
	v_pk_add_f32 v[4:5], v[172:173], v[10:11]
	v_add_f32_e32 v2, v2, v3
	v_add_f32_e32 v2, v2, v4
	v_add_f32_e32 v2, v2, v5
	v_fmamk_f32 v2, v2, 0x3a800000, v250
	v_mul_f32_e32 v3, 0x4b800000, v2
	v_cmp_gt_f32_e64 s[42:43], s0, v2
	s_waitcnt vmcnt(0)
	v_mov_b32_e32 v174, v31
	v_mov_b32_e32 v175, v32
	v_cndmask_b32_e64 v2, v2, v3, s[42:43]
	v_mov_b32_e32 v31, v33
	v_mov_b32_e32 v180, v15
	v_mov_b32_e32 v181, v16
	v_rsq_f32_e32 v182, v2
	v_pk_add_f32 v[2:3], v[174:175], v[30:31]
	v_mov_b32_e32 v15, v17
	v_pk_add_f32 v[4:5], v[180:181], v[14:15]
	v_add_f32_e32 v2, v2, v3
	v_add_f32_e32 v2, v2, v4
	v_add_f32_e32 v2, v2, v5
	v_fmamk_f32 v2, v2, 0x3a800000, v250
	v_mul_f32_e32 v3, 0x4b800000, v2
	v_cmp_gt_f32_e64 s[44:45], s0, v2
	s_waitcnt vmcnt(6)
	v_add_u32_e32 v183, v178, v176
	s_waitcnt lgkmcnt(0)
	s_barrier
	v_cndmask_b32_e64 v2, v2, v3, s[44:45]
	v_rsq_f32_e32 v180, v2
	ds_read_b128 v[2:5], v183 offset:15360
	ds_read_b128 v[6:9], v183 offset:14336
	ds_read_b128 v[10:13], v183 offset:13312
	ds_read_b128 v[14:17], v183 offset:12288
	ds_read_b128 v[18:21], v183 offset:11264
	ds_read_b128 v[22:25], v183 offset:10240
	ds_read_b128 v[26:29], v183 offset:9216
	ds_read_b128 v[30:33], v183 offset:8192
	v_add3_u32 v178, s13, v177, v176
	ds_read_b128 v[162:165], v178 offset:3072
	ds_read_b128 v[166:169], v178 offset:2048
	ds_read_b128 v[170:173], v178 offset:1024
	ds_read_b128 v[174:177], v178
	v_rsq_f32_e32 v0, v0
	v_mul_f32_e32 v184, 0x45800000, v179
	v_mul_f32_e32 v185, 0x45800000, v182
	v_mul_f32_e32 v186, 0x45800000, v180
	v_mul_f32_e32 v181, 0x45800000, v0
	s_waitcnt lgkmcnt(0)
	v_mfma_f32_16x16x32_bf16 v[34:37], v[30:33], v[174:177], v[34:37]
	v_mfma_f32_16x16x32_bf16 v[38:41], v[30:33], v[170:173], v[38:41]
	v_mfma_f32_16x16x32_bf16 v[42:45], v[30:33], v[166:169], v[42:45]
	v_mfma_f32_16x16x32_bf16 v[46:49], v[30:33], v[162:165], v[46:49]
	v_mfma_f32_16x16x32_bf16 v[50:53], v[26:29], v[174:177], v[50:53]
	v_mfma_f32_16x16x32_bf16 v[54:57], v[26:29], v[170:173], v[54:57]
	v_mfma_f32_16x16x32_bf16 v[58:61], v[26:29], v[166:169], v[58:61]
	v_mfma_f32_16x16x32_bf16 v[62:65], v[26:29], v[162:165], v[62:65]
	v_mfma_f32_16x16x32_bf16 v[66:69], v[22:25], v[174:177], v[66:69]
	v_mfma_f32_16x16x32_bf16 v[70:73], v[22:25], v[170:173], v[70:73]
	v_mfma_f32_16x16x32_bf16 v[74:77], v[22:25], v[166:169], v[74:77]
	v_mfma_f32_16x16x32_bf16 v[22:25], v[22:25], v[162:165], v[78:81]
	v_mfma_f32_16x16x32_bf16 v[78:81], v[18:21], v[174:177], v[82:85]
	v_mfma_f32_16x16x32_bf16 v[82:85], v[18:21], v[170:173], v[86:89]
	v_mfma_f32_16x16x32_bf16 v[86:89], v[18:21], v[166:169], v[90:93]
	v_mfma_f32_16x16x32_bf16 v[18:21], v[18:21], v[162:165], v[94:97]
	v_mfma_f32_16x16x32_bf16 v[90:93], v[14:17], v[174:177], v[98:101]
	v_mfma_f32_16x16x32_bf16 v[94:97], v[14:17], v[170:173], v[102:105]
	v_mfma_f32_16x16x32_bf16 v[98:101], v[14:17], v[166:169], v[106:109]
	v_mfma_f32_16x16x32_bf16 v[14:17], v[14:17], v[162:165], v[110:113]
	v_mfma_f32_16x16x32_bf16 v[102:105], v[10:13], v[174:177], v[114:117]
	v_mfma_f32_16x16x32_bf16 v[106:109], v[10:13], v[170:173], v[118:121]
	v_mfma_f32_16x16x32_bf16 v[110:113], v[10:13], v[166:169], v[122:125]
	v_mfma_f32_16x16x32_bf16 v[10:13], v[10:13], v[162:165], v[126:129]
	v_mfma_f32_16x16x32_bf16 v[114:117], v[6:9], v[174:177], v[130:133]
	v_mfma_f32_16x16x32_bf16 v[118:121], v[6:9], v[170:173], v[134:137]
	v_mfma_f32_16x16x32_bf16 v[122:125], v[6:9], v[166:169], v[138:141]
	v_mfma_f32_16x16x32_bf16 v[6:9], v[6:9], v[162:165], v[142:145]
	v_mfma_f32_16x16x32_bf16 v[126:129], v[2:5], v[174:177], v[146:149]
	v_mfma_f32_16x16x32_bf16 v[130:133], v[2:5], v[170:173], v[150:153]
	v_mfma_f32_16x16x32_bf16 v[134:137], v[2:5], v[166:169], v[154:157]
	v_mfma_f32_16x16x32_bf16 v[2:5], v[2:5], v[162:165], v[158:161]
	s_waitcnt vmcnt(0)
	v_cndmask_b32_e32 v30, v0, v181, vcc
	v_cndmask_b32_e64 v28, v179, v184, s[40:41]
	v_cndmask_b32_e64 v26, v182, v185, s[42:43]
	v_cndmask_b32_e64 v0, v180, v186, s[44:45]
	s_waitcnt lgkmcnt(0)
	s_barrier
	ds_read_b128 v[138:141], v178 offset:24576
	ds_read_b128 v[142:145], v178 offset:25600
	ds_read_b128 v[146:149], v178 offset:26624
	ds_read_b128 v[150:153], v178 offset:27648
	ds_read_b128 v[154:157], v183 offset:32768
	ds_read_b128 v[158:161], v183 offset:33792
	ds_read_b128 v[162:165], v183 offset:34816
	ds_read_b128 v[166:169], v183 offset:35840
	ds_read_b128 v[170:173], v183 offset:36864
	ds_read_b128 v[174:177], v183 offset:37888
	ds_read_b128 v[178:181], v183 offset:38912
	ds_read_b128 v[182:185], v183 offset:39936
	s_waitcnt lgkmcnt(7)
	v_mfma_f32_16x16x32_bf16 v[32:35], v[154:157], v[138:141], v[34:37]
	v_mfma_f32_16x16x32_bf16 v[36:39], v[154:157], v[142:145], v[38:41]
	v_mfma_f32_16x16x32_bf16 v[40:43], v[154:157], v[146:149], v[42:45]
	v_mfma_f32_16x16x32_bf16 v[44:47], v[154:157], v[150:153], v[46:49]
	s_waitcnt lgkmcnt(6)
	v_mfma_f32_16x16x32_bf16 v[48:51], v[158:161], v[138:141], v[50:53]
	v_mfma_f32_16x16x32_bf16 v[52:55], v[158:161], v[142:145], v[54:57]
	v_mfma_f32_16x16x32_bf16 v[56:59], v[158:161], v[146:149], v[58:61]
	v_mfma_f32_16x16x32_bf16 v[60:63], v[158:161], v[150:153], v[62:65]
	s_waitcnt lgkmcnt(5)
	v_mfma_f32_16x16x32_bf16 v[64:67], v[162:165], v[138:141], v[66:69]
	v_mfma_f32_16x16x32_bf16 v[68:71], v[162:165], v[142:145], v[70:73]
	v_mfma_f32_16x16x32_bf16 v[72:75], v[162:165], v[146:149], v[74:77]
	v_mfma_f32_16x16x32_bf16 v[154:157], v[162:165], v[150:153], v[22:25]
	s_waitcnt lgkmcnt(4)
	v_mfma_f32_16x16x32_bf16 v[76:79], v[166:169], v[138:141], v[78:81]
	v_mfma_f32_16x16x32_bf16 v[80:83], v[166:169], v[142:145], v[82:85]
	v_mfma_f32_16x16x32_bf16 v[84:87], v[166:169], v[146:149], v[86:89]
	v_mfma_f32_16x16x32_bf16 v[158:161], v[166:169], v[150:153], v[18:21]
	s_waitcnt lgkmcnt(3)
	v_mfma_f32_16x16x32_bf16 v[88:91], v[170:173], v[138:141], v[90:93]
	v_mfma_f32_16x16x32_bf16 v[92:95], v[170:173], v[142:145], v[94:97]
	v_mfma_f32_16x16x32_bf16 v[96:99], v[170:173], v[146:149], v[98:101]
	v_mfma_f32_16x16x32_bf16 v[162:165], v[170:173], v[150:153], v[14:17]
	s_waitcnt lgkmcnt(2)
	v_mfma_f32_16x16x32_bf16 v[100:103], v[174:177], v[138:141], v[102:105]
	v_mfma_f32_16x16x32_bf16 v[104:107], v[174:177], v[142:145], v[106:109]
	v_mfma_f32_16x16x32_bf16 v[108:111], v[174:177], v[146:149], v[110:113]
	v_mfma_f32_16x16x32_bf16 v[166:169], v[174:177], v[150:153], v[10:13]
	s_waitcnt lgkmcnt(1)
	v_mfma_f32_16x16x32_bf16 v[112:115], v[178:181], v[138:141], v[114:117]
	v_mfma_f32_16x16x32_bf16 v[116:119], v[178:181], v[142:145], v[118:121]
	v_mfma_f32_16x16x32_bf16 v[22:25], v[178:181], v[146:149], v[122:125]
	v_mfma_f32_16x16x32_bf16 v[18:21], v[178:181], v[150:153], v[6:9]
	s_waitcnt lgkmcnt(0)
	v_mfma_f32_16x16x32_bf16 v[14:17], v[182:185], v[138:141], v[126:129]
	v_mfma_f32_16x16x32_bf16 v[10:13], v[182:185], v[142:145], v[130:133]
	v_mfma_f32_16x16x32_bf16 v[6:9], v[182:185], v[146:149], v[134:137]
	v_mfma_f32_16x16x32_bf16 v[2:5], v[182:185], v[150:153], v[2:5]
	v_mov_b32_e32 v27, v224
	s_movk_i32 s0, 0x210
	v_lshrrev_b32_e32 v120, 1, v27
	v_and_b32_e32 v31, 0x7fffff80, v27
	v_and_b32_e32 v120, 24, v120
	v_and_b32_e32 v29, 0x4f, v27
	v_lshl_or_b32 v31, v31, 1, v120
	v_pk_mul_f32 v[32:33], v[30:31], v[32:33] op_sel_hi:[0,1]
	v_pk_mul_f32 v[34:35], v[30:31], v[34:35] op_sel_hi:[0,1]
	v_mad_u32_u24 v29, v29, s0, v31
	v_cvt_pk_bf16_f32 v32, v32, v33
	v_cvt_pk_bf16_f32 v33, v34, v35
	v_pk_mul_f32 v[34:35], v[28:29], v[36:37] op_sel_hi:[0,1]
	v_pk_mul_f32 v[36:37], v[28:29], v[38:39] op_sel_hi:[0,1]
	v_cvt_pk_bf16_f32 v34, v34, v35
	v_cvt_pk_bf16_f32 v35, v36, v37
	v_pk_mul_f32 v[36:37], v[26:27], v[40:41] op_sel_hi:[0,1]
	v_pk_mul_f32 v[38:39], v[26:27], v[42:43] op_sel_hi:[0,1]
	v_cvt_pk_bf16_f32 v36, v36, v37
	v_cvt_pk_bf16_f32 v37, v38, v39
	v_pk_mul_f32 v[38:39], v[0:1], v[44:45] op_sel_hi:[0,1]
	v_pk_mul_f32 v[40:41], v[0:1], v[46:47] op_sel_hi:[0,1]
	v_cvt_pk_bf16_f32 v38, v38, v39
	v_cvt_pk_bf16_f32 v39, v40, v41
	v_pk_mul_f32 v[40:41], v[30:31], v[48:49] op_sel_hi:[0,1]
	v_pk_mul_f32 v[42:43], v[30:31], v[50:51] op_sel_hi:[0,1]
	v_cvt_pk_bf16_f32 v40, v40, v41
	v_cvt_pk_bf16_f32 v41, v42, v43
	s_barrier
	ds_write2_b64 v29, v[32:33], v[40:41] offset1:4
	v_pk_mul_f32 v[32:33], v[28:29], v[52:53] op_sel_hi:[0,1]
	v_pk_mul_f32 v[40:41], v[28:29], v[54:55] op_sel_hi:[0,1]
	v_cvt_pk_bf16_f32 v32, v32, v33
	v_cvt_pk_bf16_f32 v33, v40, v41
	v_add_u32_e32 v31, 0x2000, v29
	ds_write2_b64 v31, v[34:35], v[32:33] offset0:32 offset1:36
	v_pk_mul_f32 v[32:33], v[26:27], v[56:57] op_sel_hi:[0,1]
	v_pk_mul_f32 v[34:35], v[26:27], v[58:59] op_sel_hi:[0,1]
	v_cvt_pk_bf16_f32 v32, v32, v33
	v_cvt_pk_bf16_f32 v33, v34, v35
	v_add_u32_e32 v44, 0x4000, v29
	ds_write2_b64 v44, v[36:37], v[32:33] offset0:64 offset1:68
	v_pk_mul_f32 v[32:33], v[0:1], v[60:61] op_sel_hi:[0,1]
	v_pk_mul_f32 v[34:35], v[0:1], v[62:63] op_sel_hi:[0,1]
	v_cvt_pk_bf16_f32 v32, v32, v33
	v_cvt_pk_bf16_f32 v33, v34, v35
	v_add_u32_e32 v45, 0x6000, v29
	ds_write2_b64 v45, v[38:39], v[32:33] offset0:96 offset1:100
	v_pk_mul_f32 v[32:33], v[30:31], v[64:65] op_sel_hi:[0,1]
	v_pk_mul_f32 v[34:35], v[30:31], v[66:67] op_sel_hi:[0,1]
	v_cvt_pk_bf16_f32 v32, v32, v33
	v_cvt_pk_bf16_f32 v33, v34, v35
	v_pk_mul_f32 v[34:35], v[28:29], v[68:69] op_sel_hi:[0,1]
	v_pk_mul_f32 v[36:37], v[28:29], v[70:71] op_sel_hi:[0,1]
	v_cvt_pk_bf16_f32 v34, v34, v35
	v_cvt_pk_bf16_f32 v35, v36, v37
	v_pk_mul_f32 v[36:37], v[26:27], v[72:73] op_sel_hi:[0,1]
	v_pk_mul_f32 v[38:39], v[26:27], v[74:75] op_sel_hi:[0,1]
	v_cvt_pk_bf16_f32 v36, v36, v37
	v_cvt_pk_bf16_f32 v37, v38, v39
	v_pk_mul_f32 v[38:39], v[0:1], v[154:155] op_sel_hi:[0,1]
	v_pk_mul_f32 v[40:41], v[0:1], v[156:157] op_sel_hi:[0,1]
	v_cvt_pk_bf16_f32 v38, v38, v39
	v_cvt_pk_bf16_f32 v39, v40, v41
	v_pk_mul_f32 v[40:41], v[30:31], v[76:77] op_sel_hi:[0,1]
	v_pk_mul_f32 v[42:43], v[30:31], v[78:79] op_sel_hi:[0,1]
	v_cvt_pk_bf16_f32 v40, v40, v41
	v_cvt_pk_bf16_f32 v41, v42, v43
	ds_write2_b64 v29, v[32:33], v[40:41] offset0:8 offset1:12
	v_pk_mul_f32 v[32:33], v[28:29], v[80:81] op_sel_hi:[0,1]
	v_pk_mul_f32 v[40:41], v[28:29], v[82:83] op_sel_hi:[0,1]
	v_cvt_pk_bf16_f32 v32, v32, v33
	v_cvt_pk_bf16_f32 v33, v40, v41
	ds_write2_b64 v31, v[34:35], v[32:33] offset0:40 offset1:44
	v_pk_mul_f32 v[32:33], v[26:27], v[84:85] op_sel_hi:[0,1]
	v_pk_mul_f32 v[34:35], v[26:27], v[86:87] op_sel_hi:[0,1]
	v_cvt_pk_bf16_f32 v32, v32, v33
	v_cvt_pk_bf16_f32 v33, v34, v35
	ds_write2_b64 v44, v[36:37], v[32:33] offset0:72 offset1:76
	v_pk_mul_f32 v[32:33], v[0:1], v[158:159] op_sel_hi:[0,1]
	v_pk_mul_f32 v[34:35], v[0:1], v[160:161] op_sel_hi:[0,1]
	v_cvt_pk_bf16_f32 v32, v32, v33
	v_cvt_pk_bf16_f32 v33, v34, v35
	ds_write2_b64 v45, v[38:39], v[32:33] offset0:104 offset1:108
	v_pk_mul_f32 v[32:33], v[30:31], v[88:89] op_sel_hi:[0,1]
	v_pk_mul_f32 v[34:35], v[30:31], v[90:91] op_sel_hi:[0,1]
	v_cvt_pk_bf16_f32 v32, v32, v33
	v_cvt_pk_bf16_f32 v33, v34, v35
	v_pk_mul_f32 v[34:35], v[28:29], v[92:93] op_sel_hi:[0,1]
	v_pk_mul_f32 v[36:37], v[28:29], v[94:95] op_sel_hi:[0,1]
	v_cvt_pk_bf16_f32 v34, v34, v35
	v_cvt_pk_bf16_f32 v35, v36, v37
	v_pk_mul_f32 v[36:37], v[26:27], v[96:97] op_sel_hi:[0,1]
	v_pk_mul_f32 v[38:39], v[26:27], v[98:99] op_sel_hi:[0,1]
	v_cvt_pk_bf16_f32 v36, v36, v37
	v_cvt_pk_bf16_f32 v37, v38, v39
	v_pk_mul_f32 v[38:39], v[0:1], v[162:163] op_sel_hi:[0,1]
	v_pk_mul_f32 v[40:41], v[0:1], v[164:165] op_sel_hi:[0,1]
	v_cvt_pk_bf16_f32 v38, v38, v39
	v_cvt_pk_bf16_f32 v39, v40, v41
	v_pk_mul_f32 v[40:41], v[30:31], v[100:101] op_sel_hi:[0,1]
	v_pk_mul_f32 v[42:43], v[30:31], v[102:103] op_sel_hi:[0,1]
	v_cvt_pk_bf16_f32 v40, v40, v41
	v_cvt_pk_bf16_f32 v41, v42, v43
	ds_write2_b64 v29, v[32:33], v[40:41] offset0:16 offset1:20
	v_pk_mul_f32 v[32:33], v[28:29], v[104:105] op_sel_hi:[0,1]
	v_pk_mul_f32 v[40:41], v[28:29], v[106:107] op_sel_hi:[0,1]
	v_cvt_pk_bf16_f32 v32, v32, v33
	v_cvt_pk_bf16_f32 v33, v40, v41
	ds_write2_b64 v31, v[34:35], v[32:33] offset0:48 offset1:52
	v_pk_mul_f32 v[32:33], v[26:27], v[108:109] op_sel_hi:[0,1]
	v_pk_mul_f32 v[34:35], v[26:27], v[110:111] op_sel_hi:[0,1]
	v_cvt_pk_bf16_f32 v32, v32, v33
	v_cvt_pk_bf16_f32 v33, v34, v35
	ds_write2_b64 v44, v[36:37], v[32:33] offset0:80 offset1:84
	v_pk_mul_f32 v[32:33], v[0:1], v[166:167] op_sel_hi:[0,1]
	v_pk_mul_f32 v[34:35], v[0:1], v[168:169] op_sel_hi:[0,1]
	v_cvt_pk_bf16_f32 v32, v32, v33
	v_cvt_pk_bf16_f32 v33, v34, v35
	v_pk_mul_f32 v[18:19], v[0:1], v[18:19] op_sel_hi:[0,1]
	v_pk_mul_f32 v[20:21], v[0:1], v[20:21] op_sel_hi:[0,1]
	v_pk_mul_f32 v[2:3], v[0:1], v[2:3] op_sel_hi:[0,1]
	v_pk_mul_f32 v[4:5], v[0:1], v[4:5] op_sel_hi:[0,1]
	v_lshlrev_b32_e32 v0, 3, v27
	ds_write2_b64 v45, v[38:39], v[32:33] offset0:112 offset1:116
	v_pk_mul_f32 v[32:33], v[30:31], v[112:113] op_sel_hi:[0,1]
	v_pk_mul_f32 v[34:35], v[30:31], v[114:115] op_sel_hi:[0,1]
	v_cvt_pk_bf16_f32 v18, v18, v19
	v_cvt_pk_bf16_f32 v19, v20, v21
	v_cvt_pk_bf16_f32 v2, v2, v3
	v_cvt_pk_bf16_f32 v3, v4, v5
	v_and_b32_e32 v0, 0xf8, v0
	v_cvt_pk_bf16_f32 v32, v32, v33
	v_cvt_pk_bf16_f32 v33, v34, v35
	v_pk_mul_f32 v[34:35], v[28:29], v[116:117] op_sel_hi:[0,1]
	v_pk_mul_f32 v[36:37], v[28:29], v[118:119] op_sel_hi:[0,1]
	v_pk_mul_f32 v[22:23], v[26:27], v[22:23] op_sel_hi:[0,1]
	v_pk_mul_f32 v[24:25], v[26:27], v[24:25] op_sel_hi:[0,1]
	v_pk_mul_f32 v[14:15], v[30:31], v[14:15] op_sel_hi:[0,1]
	v_pk_mul_f32 v[16:17], v[30:31], v[16:17] op_sel_hi:[0,1]
	v_pk_mul_f32 v[10:11], v[28:29], v[10:11] op_sel_hi:[0,1]
	v_pk_mul_f32 v[12:13], v[28:29], v[12:13] op_sel_hi:[0,1]
	v_pk_mul_f32 v[6:7], v[26:27], v[6:7] op_sel_hi:[0,1]
	v_pk_mul_f32 v[8:9], v[26:27], v[8:9] op_sel_hi:[0,1]
	ds_write2_b64 v45, v[18:19], v[2:3] offset0:120 offset1:124
	v_or_b32_e32 v2, s82, v0
	s_movk_i32 s0, 0x800
	v_cvt_pk_bf16_f32 v34, v34, v35
	v_cvt_pk_bf16_f32 v35, v36, v37
	v_cvt_pk_bf16_f32 v22, v22, v23
	v_cvt_pk_bf16_f32 v23, v24, v25
	v_cvt_pk_bf16_f32 v14, v14, v15
	v_cvt_pk_bf16_f32 v15, v16, v17
	v_cvt_pk_bf16_f32 v10, v10, v11
	v_cvt_pk_bf16_f32 v11, v12, v13
	v_cvt_pk_bf16_f32 v6, v6, v7
	v_cvt_pk_bf16_f32 v7, v8, v9
	v_cmp_gt_i32_e64 s[44:45], s0, v2
	s_mov_b64 s[12:13], 12
	s_mov_b64 s[40:41], s[54:55]
	s_mov_b32 s0, s82
	ds_write2_b64 v29, v[32:33], v[14:15] offset0:24 offset1:28
	ds_write2_b64 v31, v[34:35], v[10:11] offset0:56 offset1:60
	ds_write2_b64 v44, v[22:23], v[6:7] offset0:88 offset1:92
	s_waitcnt lgkmcnt(0)
	s_barrier

.LBB0_119:
	s_mul_i32 s68, s1, 0x6000
	s_add_i32 s69, s68, 0xffffa000
	s_cmp_gt_i32 s1, 0
	s_waitcnt vmcnt(6)
	s_cselect_b32 s69, s69, 0xc000
	s_waitcnt lgkmcnt(0)
	s_barrier
	s_setprio 2
	v_or_b32_e32 v0, s68, v146
	v_add_u32_e32 v0, v0, v144
	v_add3_u32 v212, s68, v145, v144
	ds_read_b128 v[164:167], v212 offset:8192
	ds_read_b128 v[148:151], v0
	ds_read_b128 v[152:155], v0 offset:1024
	ds_read_b128 v[156:159], v0 offset:2048
	ds_read_b128 v[160:163], v0 offset:3072
	ds_read_b128 v[168:171], v212 offset:9216
	ds_read_b128 v[172:175], v212 offset:10240
	ds_read_b128 v[176:179], v212 offset:11264
	ds_read_b128 v[180:183], v212 offset:12288
	ds_read_b128 v[184:187], v212 offset:13312
	ds_read_b128 v[188:191], v212 offset:14336
	ds_read_b128 v[192:195], v212 offset:15360
	s_waitcnt lgkmcnt(10)
	v_mfma_f32_16x16x32_bf16 v[126:129], v[164:167], v[148:151], v[126:129]
	s_waitcnt lgkmcnt(9)
	v_mfma_f32_16x16x32_bf16 v[122:125], v[164:167], v[152:155], v[122:125]
	s_waitcnt lgkmcnt(8)
	v_mfma_f32_16x16x32_bf16 v[118:121], v[164:167], v[156:159], v[118:121]
	s_waitcnt lgkmcnt(7)
	v_mfma_f32_16x16x32_bf16 v[114:117], v[164:167], v[160:163], v[114:117]
	v_lshl_add_u64 v[212:213], v[142:143], 0, s[42:43]
	v_lshl_add_u64 v[212:213], v[130:131], 1, v[212:213]
	s_add_i32 s70, s69, s15
	s_mov_b32 m0, s70
	s_nop 0
	global_load_lds_dwordx4 v[212:213], off
	v_lshl_add_u64 v[212:213], v[142:143], 0, s[42:43]
	v_lshl_add_u64 v[212:213], v[132:133], 1, v[212:213]
	s_add_i32 s70, s69, s13
	s_mov_b32 m0, s70
	s_nop 0
	global_load_lds_dwordx4 v[212:213], off
	s_add_i32 s69, s14, s69
	v_lshl_add_u64 v[212:213], v[140:141], 0, s[42:43]
	s_mov_b32 m0, s69
	s_nop 0
	global_load_lds_dwordx4 v[212:213], off
	v_lshl_add_u64 v[212:213], v[138:139], 0, s[42:43]
	s_add_i32 s70, s69, 0x400
	s_mov_b32 m0, s70
	s_nop 0
	global_load_lds_dwordx4 v[212:213], off
	v_lshl_add_u64 v[212:213], v[136:137], 0, s[42:43]
	s_add_i32 s70, s69, 0x800
	s_mov_b32 m0, s70
	s_nop 0
	global_load_lds_dwordx4 v[212:213], off
	v_lshl_add_u64 v[212:213], v[134:135], 0, s[42:43]
	s_addk_i32 s69, 0xc00
	s_mov_b32 m0, s69
	s_nop 0
	global_load_lds_dwordx4 v[212:213], off
	s_setprio 0
	s_waitcnt lgkmcnt(6)
	v_mfma_f32_16x16x32_bf16 v[110:113], v[168:171], v[148:151], v[110:113]
	v_mfma_f32_16x16x32_bf16 v[106:109], v[168:171], v[152:155], v[106:109]
	v_mfma_f32_16x16x32_bf16 v[102:105], v[168:171], v[156:159], v[102:105]
	v_mfma_f32_16x16x32_bf16 v[98:101], v[168:171], v[160:163], v[98:101]
	s_waitcnt lgkmcnt(5)
	v_mfma_f32_16x16x32_bf16 v[94:97], v[172:175], v[148:151], v[94:97]
	v_mfma_f32_16x16x32_bf16 v[90:93], v[172:175], v[152:155], v[90:93]
	v_mfma_f32_16x16x32_bf16 v[86:89], v[172:175], v[156:159], v[86:89]
	v_mfma_f32_16x16x32_bf16 v[82:85], v[172:175], v[160:163], v[82:85]
	s_waitcnt lgkmcnt(4)
	v_mfma_f32_16x16x32_bf16 v[78:81], v[176:179], v[148:151], v[78:81]
	v_mfma_f32_16x16x32_bf16 v[74:77], v[176:179], v[152:155], v[74:77]
	v_mfma_f32_16x16x32_bf16 v[70:73], v[176:179], v[156:159], v[70:73]
	v_mfma_f32_16x16x32_bf16 v[66:69], v[176:179], v[160:163], v[66:69]
	s_waitcnt lgkmcnt(3)
	v_mfma_f32_16x16x32_bf16 v[62:65], v[180:183], v[148:151], v[62:65]
	v_mfma_f32_16x16x32_bf16 v[58:61], v[180:183], v[152:155], v[58:61]
	v_mfma_f32_16x16x32_bf16 v[54:57], v[180:183], v[156:159], v[54:57]
	v_mfma_f32_16x16x32_bf16 v[50:53], v[180:183], v[160:163], v[50:53]
	s_waitcnt lgkmcnt(2)
	v_mfma_f32_16x16x32_bf16 v[46:49], v[184:187], v[148:151], v[46:49]
	v_mfma_f32_16x16x32_bf16 v[42:45], v[184:187], v[152:155], v[42:45]
	v_mfma_f32_16x16x32_bf16 v[38:41], v[184:187], v[156:159], v[38:41]
	v_mfma_f32_16x16x32_bf16 v[34:37], v[184:187], v[160:163], v[34:37]
	s_waitcnt lgkmcnt(1)
	v_mfma_f32_16x16x32_bf16 v[30:33], v[188:191], v[148:151], v[30:33]
	v_mfma_f32_16x16x32_bf16 v[26:29], v[188:191], v[152:155], v[26:29]
	v_mfma_f32_16x16x32_bf16 v[22:25], v[188:191], v[156:159], v[22:25]
	v_mfma_f32_16x16x32_bf16 v[18:21], v[188:191], v[160:163], v[18:21]
	s_waitcnt lgkmcnt(0)
	v_mfma_f32_16x16x32_bf16 v[14:17], v[192:195], v[148:151], v[14:17]
	v_mfma_f32_16x16x32_bf16 v[10:13], v[192:195], v[152:155], v[10:13]
	v_mfma_f32_16x16x32_bf16 v[6:9], v[192:195], v[156:159], v[6:9]
	v_mfma_f32_16x16x32_bf16 v[2:5], v[192:195], v[160:163], v[2:5]
	s_add_i32 s68, s1, 1
	s_cmp_lg_u32 s1, 2
	s_cselect_b32 s1, s68, 0
	s_add_u32 s42, s42, 64
	s_addc_u32 s43, s43, 0
	s_cmpk_eq_i32 s42, 0x1500
	s_cbranch_scc0 .LBB0_119
	s_waitcnt vmcnt(6)
	v_add_u32_e32 v0, v146, v144
	v_add_u32_e32 v221, v145, v144
	s_waitcnt lgkmcnt(0)
	s_barrier
	ds_read_b128 v[130:133], v0
	ds_read_b128 v[134:137], v0 offset:1024
	ds_read_b128 v[138:141], v0 offset:2048
	ds_read_b128 v[146:149], v0 offset:3072
	ds_read_b128 v[142:145], v221 offset:8192
	ds_read_b128 v[150:153], v221 offset:9216
	ds_read_b128 v[154:157], v221 offset:10240
	ds_read_b128 v[158:161], v221 offset:11264
	ds_read_b128 v[162:165], v221 offset:12288
	ds_read_b128 v[166:169], v221 offset:13312
	ds_read_b128 v[170:173], v221 offset:14336
	ds_read_b128 v[174:177], v221 offset:15360
	s_waitcnt lgkmcnt(7)
	v_mfma_f32_16x16x32_bf16 v[126:129], v[142:145], v[130:133], v[126:129]
	v_mfma_f32_16x16x32_bf16 v[122:125], v[142:145], v[134:137], v[122:125]
	v_mfma_f32_16x16x32_bf16 v[118:121], v[142:145], v[138:141], v[118:121]
	v_mfma_f32_16x16x32_bf16 v[114:117], v[142:145], v[146:149], v[114:117]
	s_waitcnt lgkmcnt(6)
	v_mfma_f32_16x16x32_bf16 v[110:113], v[150:153], v[130:133], v[110:113]
	v_mfma_f32_16x16x32_bf16 v[106:109], v[150:153], v[134:137], v[106:109]
	v_mfma_f32_16x16x32_bf16 v[102:105], v[150:153], v[138:141], v[102:105]
	v_mfma_f32_16x16x32_bf16 v[98:101], v[150:153], v[146:149], v[98:101]
	s_waitcnt lgkmcnt(5)
	v_mfma_f32_16x16x32_bf16 v[94:97], v[154:157], v[130:133], v[94:97]
	v_mfma_f32_16x16x32_bf16 v[90:93], v[154:157], v[134:137], v[90:93]
	v_mfma_f32_16x16x32_bf16 v[86:89], v[154:157], v[138:141], v[86:89]
	v_mfma_f32_16x16x32_bf16 v[82:85], v[154:157], v[146:149], v[82:85]
	s_waitcnt lgkmcnt(4)
	v_mfma_f32_16x16x32_bf16 v[78:81], v[158:161], v[130:133], v[78:81]
	v_mfma_f32_16x16x32_bf16 v[74:77], v[158:161], v[134:137], v[74:77]
	v_mfma_f32_16x16x32_bf16 v[70:73], v[158:161], v[138:141], v[70:73]
	v_mfma_f32_16x16x32_bf16 v[66:69], v[158:161], v[146:149], v[66:69]
	s_waitcnt lgkmcnt(3)
	v_mfma_f32_16x16x32_bf16 v[142:145], v[162:165], v[130:133], v[62:65]
	v_mfma_f32_16x16x32_bf16 v[150:153], v[162:165], v[134:137], v[58:61]
	v_mfma_f32_16x16x32_bf16 v[154:157], v[162:165], v[138:141], v[54:57]
	v_mfma_f32_16x16x32_bf16 v[158:161], v[162:165], v[146:149], v[50:53]
	s_waitcnt lgkmcnt(2)
	v_mfma_f32_16x16x32_bf16 v[162:165], v[166:169], v[130:133], v[46:49]
	v_mfma_f32_16x16x32_bf16 v[178:181], v[166:169], v[134:137], v[42:45]
	v_mfma_f32_16x16x32_bf16 v[182:185], v[166:169], v[138:141], v[38:41]
	v_mfma_f32_16x16x32_bf16 v[166:169], v[166:169], v[146:149], v[34:37]
	s_waitcnt lgkmcnt(1)
	v_mfma_f32_16x16x32_bf16 v[186:189], v[170:173], v[130:133], v[30:33]
	v_mfma_f32_16x16x32_bf16 v[190:193], v[170:173], v[134:137], v[26:29]
	v_mfma_f32_16x16x32_bf16 v[194:197], v[170:173], v[138:141], v[22:25]
	v_mfma_f32_16x16x32_bf16 v[170:173], v[170:173], v[146:149], v[18:21]
	s_waitcnt lgkmcnt(0)
	v_mfma_f32_16x16x32_bf16 v[130:133], v[174:177], v[130:133], v[14:17]
	v_mfma_f32_16x16x32_bf16 v[134:137], v[174:177], v[134:137], v[10:13]
	v_mfma_f32_16x16x32_bf16 v[138:141], v[174:177], v[138:141], v[6:9]
	v_mfma_f32_16x16x32_bf16 v[146:149], v[174:177], v[146:149], v[2:5]
	s_waitcnt vmcnt(0)
	s_waitcnt lgkmcnt(0)
	s_barrier
	ds_read_b128 v[174:177], v0 offset:24576
	ds_read_b128 v[198:201], v0 offset:25600
	ds_read_b128 v[202:205], v0 offset:26624
	ds_read_b128 v[206:209], v0 offset:27648
	ds_read_b128 v[14:17], v221 offset:32768
	ds_read_b128 v[30:33], v221 offset:33792
	ds_read_b128 v[46:49], v221 offset:34816
	ds_read_b128 v[62:65], v221 offset:35840
	ds_read_b128 v[210:213], v221 offset:36864
	ds_read_b128 v[216:219], v221 offset:37888
	ds_read_b128 v[226:229], v221 offset:38912
	ds_read_b128 v[230:233], v221 offset:39936
	s_waitcnt lgkmcnt(7)
	v_mfma_f32_16x16x32_bf16 v[2:5], v[14:17], v[174:177], v[126:129]
	v_mfma_f32_16x16x32_bf16 v[6:9], v[14:17], v[198:201], v[122:125]
	v_mfma_f32_16x16x32_bf16 v[10:13], v[14:17], v[202:205], v[118:121]
	v_mfma_f32_16x16x32_bf16 v[14:17], v[14:17], v[206:209], v[114:117]
	s_waitcnt lgkmcnt(6)
	v_mfma_f32_16x16x32_bf16 v[18:21], v[30:33], v[174:177], v[110:113]
	v_mfma_f32_16x16x32_bf16 v[22:25], v[30:33], v[198:201], v[106:109]
	v_mfma_f32_16x16x32_bf16 v[26:29], v[30:33], v[202:205], v[102:105]
	v_mfma_f32_16x16x32_bf16 v[30:33], v[30:33], v[206:209], v[98:101]
	s_waitcnt lgkmcnt(5)
	v_mfma_f32_16x16x32_bf16 v[34:37], v[46:49], v[174:177], v[94:97]
	v_mfma_f32_16x16x32_bf16 v[38:41], v[46:49], v[198:201], v[90:93]
	v_mfma_f32_16x16x32_bf16 v[42:45], v[46:49], v[202:205], v[86:89]
	v_mfma_f32_16x16x32_bf16 v[46:49], v[46:49], v[206:209], v[82:85]
	s_waitcnt lgkmcnt(4)
	v_mfma_f32_16x16x32_bf16 v[50:53], v[62:65], v[174:177], v[78:81]
	v_mfma_f32_16x16x32_bf16 v[54:57], v[62:65], v[198:201], v[74:77]
	v_mfma_f32_16x16x32_bf16 v[58:61], v[62:65], v[202:205], v[70:73]
	v_mfma_f32_16x16x32_bf16 v[62:65], v[62:65], v[206:209], v[66:69]
	s_waitcnt lgkmcnt(3)
	v_mfma_f32_16x16x32_bf16 v[66:69], v[210:213], v[174:177], v[142:145]
	v_mfma_f32_16x16x32_bf16 v[70:73], v[210:213], v[198:201], v[150:153]
	v_mfma_f32_16x16x32_bf16 v[74:77], v[210:213], v[202:205], v[154:157]
	v_mfma_f32_16x16x32_bf16 v[78:81], v[210:213], v[206:209], v[158:161]
	s_waitcnt lgkmcnt(2)
	v_mfma_f32_16x16x32_bf16 v[82:85], v[216:219], v[174:177], v[162:165]
	v_mfma_f32_16x16x32_bf16 v[86:89], v[216:219], v[198:201], v[178:181]
	v_mfma_f32_16x16x32_bf16 v[90:93], v[216:219], v[202:205], v[182:185]
	v_mfma_f32_16x16x32_bf16 v[94:97], v[216:219], v[206:209], v[166:169]
	s_waitcnt lgkmcnt(1)
	v_mfma_f32_16x16x32_bf16 v[98:101], v[226:229], v[174:177], v[186:189]
	v_mfma_f32_16x16x32_bf16 v[102:105], v[226:229], v[198:201], v[190:193]
	v_mfma_f32_16x16x32_bf16 v[106:109], v[226:229], v[202:205], v[194:197]
	v_mfma_f32_16x16x32_bf16 v[110:113], v[226:229], v[206:209], v[170:173]
	s_waitcnt lgkmcnt(0)
	v_mfma_f32_16x16x32_bf16 v[114:117], v[230:233], v[174:177], v[130:133]
	v_mfma_f32_16x16x32_bf16 v[118:121], v[230:233], v[198:201], v[134:137]
	v_mfma_f32_16x16x32_bf16 v[122:125], v[230:233], v[202:205], v[138:141]
	v_mfma_f32_16x16x32_bf16 v[126:129], v[230:233], v[206:209], v[146:149]
	v_mov_b32_e32 v130, v224
	s_ashr_i32 s13, s12, 31
	v_and_b32_e32 v131, 31, v130
	v_ashrrev_i32_e32 v197, 7, v130
	v_ashrrev_i32_e32 v132, 5, v130
	v_lshlrev_b32_e32 v0, 2, v131
	s_lshl_b64 s[68:69], s[12:13], 11
	v_lshlrev_b32_e32 v164, 4, v131
	v_cmp_eq_u32_e64 s[42:43], 0, v131
	v_and_b32_e32 v131, 0x4f, v130
	v_and_b32_e32 v130, 48, v130
	s_movk_i32 s13, 0x210
	v_cmp_lt_i32_e32 vcc, v247, v214
	v_mad_u32_u24 v202, v131, s13, v130
	s_ashr_i32 s1, s0, 31
	v_cndmask_b32_e32 v130, v225, v247, vcc
	v_cmp_lt_i32_e32 vcc, v248, v214
	v_lshlrev_b32_e32 v203, 2, v130
	s_lshl_b32 s70, s87, 1
	v_cndmask_b32_e32 v130, v225, v248, vcc
	v_cmp_lt_i32_e32 vcc, v249, v214
	v_lshlrev_b32_e32 v204, 2, v130
	v_lshl_or_b32 v0, v132, 10, v0
	v_cndmask_b32_e32 v130, v225, v249, vcc
	v_cmp_lt_i32_e32 vcc, v223, v214
	v_lshlrev_b32_e32 v205, 2, v130
	v_mul_lo_u32 v165, v132, s13
	v_cndmask_b32_e32 v130, v225, v223, vcc
	v_cmp_lt_i32_e32 vcc, v252, v214
	v_lshlrev_b32_e32 v206, 2, v130
	s_mov_b32 s14, 0
	v_cndmask_b32_e32 v130, v225, v252, vcc
	v_lshlrev_b32_e32 v207, 2, v130
	v_add_u32_e32 v130, s12, v132
	v_ashrrev_i32_e32 v131, 31, v130
	s_add_u32 s12, s74, s68
	v_lshlrev_b64 v[132:133], 5, v[130:131]
	v_add_u32_e32 v134, 8, v130
	v_add_u32_e32 v136, 16, v130
	v_add_u32_e32 v138, 24, v130
	v_add_u32_e32 v140, 32, v130
	v_add_u32_e32 v142, 40, v130
	v_add_u32_e32 v144, 48, v130
	v_add_u32_e32 v146, 56, v130
	v_add_u32_e32 v148, 64, v130
	v_add_u32_e32 v150, 0x48, v130
	v_add_u32_e32 v152, 0x50, v130
	v_add_u32_e32 v154, 0x58, v130
	v_add_u32_e32 v156, 0x60, v130
	v_add_u32_e32 v158, 0x68, v130
	v_add_u32_e32 v160, 0x70, v130
	v_add_u32_e32 v130, 0x78, v130
	s_addc_u32 s13, s75, s69
	s_lshl_b64 s[0:1], s[0:1], 1
	v_ashrrev_i32_e32 v135, 31, v134
	v_ashrrev_i32_e32 v137, 31, v136
	v_ashrrev_i32_e32 v139, 31, v138
	v_ashrrev_i32_e32 v141, 31, v140
	v_ashrrev_i32_e32 v143, 31, v142
	v_ashrrev_i32_e32 v145, 31, v144
	v_ashrrev_i32_e32 v147, 31, v146
	v_ashrrev_i32_e32 v149, 31, v148
	v_ashrrev_i32_e32 v151, 31, v150
	v_ashrrev_i32_e32 v153, 31, v152
	v_ashrrev_i32_e32 v155, 31, v154
	v_ashrrev_i32_e32 v157, 31, v156
	v_ashrrev_i32_e32 v159, 31, v158
	v_ashrrev_i32_e32 v161, 31, v160
	v_ashrrev_i32_e32 v131, 31, v130
	s_add_u32 s0, s12, s0
	v_lshlrev_b64 v[134:135], 5, v[134:135]
	v_lshlrev_b64 v[136:137], 5, v[136:137]
	v_lshlrev_b64 v[138:139], 5, v[138:139]
	v_lshlrev_b64 v[140:141], 5, v[140:141]
	v_lshlrev_b64 v[142:143], 5, v[142:143]
	v_lshlrev_b64 v[144:145], 5, v[144:145]
	v_lshlrev_b64 v[146:147], 5, v[146:147]
	v_lshlrev_b64 v[148:149], 5, v[148:149]
	v_lshlrev_b64 v[150:151], 5, v[150:151]
	v_lshlrev_b64 v[152:153], 5, v[152:153]
	v_lshlrev_b64 v[154:155], 5, v[154:155]
	v_lshlrev_b64 v[156:157], 5, v[156:157]
	v_lshlrev_b64 v[158:159], 5, v[158:159]
	v_lshlrev_b64 v[160:161], 5, v[160:161]
	v_lshlrev_b64 v[162:163], 5, v[130:131]
	s_addc_u32 s1, s13, s1
	v_lshl_add_u64 v[130:131], v[0:1], 1, s[0:1]
	v_lshl_add_u64 v[132:133], s[44:45], 0, v[132:133]
	v_lshl_add_u64 v[134:135], s[44:45], 0, v[134:135]
	v_lshl_add_u64 v[136:137], s[44:45], 0, v[136:137]
	v_lshl_add_u64 v[138:139], s[44:45], 0, v[138:139]
	v_lshl_add_u64 v[140:141], s[44:45], 0, v[140:141]
	v_lshl_add_u64 v[142:143], s[44:45], 0, v[142:143]
	v_lshl_add_u64 v[144:145], s[44:45], 0, v[144:145]
	v_lshl_add_u64 v[146:147], s[44:45], 0, v[146:147]
	v_lshl_add_u64 v[148:149], s[44:45], 0, v[148:149]
	v_lshl_add_u64 v[150:151], s[44:45], 0, v[150:151]
	v_lshl_add_u64 v[152:153], s[44:45], 0, v[152:153]
	v_lshl_add_u64 v[154:155], s[44:45], 0, v[154:155]
	v_lshl_add_u64 v[156:157], s[44:45], 0, v[156:157]
	v_lshl_add_u64 v[158:159], s[44:45], 0, v[158:159]
	v_lshl_add_u64 v[160:161], s[44:45], 0, v[160:161]
	v_lshl_add_u64 v[162:163], s[44:45], 0, v[162:163]
	s_mov_b64 s[0:1], -1
	v_add_u32_e32 v0, v164, v165
	s_branch .LBB0_122

.LBB0_167:
	s_mul_i32 s4, s43, 0x6000
	s_add_i32 s5, s4, 0xffffa000
	s_cmp_gt_i32 s43, 0
	s_waitcnt vmcnt(6)
	s_cselect_b32 s5, s5, 0xc000
	s_waitcnt lgkmcnt(0)
	s_barrier
	s_setprio 2
	v_add3_u32 v0, s4, v177, v176
	v_add_u32_e32 v0, s47, v0
	v_add3_u32 v212, s4, v178, v176
	ds_read_b128 v[196:199], v212 offset:8192
	ds_read_b128 v[180:183], v0
	ds_read_b128 v[184:187], v0 offset:1024
	ds_read_b128 v[188:191], v0 offset:2048
	ds_read_b128 v[192:195], v0 offset:3072
	ds_read_b128 v[200:203], v212 offset:9216
	ds_read_b128 v[204:207], v212 offset:10240
	ds_read_b128 v[208:211], v212 offset:11264
	ds_read_b128 v[216:219], v212 offset:12288
	ds_read_b128 v[226:229], v212 offset:13312
	ds_read_b128 v[230:233], v212 offset:14336
	ds_read_b128 v[234:237], v212 offset:15360
	s_waitcnt lgkmcnt(10)
	v_mfma_f32_16x16x32_bf16 v[34:37], v[196:199], v[180:183], v[34:37]
	s_waitcnt lgkmcnt(9)
	v_mfma_f32_16x16x32_bf16 v[38:41], v[196:199], v[184:187], v[38:41]
	s_waitcnt lgkmcnt(8)
	v_mfma_f32_16x16x32_bf16 v[42:45], v[196:199], v[188:191], v[42:45]
	s_waitcnt lgkmcnt(7)
	v_mfma_f32_16x16x32_bf16 v[46:49], v[196:199], v[192:195], v[46:49]
	v_lshl_add_u64 v[212:213], v[174:175], 0, s[12:13]
	v_lshl_add_u64 v[212:213], v[162:163], 1, v[212:213]
	s_add_i32 s44, s5, s42
	s_mov_b32 m0, s44
	s_nop 0
	global_load_lds_dwordx4 v[212:213], off
	v_lshl_add_u64 v[212:213], v[174:175], 0, s[12:13]
	v_lshl_add_u64 v[212:213], v[164:165], 1, v[212:213]
	s_add_i32 s44, s5, s40
	s_mov_b32 m0, s44
	s_nop 0
	global_load_lds_dwordx4 v[212:213], off
	s_add_i32 s5, s41, s5
	v_lshl_add_u64 v[212:213], v[172:173], 0, s[12:13]
	s_mov_b32 m0, s5
	s_nop 0
	global_load_lds_dwordx4 v[212:213], off
	v_lshl_add_u64 v[212:213], v[170:171], 0, s[12:13]
	s_add_i32 s44, s5, 0x400
	s_mov_b32 m0, s44
	s_nop 0
	global_load_lds_dwordx4 v[212:213], off
	v_lshl_add_u64 v[212:213], v[168:169], 0, s[12:13]
	s_add_i32 s44, s5, 0x800
	s_mov_b32 m0, s44
	s_nop 0
	global_load_lds_dwordx4 v[212:213], off
	s_addk_i32 s5, 0xc00
	v_lshl_add_u64 v[212:213], v[166:167], 0, s[12:13]
	s_mov_b32 m0, s5
	s_nop 0
	global_load_lds_dwordx4 v[212:213], off
	s_setprio 0
	s_waitcnt lgkmcnt(6)
	v_mfma_f32_16x16x32_bf16 v[50:53], v[200:203], v[180:183], v[50:53]
	v_mfma_f32_16x16x32_bf16 v[54:57], v[200:203], v[184:187], v[54:57]
	v_mfma_f32_16x16x32_bf16 v[58:61], v[200:203], v[188:191], v[58:61]
	v_mfma_f32_16x16x32_bf16 v[62:65], v[200:203], v[192:195], v[62:65]
	s_waitcnt lgkmcnt(5)
	v_mfma_f32_16x16x32_bf16 v[66:69], v[204:207], v[180:183], v[66:69]
	v_mfma_f32_16x16x32_bf16 v[70:73], v[204:207], v[184:187], v[70:73]
	v_mfma_f32_16x16x32_bf16 v[74:77], v[204:207], v[188:191], v[74:77]
	v_mfma_f32_16x16x32_bf16 v[78:81], v[204:207], v[192:195], v[78:81]
	s_waitcnt lgkmcnt(4)
	v_mfma_f32_16x16x32_bf16 v[82:85], v[208:211], v[180:183], v[82:85]
	v_mfma_f32_16x16x32_bf16 v[86:89], v[208:211], v[184:187], v[86:89]
	v_mfma_f32_16x16x32_bf16 v[90:93], v[208:211], v[188:191], v[90:93]
	v_mfma_f32_16x16x32_bf16 v[94:97], v[208:211], v[192:195], v[94:97]
	s_waitcnt lgkmcnt(3)
	v_mfma_f32_16x16x32_bf16 v[98:101], v[216:219], v[180:183], v[98:101]
	v_mfma_f32_16x16x32_bf16 v[102:105], v[216:219], v[184:187], v[102:105]
	v_mfma_f32_16x16x32_bf16 v[106:109], v[216:219], v[188:191], v[106:109]
	v_mfma_f32_16x16x32_bf16 v[110:113], v[216:219], v[192:195], v[110:113]
	s_waitcnt lgkmcnt(2)
	v_mfma_f32_16x16x32_bf16 v[114:117], v[226:229], v[180:183], v[114:117]
	v_mfma_f32_16x16x32_bf16 v[118:121], v[226:229], v[184:187], v[118:121]
	v_mfma_f32_16x16x32_bf16 v[122:125], v[226:229], v[188:191], v[122:125]
	v_mfma_f32_16x16x32_bf16 v[126:129], v[226:229], v[192:195], v[126:129]
	s_waitcnt lgkmcnt(1)
	v_mfma_f32_16x16x32_bf16 v[130:133], v[230:233], v[180:183], v[130:133]
	v_mfma_f32_16x16x32_bf16 v[134:137], v[230:233], v[184:187], v[134:137]
	v_mfma_f32_16x16x32_bf16 v[138:141], v[230:233], v[188:191], v[138:141]
	v_mfma_f32_16x16x32_bf16 v[142:145], v[230:233], v[192:195], v[142:145]
	s_waitcnt lgkmcnt(0)
	v_mfma_f32_16x16x32_bf16 v[146:149], v[234:237], v[180:183], v[146:149]
	v_mfma_f32_16x16x32_bf16 v[150:153], v[234:237], v[184:187], v[150:153]
	v_mfma_f32_16x16x32_bf16 v[154:157], v[234:237], v[188:191], v[154:157]
	v_mfma_f32_16x16x32_bf16 v[158:161], v[234:237], v[192:195], v[158:161]
	s_add_i32 s4, s43, 1
	s_cmp_lg_u32 s43, 2
	s_cselect_b32 s43, s4, 0
	s_add_u32 s12, s12, 64
	s_addc_u32 s13, s13, 0
	s_cmpk_eq_i32 s12, 0x780
	s_cbranch_scc0 .LBB0_167
	s_waitcnt vmcnt(6)
	v_mov_b32_e32 v162, v23
	v_mov_b32_e32 v163, v24
	v_mov_b32_e32 v23, v25
	v_mov_b32_e32 v164, v7
	v_mov_b32_e32 v165, v8
	v_pk_add_f32 v[22:23], v[162:163], v[22:23]
	v_mov_b32_e32 v7, v9
	v_pk_add_f32 v[6:7], v[164:165], v[6:7]
	v_add_f32_e32 v0, v22, v23
	v_add_f32_e32 v0, v0, v6
	v_add_f32_e32 v0, v0, v7
	v_fmamk_f32 v0, v0, 0x3a800000, v250
	s_mov_b32 s4, 0x800000
	s_waitcnt vmcnt(4)
	v_mov_b32_e32 v166, v19
	v_mov_b32_e32 v167, v20
	v_mov_b32_e32 v168, v3
	v_mul_f32_e32 v3, 0x4b800000, v0
	v_cmp_gt_f32_e32 vcc, s4, v0
	v_mov_b32_e32 v19, v21
	v_mov_b32_e32 v169, v4
	v_cndmask_b32_e32 v0, v0, v3, vcc
	v_pk_add_f32 v[6:7], v[166:167], v[18:19]
	v_mov_b32_e32 v3, v5
	v_pk_add_f32 v[2:3], v[168:169], v[2:3]
	v_add_f32_e32 v4, v6, v7
	v_add_f32_e32 v2, v4, v2
	v_add_f32_e32 v2, v2, v3
	v_fmamk_f32 v2, v2, 0x3a800000, v250
	v_mul_f32_e32 v3, 0x4b800000, v2
	v_cmp_gt_f32_e64 s[40:41], s4, v2
	s_waitcnt vmcnt(2)
	v_mov_b32_e32 v170, v27
	v_mov_b32_e32 v171, v28
	v_cndmask_b32_e64 v2, v2, v3, s[40:41]
	v_mov_b32_e32 v27, v29
	v_mov_b32_e32 v172, v11
	v_mov_b32_e32 v173, v12
	v_rsq_f32_e32 v182, v2
	v_pk_add_f32 v[2:3], v[170:171], v[26:27]
	v_mov_b32_e32 v11, v13
	v_pk_add_f32 v[4:5], v[172:173], v[10:11]
	v_add_f32_e32 v2, v2, v3
	v_add_f32_e32 v2, v2, v4
	v_add_f32_e32 v2, v2, v5
	v_fmamk_f32 v2, v2, 0x3a800000, v250
	v_mul_f32_e32 v3, 0x4b800000, v2
	v_cmp_gt_f32_e64 s[42:43], s4, v2
	s_waitcnt vmcnt(0)
	v_mov_b32_e32 v174, v31
	v_mov_b32_e32 v175, v32
	v_cndmask_b32_e64 v2, v2, v3, s[42:43]
	v_mov_b32_e32 v31, v33
	v_mov_b32_e32 v180, v15
	v_mov_b32_e32 v181, v16
	v_rsq_f32_e32 v183, v2
	v_pk_add_f32 v[2:3], v[174:175], v[30:31]
	v_mov_b32_e32 v15, v17
	v_pk_add_f32 v[4:5], v[180:181], v[14:15]
	v_add_f32_e32 v2, v2, v3
	v_add_f32_e32 v2, v2, v4
	v_add_f32_e32 v2, v2, v5
	v_fmamk_f32 v2, v2, 0x3a800000, v250
	v_mul_f32_e32 v3, 0x4b800000, v2
	v_cmp_gt_f32_e64 s[44:45], s4, v2
	s_waitcnt vmcnt(6)
	v_add_u32_e32 v185, v178, v176
	s_waitcnt lgkmcnt(0)
	s_barrier
	v_cndmask_b32_e64 v2, v2, v3, s[44:45]
	v_rsq_f32_e32 v184, v2
	ds_read_b128 v[2:5], v185 offset:15360
	ds_read_b128 v[6:9], v185 offset:14336
	ds_read_b128 v[10:13], v185 offset:13312
	ds_read_b128 v[14:17], v185 offset:12288
	ds_read_b128 v[18:21], v185 offset:11264
	ds_read_b128 v[22:25], v185 offset:10240
	ds_read_b128 v[26:29], v185 offset:9216
	ds_read_b128 v[30:33], v185 offset:8192
	v_add3_u32 v186, s47, v177, v176
	ds_read_b128 v[162:165], v186 offset:3072
	ds_read_b128 v[166:169], v186 offset:2048
	ds_read_b128 v[170:173], v186 offset:1024
	ds_read_b128 v[174:177], v186
	v_rsq_f32_e32 v0, v0
	v_mul_f32_e32 v188, 0x45800000, v182
	v_mul_f32_e32 v189, 0x45800000, v183
	v_mul_f32_e32 v190, 0x45800000, v184
	v_mul_f32_e32 v187, 0x45800000, v0
	s_waitcnt lgkmcnt(0)
	v_mfma_f32_16x16x32_bf16 v[34:37], v[30:33], v[174:177], v[34:37]
	v_mfma_f32_16x16x32_bf16 v[38:41], v[30:33], v[170:173], v[38:41]
	v_mfma_f32_16x16x32_bf16 v[178:181], v[30:33], v[166:169], v[42:45]
	v_mfma_f32_16x16x32_bf16 v[30:33], v[30:33], v[162:165], v[46:49]
	v_mfma_f32_16x16x32_bf16 v[48:51], v[26:29], v[174:177], v[50:53]
	v_mfma_f32_16x16x32_bf16 v[52:55], v[26:29], v[170:173], v[54:57]
	v_mfma_f32_16x16x32_bf16 v[56:59], v[26:29], v[166:169], v[58:61]
	v_mfma_f32_16x16x32_bf16 v[26:29], v[26:29], v[162:165], v[62:65]
	v_mfma_f32_16x16x32_bf16 v[60:63], v[22:25], v[174:177], v[66:69]
	v_mfma_f32_16x16x32_bf16 v[64:67], v[22:25], v[170:173], v[70:73]
	v_mfma_f32_16x16x32_bf16 v[68:71], v[22:25], v[166:169], v[74:77]
	v_mfma_f32_16x16x32_bf16 v[22:25], v[22:25], v[162:165], v[78:81]
	v_mfma_f32_16x16x32_bf16 v[72:75], v[18:21], v[174:177], v[82:85]
	v_mfma_f32_16x16x32_bf16 v[76:79], v[18:21], v[170:173], v[86:89]
	v_mfma_f32_16x16x32_bf16 v[80:83], v[18:21], v[166:169], v[90:93]
	v_mfma_f32_16x16x32_bf16 v[18:21], v[18:21], v[162:165], v[94:97]
	v_mfma_f32_16x16x32_bf16 v[84:87], v[14:17], v[174:177], v[98:101]
	v_mfma_f32_16x16x32_bf16 v[88:91], v[14:17], v[170:173], v[102:105]
	v_mfma_f32_16x16x32_bf16 v[92:95], v[14:17], v[166:169], v[106:109]
	v_mfma_f32_16x16x32_bf16 v[14:17], v[14:17], v[162:165], v[110:113]
	v_mfma_f32_16x16x32_bf16 v[96:99], v[10:13], v[174:177], v[114:117]
	v_mfma_f32_16x16x32_bf16 v[100:103], v[10:13], v[170:173], v[118:121]
	v_mfma_f32_16x16x32_bf16 v[104:107], v[10:13], v[166:169], v[122:125]
	v_mfma_f32_16x16x32_bf16 v[10:13], v[10:13], v[162:165], v[126:129]
	v_mfma_f32_16x16x32_bf16 v[108:111], v[6:9], v[174:177], v[130:133]
	v_mfma_f32_16x16x32_bf16 v[112:115], v[6:9], v[170:173], v[134:137]
	v_mfma_f32_16x16x32_bf16 v[116:119], v[6:9], v[166:169], v[138:141]
	v_mfma_f32_16x16x32_bf16 v[120:123], v[2:5], v[174:177], v[146:149]
	v_mfma_f32_16x16x32_bf16 v[124:127], v[2:5], v[170:173], v[150:153]
	v_mfma_f32_16x16x32_bf16 v[128:131], v[2:5], v[166:169], v[154:157]
	v_mfma_f32_16x16x32_bf16 v[6:9], v[6:9], v[162:165], v[142:145]
	v_mfma_f32_16x16x32_bf16 v[2:5], v[2:5], v[162:165], v[158:161]
	s_waitcnt vmcnt(0)
	v_cndmask_b32_e32 v46, v0, v187, vcc
	v_cndmask_b32_e64 v44, v182, v188, s[40:41]
	v_cndmask_b32_e64 v42, v183, v189, s[42:43]
	v_cndmask_b32_e64 v0, v184, v190, s[44:45]
	s_waitcnt lgkmcnt(0)
	s_barrier
	ds_read_b128 v[132:135], v186 offset:24576
	ds_read_b128 v[136:139], v186 offset:25600
	ds_read_b128 v[140:143], v186 offset:26624
	ds_read_b128 v[144:147], v186 offset:27648
	ds_read_b128 v[148:151], v185 offset:32768
	ds_read_b128 v[152:155], v185 offset:33792
	ds_read_b128 v[156:159], v185 offset:34816
	ds_read_b128 v[160:163], v185 offset:35840
	ds_read_b128 v[164:167], v185 offset:36864
	ds_read_b128 v[168:171], v185 offset:37888
	ds_read_b128 v[172:175], v185 offset:38912
	ds_read_b128 v[182:185], v185 offset:39936
	s_waitcnt lgkmcnt(4)
	v_mfma_f32_16x16x32_bf16 v[242:245], v[160:163], v[140:143], v[80:83]
	v_mfma_f32_16x16x32_bf16 v[246:249], v[160:163], v[144:147], v[18:21]
	s_waitcnt lgkmcnt(3)
	v_mfma_f32_16x16x32_bf16 v[210:213], v[164:167], v[132:135], v[84:87]
	v_mfma_f32_16x16x32_bf16 v[194:197], v[164:167], v[136:139], v[88:91]
	v_mfma_f32_16x16x32_bf16 v[206:209], v[164:167], v[140:143], v[92:95]
	v_mfma_f32_16x16x32_bf16 v[164:167], v[164:167], v[144:147], v[14:17]
	v_mfma_f32_16x16x32_bf16 v[186:189], v[148:151], v[132:135], v[34:37]
	v_mfma_f32_16x16x32_bf16 v[190:193], v[148:151], v[136:139], v[38:41]
	v_mfma_f32_16x16x32_bf16 v[176:179], v[148:151], v[140:143], v[178:181]
	v_mfma_f32_16x16x32_bf16 v[198:201], v[148:151], v[144:147], v[30:33]
	v_mfma_f32_16x16x32_bf16 v[48:51], v[152:155], v[132:135], v[48:51]
	v_mfma_f32_16x16x32_bf16 v[52:55], v[152:155], v[136:139], v[52:55]
	v_mfma_f32_16x16x32_bf16 v[56:59], v[152:155], v[140:143], v[56:59]
	v_mfma_f32_16x16x32_bf16 v[202:205], v[152:155], v[144:147], v[26:29]
	v_mfma_f32_16x16x32_bf16 v[60:63], v[156:159], v[132:135], v[60:63]
	v_mfma_f32_16x16x32_bf16 v[216:219], v[156:159], v[136:139], v[64:67]
	v_mfma_f32_16x16x32_bf16 v[226:229], v[156:159], v[140:143], v[68:71]
	v_mfma_f32_16x16x32_bf16 v[230:233], v[156:159], v[144:147], v[22:25]
	v_mfma_f32_16x16x32_bf16 v[234:237], v[160:163], v[132:135], v[72:75]
	v_mfma_f32_16x16x32_bf16 v[238:241], v[160:163], v[136:139], v[76:79]
	s_waitcnt lgkmcnt(2)
	v_mfma_f32_16x16x32_bf16 v[150:153], v[168:171], v[132:135], v[96:99]
	v_mfma_f32_16x16x32_bf16 v[160:163], v[168:171], v[136:139], v[100:103]
	v_mfma_f32_16x16x32_bf16 v[38:41], v[168:171], v[140:143], v[104:107]
	v_mfma_f32_16x16x32_bf16 v[34:37], v[168:171], v[144:147], v[10:13]
	s_waitcnt lgkmcnt(1)
	v_mfma_f32_16x16x32_bf16 v[30:33], v[172:175], v[132:135], v[108:111]
	v_mfma_f32_16x16x32_bf16 v[26:29], v[172:175], v[136:139], v[112:115]
	v_mfma_f32_16x16x32_bf16 v[22:25], v[172:175], v[140:143], v[116:119]
	v_mfma_f32_16x16x32_bf16 v[18:21], v[172:175], v[144:147], v[6:9]
	s_waitcnt lgkmcnt(0)
	v_mfma_f32_16x16x32_bf16 v[14:17], v[182:185], v[132:135], v[120:123]
	v_mfma_f32_16x16x32_bf16 v[10:13], v[182:185], v[136:139], v[124:127]
	v_mfma_f32_16x16x32_bf16 v[6:9], v[182:185], v[140:143], v[128:131]
	v_mfma_f32_16x16x32_bf16 v[2:5], v[182:185], v[144:147], v[2:5]
	v_mov_b32_e32 v43, v224
	s_lshl_b32 s4, s46, 3
	v_lshrrev_b32_e32 v65, 1, v43
	v_lshlrev_b32_e32 v45, 3, v43
	v_and_b32_e32 v140, 24, v65
	v_ashrrev_i32_e32 v65, 4, v43
	v_and_b32_e32 v47, 56, v45
	v_add_u32_e32 v66, 0x7c, v65
	v_cmp_gt_i32_e32 vcc, 2, v65
	v_ashrrev_i32_e32 v142, 7, v43
	v_and_b32_e32 v64, 0x4f, v43
	v_cmp_gt_i32_e64 s[40:41], 64, v43
	v_cndmask_b32_e32 v66, v66, v65, vcc
	v_and_b32_e32 v67, 0x78, v45
	v_bfe_u32 v45, v45, 6, 1
	v_lshl_add_u32 v65, v65, 1, s4
	v_ashrrev_i32_e32 v43, 3, v43
	s_movk_i32 s4, 0xffe1
	v_pk_mul_f32 v[48:49], v[46:47], v[48:49] op_sel_hi:[0,1]
	v_or_b32_e32 v45, v65, v45
	v_cmp_lt_i32_e64 s[44:45], s4, v43
	s_movk_i32 s4, 0xffc1
	v_cvt_pk_bf16_f32 v74, v48, v49
	v_pk_mul_f32 v[48:49], v[46:47], v[50:51] op_sel_hi:[0,1]
	s_movk_i32 s5, 0x110
	v_add_u32_e32 v132, s15, v43
	v_cmp_lt_i32_e64 s[46:47], s4, v43
	s_movk_i32 s4, 0xffa1
	v_cvt_pk_bf16_f32 v75, v48, v49
	v_pk_mul_f32 v[48:49], v[44:45], v[52:53] op_sel_hi:[0,1]
	v_mul_u32_u24_e32 v141, 0x110, v64
	v_cmp_lt_i32_e64 s[42:43], 1, v43
	v_mul_lo_u32 v64, v43, s5
	v_cmp_lt_i32_e64 s[48:49], s4, v43
	v_add_u32_e32 v43, 0x60, v132
	v_cvt_pk_bf16_f32 v76, v48, v49
	v_pk_mul_f32 v[48:49], v[44:45], v[54:55] op_sel_hi:[0,1]
	v_cvt_pk_bf16_f32 v77, v48, v49
	v_pk_mul_f32 v[48:49], v[42:43], v[56:57] op_sel_hi:[0,1]
	v_cvt_pk_bf16_f32 v78, v48, v49
	v_pk_mul_f32 v[48:49], v[42:43], v[58:59] op_sel_hi:[0,1]
	v_cvt_pk_bf16_f32 v79, v48, v49
	v_pk_mul_f32 v[48:49], v[0:1], v[202:203] op_sel_hi:[0,1]
	v_cvt_pk_bf16_f32 v80, v48, v49
	v_pk_mul_f32 v[48:49], v[0:1], v[204:205] op_sel_hi:[0,1]
	v_cvt_pk_bf16_f32 v81, v48, v49
	v_pk_mul_f32 v[48:49], v[46:47], v[60:61] op_sel_hi:[0,1]
	v_cvt_pk_bf16_f32 v82, v48, v49
	v_pk_mul_f32 v[48:49], v[46:47], v[62:63] op_sel_hi:[0,1]
	v_cvt_pk_bf16_f32 v83, v48, v49
	v_pk_mul_f32 v[48:49], v[44:45], v[216:217] op_sel_hi:[0,1]
	v_cvt_pk_bf16_f32 v84, v48, v49
	v_pk_mul_f32 v[48:49], v[44:45], v[218:219] op_sel_hi:[0,1]
	v_cvt_pk_bf16_f32 v85, v48, v49
	v_pk_mul_f32 v[48:49], v[42:43], v[226:227] op_sel_hi:[0,1]
	v_cvt_pk_bf16_f32 v86, v48, v49
	v_pk_mul_f32 v[48:49], v[42:43], v[228:229] op_sel_hi:[0,1]
	v_cvt_pk_bf16_f32 v87, v48, v49
	v_pk_mul_f32 v[48:49], v[0:1], v[230:231] op_sel_hi:[0,1]
	v_cvt_pk_bf16_f32 v88, v48, v49
	v_pk_mul_f32 v[48:49], v[0:1], v[232:233] op_sel_hi:[0,1]
	v_cvt_pk_bf16_f32 v89, v48, v49
	v_pk_mul_f32 v[48:49], v[46:47], v[234:235] op_sel_hi:[0,1]
	v_cvt_pk_bf16_f32 v90, v48, v49
	v_pk_mul_f32 v[48:49], v[46:47], v[236:237] op_sel_hi:[0,1]
	v_cvt_pk_bf16_f32 v91, v48, v49
	v_pk_mul_f32 v[48:49], v[44:45], v[238:239] op_sel_hi:[0,1]
	v_cvt_pk_bf16_f32 v92, v48, v49
	v_pk_mul_f32 v[48:49], v[44:45], v[240:241] op_sel_hi:[0,1]
	v_cvt_pk_bf16_f32 v93, v48, v49
	v_pk_mul_f32 v[48:49], v[42:43], v[242:243] op_sel_hi:[0,1]
	v_cvt_pk_bf16_f32 v94, v48, v49
	v_pk_mul_f32 v[48:49], v[42:43], v[244:245] op_sel_hi:[0,1]
	v_cvt_pk_bf16_f32 v95, v48, v49
	v_pk_mul_f32 v[48:49], v[0:1], v[246:247] op_sel_hi:[0,1]
	v_cvt_pk_bf16_f32 v96, v48, v49
	v_pk_mul_f32 v[48:49], v[0:1], v[248:249] op_sel_hi:[0,1]
	v_cvt_pk_bf16_f32 v97, v48, v49
	v_pk_mul_f32 v[48:49], v[46:47], v[210:211] op_sel_hi:[0,1]
	v_cvt_pk_bf16_f32 v98, v48, v49
	v_pk_mul_f32 v[48:49], v[46:47], v[212:213] op_sel_hi:[0,1]
	v_cvt_pk_bf16_f32 v99, v48, v49
	v_pk_mul_f32 v[48:49], v[44:45], v[194:195] op_sel_hi:[0,1]
	v_cvt_pk_bf16_f32 v100, v48, v49
	v_pk_mul_f32 v[48:49], v[44:45], v[196:197] op_sel_hi:[0,1]
	v_mul_lo_u32 v66, v66, s5
	v_lshl_add_u32 v144, v47, 1, v64
	v_pk_mul_f32 v[64:65], v[46:47], v[186:187] op_sel_hi:[0,1]
	v_cvt_pk_bf16_f32 v101, v48, v49
	v_pk_mul_f32 v[48:49], v[42:43], v[206:207] op_sel_hi:[0,1]
	v_lshl_add_u32 v143, v67, 1, v66
	v_cvt_pk_bf16_f32 v66, v64, v65
	v_pk_mul_f32 v[64:65], v[46:47], v[188:189] op_sel_hi:[0,1]
	v_cvt_pk_bf16_f32 v102, v48, v49
	v_pk_mul_f32 v[48:49], v[42:43], v[208:209] op_sel_hi:[0,1]
	v_cvt_pk_bf16_f32 v67, v64, v65
	v_pk_mul_f32 v[64:65], v[44:45], v[190:191] op_sel_hi:[0,1]
	v_cvt_pk_bf16_f32 v103, v48, v49
	v_pk_mul_f32 v[48:49], v[0:1], v[164:165] op_sel_hi:[0,1]
	v_cvt_pk_bf16_f32 v68, v64, v65
	v_pk_mul_f32 v[64:65], v[44:45], v[192:193] op_sel_hi:[0,1]
	v_cvt_pk_bf16_f32 v104, v48, v49
	v_pk_mul_f32 v[48:49], v[0:1], v[166:167] op_sel_hi:[0,1]
	v_pk_mul_f32 v[2:3], v[0:1], v[2:3] op_sel_hi:[0,1]
	v_cvt_pk_bf16_f32 v69, v64, v65
	v_pk_mul_f32 v[64:65], v[42:43], v[176:177] op_sel_hi:[0,1]
	v_cvt_pk_bf16_f32 v105, v48, v49
	v_pk_mul_f32 v[48:49], v[46:47], v[150:151] op_sel_hi:[0,1]
	v_cvt_pk_bf16_f32 v128, v2, v3
	v_pk_mul_f32 v[2:3], v[0:1], v[4:5] op_sel_hi:[0,1]
	v_cvt_pk_bf16_f32 v70, v64, v65
	v_pk_mul_f32 v[64:65], v[42:43], v[178:179] op_sel_hi:[0,1]
	v_cvt_pk_bf16_f32 v106, v48, v49
	v_pk_mul_f32 v[48:49], v[46:47], v[152:153] op_sel_hi:[0,1]
	v_cvt_pk_bf16_f32 v129, v2, v3
	v_mov_b64_e32 v[2:3], s[54:55]
	v_add_u32_e32 v134, 32, v132
	v_add_u32_e32 v136, 64, v132
	v_cvt_pk_bf16_f32 v71, v64, v65
	v_pk_mul_f32 v[64:65], v[0:1], v[198:199] op_sel_hi:[0,1]
	v_cvt_pk_bf16_f32 v107, v48, v49
	v_pk_mul_f32 v[48:49], v[44:45], v[160:161] op_sel_hi:[0,1]
	v_pk_mul_f32 v[38:39], v[42:43], v[38:39] op_sel_hi:[0,1]
	v_pk_mul_f32 v[34:35], v[0:1], v[34:35] op_sel_hi:[0,1]
	v_pk_mul_f32 v[30:31], v[46:47], v[30:31] op_sel_hi:[0,1]
	v_pk_mul_f32 v[26:27], v[44:45], v[26:27] op_sel_hi:[0,1]
	v_pk_mul_f32 v[22:23], v[42:43], v[22:23] op_sel_hi:[0,1]
	v_pk_mul_f32 v[18:19], v[0:1], v[18:19] op_sel_hi:[0,1]
	v_pk_mul_f32 v[14:15], v[46:47], v[14:15] op_sel_hi:[0,1]
	v_pk_mul_f32 v[10:11], v[44:45], v[10:11] op_sel_hi:[0,1]
	v_pk_mul_f32 v[6:7], v[42:43], v[6:7] op_sel_hi:[0,1]
	v_mad_i64_i32 v[130:131], s[4:5], v45, s19, v[2:3]
	v_mov_b64_e32 v[2:3], s[52:53]
	v_cvt_pk_bf16_f32 v72, v64, v65
	v_pk_mul_f32 v[64:65], v[0:1], v[200:201] op_sel_hi:[0,1]
	v_cvt_pk_bf16_f32 v108, v48, v49
	v_pk_mul_f32 v[48:49], v[44:45], v[162:163] op_sel_hi:[0,1]
	v_cvt_pk_bf16_f32 v110, v38, v39
	v_pk_mul_f32 v[38:39], v[42:43], v[40:41] op_sel_hi:[0,1]
	v_cvt_pk_bf16_f32 v112, v34, v35
	v_pk_mul_f32 v[34:35], v[0:1], v[36:37] op_sel_hi:[0,1]
	v_cvt_pk_bf16_f32 v114, v30, v31
	v_pk_mul_f32 v[30:31], v[46:47], v[32:33] op_sel_hi:[0,1]
	v_cvt_pk_bf16_f32 v116, v26, v27
	v_pk_mul_f32 v[26:27], v[44:45], v[28:29] op_sel_hi:[0,1]
	v_cvt_pk_bf16_f32 v118, v22, v23
	v_pk_mul_f32 v[22:23], v[42:43], v[24:25] op_sel_hi:[0,1]
	v_cvt_pk_bf16_f32 v120, v18, v19
	v_pk_mul_f32 v[18:19], v[0:1], v[20:21] op_sel_hi:[0,1]
	v_cvt_pk_bf16_f32 v122, v14, v15
	v_pk_mul_f32 v[14:15], v[46:47], v[16:17] op_sel_hi:[0,1]
	v_cvt_pk_bf16_f32 v124, v10, v11
	v_pk_mul_f32 v[10:11], v[44:45], v[12:13] op_sel_hi:[0,1]
	v_cvt_pk_bf16_f32 v126, v6, v7
	v_pk_mul_f32 v[6:7], v[42:43], v[8:9] op_sel_hi:[0,1]
	v_mad_i64_i32 v[132:133], s[4:5], v132, s19, v[2:3]
	v_mad_i64_i32 v[134:135], s[4:5], v134, s19, v[2:3]
	v_mad_i64_i32 v[136:137], s[4:5], v136, s19, v[2:3]
	v_mad_i64_i32 v[138:139], s[4:5], v43, s19, v[2:3]
	v_add_u32_e32 v145, 0xfffffef0, v144
	v_add_u32_e32 v146, 0xffffff70, v144
	v_add_u32_e32 v147, 0xfffffde0, v144
	v_add_u32_e32 v148, 0xfffffe60, v144
	v_add_u32_e32 v149, 0x2200, v144
	v_add_u32_e32 v168, 0x20f0, v144
	v_add_u32_e32 v169, 0x2170, v144
	v_add_u32_e32 v170, 0x1fe0, v144
	v_add_u32_e32 v171, 0x2060, v144
	v_add_u32_e32 v154, 0x4400, v144
	v_add_u32_e32 v155, 0x42f0, v144
	v_add_u32_e32 v156, 0x4370, v144
	v_add_u32_e32 v157, 0x41e0, v144
	v_add_u32_e32 v158, 0x4260, v144
	v_add_u32_e32 v159, 0x6600, v144
	v_add_u32_e32 v172, 0x64f0, v144
	v_add_u32_e32 v173, 0x6570, v144
	v_add_u32_e32 v174, 0x63e0, v144
	v_add_u32_e32 v175, 0x6460, v144
	v_cvt_pk_bf16_f32 v73, v64, v65
	v_cvt_pk_bf16_f32 v109, v48, v49
	v_cvt_pk_bf16_f32 v111, v38, v39
	v_cvt_pk_bf16_f32 v113, v34, v35
	v_cvt_pk_bf16_f32 v115, v30, v31
	v_cvt_pk_bf16_f32 v117, v26, v27
	v_cvt_pk_bf16_f32 v119, v22, v23
	v_cvt_pk_bf16_f32 v121, v18, v19
	v_cvt_pk_bf16_f32 v123, v14, v15
	v_cvt_pk_bf16_f32 v125, v10, v11
	v_cvt_pk_bf16_f32 v127, v6, v7
	v_lshl_or_b32 v0, s14, 7, v47
	s_mov_b32 s4, 0
	s_mov_b64 s[12:13], -1
	v_add_u32_e32 v164, v140, v141
	v_xor_b32_e32 v246, 32, v225
	v_xor_b32_e32 v247, 16, v225
	v_xor_b32_e32 v248, 8, v225
	v_xor_b32_e32 v249, 4, v225
	v_mov_b32_e32 v243, v221
	s_branch .LBB0_171

.LBB0_194:
	s_mul_i32 s48, s13, 0x6000
	s_add_i32 s49, s48, 0xffffa000
	s_cmp_gt_i32 s13, 0
	s_waitcnt vmcnt(6)
	s_cselect_b32 s49, s49, 0xc000
	s_waitcnt lgkmcnt(0)
	s_barrier
	s_setprio 2
	v_or_b32_e32 v0, s48, v146
	v_add_u32_e32 v0, v0, v144
	v_add3_u32 v212, s48, v145, v144
	ds_read_b128 v[164:167], v212 offset:8192
	ds_read_b128 v[148:151], v0
	ds_read_b128 v[152:155], v0 offset:1024
	ds_read_b128 v[156:159], v0 offset:2048
	ds_read_b128 v[160:163], v0 offset:3072
	ds_read_b128 v[168:171], v212 offset:9216
	ds_read_b128 v[172:175], v212 offset:10240
	ds_read_b128 v[176:179], v212 offset:11264
	ds_read_b128 v[180:183], v212 offset:12288
	ds_read_b128 v[184:187], v212 offset:13312
	ds_read_b128 v[188:191], v212 offset:14336
	ds_read_b128 v[198:201], v212 offset:15360
	s_waitcnt lgkmcnt(10)
	v_mfma_f32_16x16x32_bf16 v[126:129], v[164:167], v[148:151], v[126:129]
	s_waitcnt lgkmcnt(9)
	v_mfma_f32_16x16x32_bf16 v[122:125], v[164:167], v[152:155], v[122:125]
	s_waitcnt lgkmcnt(8)
	v_mfma_f32_16x16x32_bf16 v[118:121], v[164:167], v[156:159], v[118:121]
	s_waitcnt lgkmcnt(7)
	v_mfma_f32_16x16x32_bf16 v[114:117], v[164:167], v[160:163], v[114:117]
	v_lshl_add_u64 v[212:213], v[142:143], 0, s[40:41]
	v_lshl_add_u64 v[212:213], v[130:131], 1, v[212:213]
	s_add_i32 s69, s49, s47
	s_mov_b32 m0, s69
	s_nop 0
	global_load_lds_dwordx4 v[212:213], off
	v_lshl_add_u64 v[212:213], v[142:143], 0, s[40:41]
	v_lshl_add_u64 v[212:213], v[132:133], 1, v[212:213]
	s_add_i32 s69, s49, s14
	s_mov_b32 m0, s69
	s_nop 0
	global_load_lds_dwordx4 v[212:213], off
	s_add_i32 s49, s15, s49
	v_lshl_add_u64 v[212:213], v[140:141], 0, s[40:41]
	s_mov_b32 m0, s49
	s_nop 0
	global_load_lds_dwordx4 v[212:213], off
	v_lshl_add_u64 v[212:213], v[138:139], 0, s[40:41]
	s_add_i32 s69, s49, 0x400
	s_mov_b32 m0, s69
	s_nop 0
	global_load_lds_dwordx4 v[212:213], off
	v_lshl_add_u64 v[212:213], v[136:137], 0, s[40:41]
	s_add_i32 s69, s49, 0x800
	s_mov_b32 m0, s69
	s_nop 0
	global_load_lds_dwordx4 v[212:213], off
	v_lshl_add_u64 v[212:213], v[134:135], 0, s[40:41]
	s_addk_i32 s49, 0xc00
	s_mov_b32 m0, s49
	s_nop 0
	global_load_lds_dwordx4 v[212:213], off
	s_setprio 0
	s_waitcnt lgkmcnt(6)
	v_mfma_f32_16x16x32_bf16 v[110:113], v[168:171], v[148:151], v[110:113]
	v_mfma_f32_16x16x32_bf16 v[106:109], v[168:171], v[152:155], v[106:109]
	v_mfma_f32_16x16x32_bf16 v[102:105], v[168:171], v[156:159], v[102:105]
	v_mfma_f32_16x16x32_bf16 v[98:101], v[168:171], v[160:163], v[98:101]
	s_waitcnt lgkmcnt(5)
	v_mfma_f32_16x16x32_bf16 v[94:97], v[172:175], v[148:151], v[94:97]
	v_mfma_f32_16x16x32_bf16 v[90:93], v[172:175], v[152:155], v[90:93]
	v_mfma_f32_16x16x32_bf16 v[86:89], v[172:175], v[156:159], v[86:89]
	v_mfma_f32_16x16x32_bf16 v[82:85], v[172:175], v[160:163], v[82:85]
	s_waitcnt lgkmcnt(4)
	v_mfma_f32_16x16x32_bf16 v[78:81], v[176:179], v[148:151], v[78:81]
	v_mfma_f32_16x16x32_bf16 v[74:77], v[176:179], v[152:155], v[74:77]
	v_mfma_f32_16x16x32_bf16 v[70:73], v[176:179], v[156:159], v[70:73]
	v_mfma_f32_16x16x32_bf16 v[66:69], v[176:179], v[160:163], v[66:69]
	s_waitcnt lgkmcnt(3)
	v_mfma_f32_16x16x32_bf16 v[62:65], v[180:183], v[148:151], v[62:65]
	v_mfma_f32_16x16x32_bf16 v[58:61], v[180:183], v[152:155], v[58:61]
	v_mfma_f32_16x16x32_bf16 v[54:57], v[180:183], v[156:159], v[54:57]
	v_mfma_f32_16x16x32_bf16 v[50:53], v[180:183], v[160:163], v[50:53]
	s_waitcnt lgkmcnt(2)
	v_mfma_f32_16x16x32_bf16 v[46:49], v[184:187], v[148:151], v[46:49]
	v_mfma_f32_16x16x32_bf16 v[42:45], v[184:187], v[152:155], v[42:45]
	v_mfma_f32_16x16x32_bf16 v[38:41], v[184:187], v[156:159], v[38:41]
	v_mfma_f32_16x16x32_bf16 v[34:37], v[184:187], v[160:163], v[34:37]
	s_waitcnt lgkmcnt(1)
	v_mfma_f32_16x16x32_bf16 v[30:33], v[188:191], v[148:151], v[30:33]
	v_mfma_f32_16x16x32_bf16 v[26:29], v[188:191], v[152:155], v[26:29]
	v_mfma_f32_16x16x32_bf16 v[22:25], v[188:191], v[156:159], v[22:25]
	v_mfma_f32_16x16x32_bf16 v[18:21], v[188:191], v[160:163], v[18:21]
	s_waitcnt lgkmcnt(0)
	v_mfma_f32_16x16x32_bf16 v[14:17], v[198:201], v[148:151], v[14:17]
	v_mfma_f32_16x16x32_bf16 v[10:13], v[198:201], v[152:155], v[10:13]
	v_mfma_f32_16x16x32_bf16 v[6:9], v[198:201], v[156:159], v[6:9]
	v_mfma_f32_16x16x32_bf16 v[2:5], v[198:201], v[160:163], v[2:5]
	s_add_i32 s48, s13, 1
	s_cmp_lg_u32 s13, 2
	s_cselect_b32 s13, s48, 0
	s_add_u32 s40, s40, 64
	s_addc_u32 s41, s41, 0
	s_cmpk_eq_i32 s40, 0x780
	s_cbranch_scc0 .LBB0_194
	s_waitcnt vmcnt(6)
	v_add_u32_e32 v0, v146, v144
	v_add_u32_e32 v194, v145, v144
	s_waitcnt lgkmcnt(0)
	s_barrier
	ds_read_b128 v[130:133], v0
	ds_read_b128 v[134:137], v0 offset:1024
	ds_read_b128 v[138:141], v0 offset:2048
	ds_read_b128 v[146:149], v0 offset:3072
	ds_read_b128 v[142:145], v194 offset:8192
	ds_read_b128 v[150:153], v194 offset:9216
	ds_read_b128 v[154:157], v194 offset:10240
	ds_read_b128 v[158:161], v194 offset:11264
	ds_read_b128 v[162:165], v194 offset:12288
	ds_read_b128 v[166:169], v194 offset:13312
	ds_read_b128 v[170:173], v194 offset:14336
	ds_read_b128 v[174:177], v194 offset:15360
	s_waitcnt lgkmcnt(7)
	v_mfma_f32_16x16x32_bf16 v[126:129], v[142:145], v[130:133], v[126:129]
	v_mfma_f32_16x16x32_bf16 v[122:125], v[142:145], v[134:137], v[122:125]
	v_mfma_f32_16x16x32_bf16 v[118:121], v[142:145], v[138:141], v[118:121]
	v_mfma_f32_16x16x32_bf16 v[114:117], v[142:145], v[146:149], v[114:117]
	s_waitcnt lgkmcnt(6)
	v_mfma_f32_16x16x32_bf16 v[110:113], v[150:153], v[130:133], v[110:113]
	v_mfma_f32_16x16x32_bf16 v[106:109], v[150:153], v[134:137], v[106:109]
	v_mfma_f32_16x16x32_bf16 v[102:105], v[150:153], v[138:141], v[102:105]
	v_mfma_f32_16x16x32_bf16 v[98:101], v[150:153], v[146:149], v[98:101]
	s_waitcnt lgkmcnt(5)
	v_mfma_f32_16x16x32_bf16 v[94:97], v[154:157], v[130:133], v[94:97]
	v_mfma_f32_16x16x32_bf16 v[90:93], v[154:157], v[134:137], v[90:93]
	v_mfma_f32_16x16x32_bf16 v[86:89], v[154:157], v[138:141], v[86:89]
	v_mfma_f32_16x16x32_bf16 v[82:85], v[154:157], v[146:149], v[82:85]
	s_waitcnt lgkmcnt(4)
	v_mfma_f32_16x16x32_bf16 v[78:81], v[158:161], v[130:133], v[78:81]
	v_mfma_f32_16x16x32_bf16 v[74:77], v[158:161], v[134:137], v[74:77]
	v_mfma_f32_16x16x32_bf16 v[70:73], v[158:161], v[138:141], v[70:73]
	v_mfma_f32_16x16x32_bf16 v[66:69], v[158:161], v[146:149], v[66:69]
	s_waitcnt lgkmcnt(3)
	v_mfma_f32_16x16x32_bf16 v[142:145], v[162:165], v[130:133], v[62:65]
	v_mfma_f32_16x16x32_bf16 v[150:153], v[162:165], v[134:137], v[58:61]
	v_mfma_f32_16x16x32_bf16 v[154:157], v[162:165], v[138:141], v[54:57]
	v_mfma_f32_16x16x32_bf16 v[158:161], v[162:165], v[146:149], v[50:53]
	s_waitcnt lgkmcnt(2)
	v_mfma_f32_16x16x32_bf16 v[162:165], v[166:169], v[130:133], v[46:49]
	v_mfma_f32_16x16x32_bf16 v[178:181], v[166:169], v[134:137], v[42:45]
	v_mfma_f32_16x16x32_bf16 v[182:185], v[166:169], v[138:141], v[38:41]
	v_mfma_f32_16x16x32_bf16 v[166:169], v[166:169], v[146:149], v[34:37]
	s_waitcnt lgkmcnt(1)
	v_mfma_f32_16x16x32_bf16 v[186:189], v[170:173], v[130:133], v[30:33]
	v_mfma_f32_16x16x32_bf16 v[190:193], v[170:173], v[134:137], v[26:29]
	v_mfma_f32_16x16x32_bf16 v[198:201], v[170:173], v[138:141], v[22:25]
	v_mfma_f32_16x16x32_bf16 v[170:173], v[170:173], v[146:149], v[18:21]
	s_waitcnt lgkmcnt(0)
	v_mfma_f32_16x16x32_bf16 v[130:133], v[174:177], v[130:133], v[14:17]
	v_mfma_f32_16x16x32_bf16 v[134:137], v[174:177], v[134:137], v[10:13]
	v_mfma_f32_16x16x32_bf16 v[138:141], v[174:177], v[138:141], v[6:9]
	v_mfma_f32_16x16x32_bf16 v[146:149], v[174:177], v[146:149], v[2:5]
	s_waitcnt vmcnt(0)
	s_waitcnt lgkmcnt(0)
	s_barrier
	ds_read_b128 v[174:177], v0 offset:24576
	ds_read_b128 v[202:205], v0 offset:25600
	ds_read_b128 v[216:219], v0 offset:26624
	ds_read_b128 v[226:229], v0 offset:27648
	ds_read_b128 v[14:17], v194 offset:32768
	ds_read_b128 v[30:33], v194 offset:33792
	ds_read_b128 v[46:49], v194 offset:34816
	ds_read_b128 v[62:65], v194 offset:35840
	ds_read_b128 v[230:233], v194 offset:36864
	ds_read_b128 v[234:237], v194 offset:37888
	ds_read_b128 v[238:241], v194 offset:38912
	ds_read_b128 v[242:245], v194 offset:39936
	s_waitcnt lgkmcnt(7)
	v_mfma_f32_16x16x32_bf16 v[2:5], v[14:17], v[174:177], v[126:129]
	v_mfma_f32_16x16x32_bf16 v[6:9], v[14:17], v[202:205], v[122:125]
	v_mfma_f32_16x16x32_bf16 v[10:13], v[14:17], v[216:219], v[118:121]
	v_mfma_f32_16x16x32_bf16 v[14:17], v[14:17], v[226:229], v[114:117]
	s_waitcnt lgkmcnt(6)
	v_mfma_f32_16x16x32_bf16 v[18:21], v[30:33], v[174:177], v[110:113]
	v_mfma_f32_16x16x32_bf16 v[22:25], v[30:33], v[202:205], v[106:109]
	v_mfma_f32_16x16x32_bf16 v[26:29], v[30:33], v[216:219], v[102:105]
	v_mfma_f32_16x16x32_bf16 v[30:33], v[30:33], v[226:229], v[98:101]
	s_waitcnt lgkmcnt(5)
	v_mfma_f32_16x16x32_bf16 v[34:37], v[46:49], v[174:177], v[94:97]
	v_mfma_f32_16x16x32_bf16 v[38:41], v[46:49], v[202:205], v[90:93]
	v_mfma_f32_16x16x32_bf16 v[42:45], v[46:49], v[216:219], v[86:89]
	v_mfma_f32_16x16x32_bf16 v[46:49], v[46:49], v[226:229], v[82:85]
	s_waitcnt lgkmcnt(4)
	v_mfma_f32_16x16x32_bf16 v[50:53], v[62:65], v[174:177], v[78:81]
	v_mfma_f32_16x16x32_bf16 v[54:57], v[62:65], v[202:205], v[74:77]
	v_mfma_f32_16x16x32_bf16 v[58:61], v[62:65], v[216:219], v[70:73]
	v_mfma_f32_16x16x32_bf16 v[62:65], v[62:65], v[226:229], v[66:69]
	s_waitcnt lgkmcnt(3)
	v_mfma_f32_16x16x32_bf16 v[66:69], v[230:233], v[174:177], v[142:145]
	v_mfma_f32_16x16x32_bf16 v[70:73], v[230:233], v[202:205], v[150:153]
	v_mfma_f32_16x16x32_bf16 v[74:77], v[230:233], v[216:219], v[154:157]
	v_mfma_f32_16x16x32_bf16 v[78:81], v[230:233], v[226:229], v[158:161]
	s_waitcnt lgkmcnt(2)
	v_mfma_f32_16x16x32_bf16 v[82:85], v[234:237], v[174:177], v[162:165]
	v_mfma_f32_16x16x32_bf16 v[86:89], v[234:237], v[202:205], v[178:181]
	v_mfma_f32_16x16x32_bf16 v[90:93], v[234:237], v[216:219], v[182:185]
	v_mfma_f32_16x16x32_bf16 v[94:97], v[234:237], v[226:229], v[166:169]
	s_waitcnt lgkmcnt(1)
	v_mfma_f32_16x16x32_bf16 v[98:101], v[238:241], v[174:177], v[186:189]
	v_mfma_f32_16x16x32_bf16 v[102:105], v[238:241], v[202:205], v[190:193]
	v_mfma_f32_16x16x32_bf16 v[106:109], v[238:241], v[216:219], v[198:201]
	v_mfma_f32_16x16x32_bf16 v[110:113], v[238:241], v[226:229], v[170:173]
	s_waitcnt lgkmcnt(0)
	v_mfma_f32_16x16x32_bf16 v[114:117], v[242:245], v[174:177], v[130:133]
	v_mfma_f32_16x16x32_bf16 v[118:121], v[242:245], v[202:205], v[134:137]
	v_mfma_f32_16x16x32_bf16 v[122:125], v[242:245], v[216:219], v[138:141]
	v_mfma_f32_16x16x32_bf16 v[126:129], v[242:245], v[226:229], v[146:149]
	v_mov_b32_e32 v130, v224
	s_ashr_i32 s13, s12, 31
	v_and_b32_e32 v131, 31, v130
	v_ashrrev_i32_e32 v197, 7, v130
	v_ashrrev_i32_e32 v132, 5, v130
	v_lshlrev_b32_e32 v0, 2, v131
	s_lshl_b64 s[48:49], s[12:13], 11
	v_lshlrev_b32_e32 v164, 4, v131
	v_cmp_eq_u32_e64 s[40:41], 0, v131
	v_and_b32_e32 v131, 0x4f, v130
	v_and_b32_e32 v130, 48, v130
	s_movk_i32 s13, 0x210
	v_cmp_lt_i32_e32 vcc, v247, v214
	v_mad_u32_u24 v202, v131, s13, v130
	s_ashr_i32 s47, s46, 31
	v_cndmask_b32_e32 v130, v225, v247, vcc
	v_cmp_lt_i32_e32 vcc, v248, v214
	v_lshlrev_b32_e32 v203, 2, v130
	s_lshl_b32 s69, s57, 1
	v_cndmask_b32_e32 v130, v225, v248, vcc
	v_cmp_lt_i32_e32 vcc, v249, v214
	v_lshlrev_b32_e32 v204, 2, v130
	s_add_u32 s15, s53, s48
	v_cndmask_b32_e32 v130, v225, v249, vcc
	v_cmp_lt_i32_e32 vcc, v223, v214
	v_lshlrev_b32_e32 v205, 2, v130
	v_lshl_or_b32 v0, v132, 10, v0
	v_cndmask_b32_e32 v130, v225, v223, vcc
	v_cmp_lt_i32_e32 vcc, v252, v214
	v_lshlrev_b32_e32 v206, 2, v130
	v_mul_lo_u32 v165, v132, s13
	v_cndmask_b32_e32 v130, v225, v252, vcc
	v_lshlrev_b32_e32 v207, 2, v130
	v_add_u32_e32 v130, s12, v132
	v_ashrrev_i32_e32 v131, 31, v130
	v_lshlrev_b64 v[132:133], 5, v[130:131]
	v_add_u32_e32 v134, 8, v130
	v_add_u32_e32 v136, 16, v130
	v_add_u32_e32 v138, 24, v130
	v_add_u32_e32 v140, 32, v130
	v_add_u32_e32 v142, 40, v130
	v_add_u32_e32 v144, 48, v130
	v_add_u32_e32 v146, 56, v130
	v_add_u32_e32 v148, 64, v130
	v_add_u32_e32 v150, 0x48, v130
	v_add_u32_e32 v152, 0x50, v130
	v_add_u32_e32 v154, 0x58, v130
	v_add_u32_e32 v156, 0x60, v130
	v_add_u32_e32 v158, 0x68, v130
	v_add_u32_e32 v160, 0x70, v130
	v_add_u32_e32 v130, 0x78, v130
	s_addc_u32 s48, s54, s49
	s_lshl_b64 s[12:13], s[46:47], 1
	v_ashrrev_i32_e32 v135, 31, v134
	v_ashrrev_i32_e32 v137, 31, v136
	v_ashrrev_i32_e32 v139, 31, v138
	v_ashrrev_i32_e32 v141, 31, v140
	v_ashrrev_i32_e32 v143, 31, v142
	v_ashrrev_i32_e32 v145, 31, v144
	v_ashrrev_i32_e32 v147, 31, v146
	v_ashrrev_i32_e32 v149, 31, v148
	v_ashrrev_i32_e32 v151, 31, v150
	v_ashrrev_i32_e32 v153, 31, v152
	v_ashrrev_i32_e32 v155, 31, v154
	v_ashrrev_i32_e32 v157, 31, v156
	v_ashrrev_i32_e32 v159, 31, v158
	v_ashrrev_i32_e32 v161, 31, v160
	v_ashrrev_i32_e32 v131, 31, v130
	s_add_u32 s12, s15, s12
	v_lshlrev_b64 v[134:135], 5, v[134:135]
	v_lshlrev_b64 v[136:137], 5, v[136:137]
	v_lshlrev_b64 v[138:139], 5, v[138:139]
	v_lshlrev_b64 v[140:141], 5, v[140:141]
	v_lshlrev_b64 v[142:143], 5, v[142:143]
	v_lshlrev_b64 v[144:145], 5, v[144:145]
	v_lshlrev_b64 v[146:147], 5, v[146:147]
	v_lshlrev_b64 v[148:149], 5, v[148:149]
	v_lshlrev_b64 v[150:151], 5, v[150:151]
	v_lshlrev_b64 v[152:153], 5, v[152:153]
	v_lshlrev_b64 v[154:155], 5, v[154:155]
	v_lshlrev_b64 v[156:157], 5, v[156:157]
	v_lshlrev_b64 v[158:159], 5, v[158:159]
	v_lshlrev_b64 v[160:161], 5, v[160:161]
	v_lshlrev_b64 v[162:163], 5, v[130:131]
	s_addc_u32 s13, s48, s13
	s_mov_b32 s14, 0
	v_lshl_add_u64 v[130:131], v[0:1], 1, s[12:13]
	v_lshl_add_u64 v[132:133], s[42:43], 0, v[132:133]
	v_lshl_add_u64 v[134:135], s[42:43], 0, v[134:135]
	v_lshl_add_u64 v[136:137], s[42:43], 0, v[136:137]
	v_lshl_add_u64 v[138:139], s[42:43], 0, v[138:139]
	v_lshl_add_u64 v[140:141], s[42:43], 0, v[140:141]
	v_lshl_add_u64 v[142:143], s[42:43], 0, v[142:143]
	v_lshl_add_u64 v[144:145], s[42:43], 0, v[144:145]
	v_lshl_add_u64 v[146:147], s[42:43], 0, v[146:147]
	v_lshl_add_u64 v[148:149], s[42:43], 0, v[148:149]
	v_lshl_add_u64 v[150:151], s[42:43], 0, v[150:151]
	v_lshl_add_u64 v[152:153], s[42:43], 0, v[152:153]
	v_lshl_add_u64 v[154:155], s[42:43], 0, v[154:155]
	v_lshl_add_u64 v[156:157], s[42:43], 0, v[156:157]
	v_lshl_add_u64 v[158:159], s[42:43], 0, v[158:159]
	v_lshl_add_u64 v[160:161], s[42:43], 0, v[160:161]
	v_lshl_add_u64 v[162:163], s[42:43], 0, v[162:163]
	s_mov_b64 s[46:47], -1
	v_add_u32_e32 v0, v164, v165
	v_mov_b32_e32 v243, 0x7f800000
	s_branch .LBB0_197

.LBB0_643:
	s_mul_i32 s44, s43, 0x6000
	s_add_i32 s45, s44, 0xffffa000
	s_cmp_gt_i32 s43, 0
	s_waitcnt vmcnt(6)
	s_cselect_b32 s45, s45, 0xc000
	s_waitcnt lgkmcnt(0)
	s_barrier
	s_setprio 2
	v_add3_u32 v0, s44, v177, v176
	v_add_u32_e32 v0, s55, v0
	v_add3_u32 v212, s44, v178, v176
	ds_read_b128 v[202:205], v212 offset:8192
	ds_read_b128 v[180:183], v0
	ds_read_b128 v[184:187], v0 offset:1024
	ds_read_b128 v[188:191], v0 offset:2048
	ds_read_b128 v[198:201], v0 offset:3072
	ds_read_b128 v[234:237], v212 offset:9216
	ds_read_b128 v[238:241], v212 offset:10240
	ds_read_b128 v[242:245], v212 offset:11264
	ds_read_b128 v[246:249], v212 offset:12288
	ds_read_b128 v[226:229], v212 offset:13312
	ds_read_b128 v[216:219], v212 offset:14336
	ds_read_b128 v[230:233], v212 offset:15360
	s_waitcnt lgkmcnt(10)
	v_mfma_f32_16x16x32_bf16 v[34:37], v[202:205], v[180:183], v[34:37]
	s_waitcnt lgkmcnt(9)
	v_mfma_f32_16x16x32_bf16 v[38:41], v[202:205], v[184:187], v[38:41]
	s_waitcnt lgkmcnt(8)
	v_mfma_f32_16x16x32_bf16 v[42:45], v[202:205], v[188:191], v[42:45]
	s_waitcnt lgkmcnt(7)
	v_mfma_f32_16x16x32_bf16 v[46:49], v[202:205], v[198:201], v[46:49]
	v_lshl_add_u64 v[212:213], v[174:175], 0, s[12:13]
	v_lshl_add_u64 v[212:213], v[162:163], 1, v[212:213]
	s_add_i32 s68, s45, s42
	s_mov_b32 m0, s68
	s_nop 0
	global_load_lds_dwordx4 v[212:213], off
	v_lshl_add_u64 v[212:213], v[174:175], 0, s[12:13]
	v_lshl_add_u64 v[212:213], v[164:165], 1, v[212:213]
	s_add_i32 s68, s45, s40
	s_mov_b32 m0, s68
	s_nop 0
	global_load_lds_dwordx4 v[212:213], off
	s_add_i32 s45, s41, s45
	v_lshl_add_u64 v[212:213], v[172:173], 0, s[12:13]
	s_mov_b32 m0, s45
	s_nop 0
	global_load_lds_dwordx4 v[212:213], off
	v_lshl_add_u64 v[212:213], v[170:171], 0, s[12:13]
	s_add_i32 s68, s45, 0x400
	s_mov_b32 m0, s68
	s_nop 0
	global_load_lds_dwordx4 v[212:213], off
	v_lshl_add_u64 v[212:213], v[168:169], 0, s[12:13]
	s_add_i32 s68, s45, 0x800
	s_mov_b32 m0, s68
	s_nop 0
	global_load_lds_dwordx4 v[212:213], off
	s_addk_i32 s45, 0xc00
	v_lshl_add_u64 v[212:213], v[166:167], 0, s[12:13]
	s_mov_b32 m0, s45
	s_nop 0
	global_load_lds_dwordx4 v[212:213], off
	s_setprio 0
	s_waitcnt lgkmcnt(6)
	v_mfma_f32_16x16x32_bf16 v[50:53], v[234:237], v[180:183], v[50:53]
	v_mfma_f32_16x16x32_bf16 v[54:57], v[234:237], v[184:187], v[54:57]
	v_mfma_f32_16x16x32_bf16 v[58:61], v[234:237], v[188:191], v[58:61]
	v_mfma_f32_16x16x32_bf16 v[62:65], v[234:237], v[198:201], v[62:65]
	s_waitcnt lgkmcnt(5)
	v_mfma_f32_16x16x32_bf16 v[66:69], v[238:241], v[180:183], v[66:69]
	v_mfma_f32_16x16x32_bf16 v[70:73], v[238:241], v[184:187], v[70:73]
	v_mfma_f32_16x16x32_bf16 v[74:77], v[238:241], v[188:191], v[74:77]
	v_mfma_f32_16x16x32_bf16 v[78:81], v[238:241], v[198:201], v[78:81]
	s_waitcnt lgkmcnt(4)
	v_mfma_f32_16x16x32_bf16 v[82:85], v[242:245], v[180:183], v[82:85]
	v_mfma_f32_16x16x32_bf16 v[86:89], v[242:245], v[184:187], v[86:89]
	v_mfma_f32_16x16x32_bf16 v[90:93], v[242:245], v[188:191], v[90:93]
	v_mfma_f32_16x16x32_bf16 v[94:97], v[242:245], v[198:201], v[94:97]
	s_waitcnt lgkmcnt(3)
	v_mfma_f32_16x16x32_bf16 v[98:101], v[246:249], v[180:183], v[98:101]
	v_mfma_f32_16x16x32_bf16 v[102:105], v[246:249], v[184:187], v[102:105]
	v_mfma_f32_16x16x32_bf16 v[106:109], v[246:249], v[188:191], v[106:109]
	v_mfma_f32_16x16x32_bf16 v[110:113], v[246:249], v[198:201], v[110:113]
	s_waitcnt lgkmcnt(2)
	v_mfma_f32_16x16x32_bf16 v[114:117], v[226:229], v[180:183], v[114:117]
	v_mfma_f32_16x16x32_bf16 v[118:121], v[226:229], v[184:187], v[118:121]
	v_mfma_f32_16x16x32_bf16 v[122:125], v[226:229], v[188:191], v[122:125]
	v_mfma_f32_16x16x32_bf16 v[126:129], v[226:229], v[198:201], v[126:129]
	s_waitcnt lgkmcnt(1)
	v_mfma_f32_16x16x32_bf16 v[130:133], v[216:219], v[180:183], v[130:133]
	v_mfma_f32_16x16x32_bf16 v[134:137], v[216:219], v[184:187], v[134:137]
	v_mfma_f32_16x16x32_bf16 v[138:141], v[216:219], v[188:191], v[138:141]
	v_mfma_f32_16x16x32_bf16 v[142:145], v[216:219], v[198:201], v[142:145]
	s_waitcnt lgkmcnt(0)
	v_mfma_f32_16x16x32_bf16 v[146:149], v[230:233], v[180:183], v[146:149]
	v_mfma_f32_16x16x32_bf16 v[150:153], v[230:233], v[184:187], v[150:153]
	v_mfma_f32_16x16x32_bf16 v[154:157], v[230:233], v[188:191], v[154:157]
	v_mfma_f32_16x16x32_bf16 v[158:161], v[230:233], v[198:201], v[158:161]
	s_add_i32 s44, s43, 1
	s_cmp_lg_u32 s43, 2
	s_cselect_b32 s43, s44, 0
	s_add_u32 s12, s12, 64
	s_addc_u32 s13, s13, 0
	s_cmpk_eq_i32 s12, 0x780
	s_cbranch_scc0 .LBB0_643
	s_waitcnt vmcnt(6)
	v_mov_b32_e32 v162, v19
	v_mov_b32_e32 v163, v20
	v_mov_b32_e32 v19, v21
	v_mov_b32_e32 v164, v3
	v_mov_b32_e32 v165, v4
	v_pk_add_f32 v[18:19], v[162:163], v[18:19]
	v_mov_b32_e32 v3, v5
	v_pk_add_f32 v[2:3], v[164:165], v[2:3]
	v_add_f32_e32 v0, v18, v19
	v_add_f32_e32 v0, v0, v2
	v_add_f32_e32 v0, v0, v3
	v_fmamk_f32 v0, v0, 0x3a800000, v250
	s_waitcnt vmcnt(4)
	v_mov_b32_e32 v166, v23
	v_mov_b32_e32 v167, v24
	v_mul_f32_e32 v2, 0x4b800000, v0
	v_cmp_gt_f32_e32 vcc, s80, v0
	v_mov_b32_e32 v23, v25
	v_mov_b32_e32 v168, v7
	v_mov_b32_e32 v169, v8
	v_cndmask_b32_e32 v0, v0, v2, vcc
	v_pk_add_f32 v[2:3], v[166:167], v[22:23]
	v_mov_b32_e32 v7, v9
	v_pk_add_f32 v[4:5], v[168:169], v[6:7]
	v_add_f32_e32 v2, v2, v3
	v_add_f32_e32 v2, v2, v4
	v_add_f32_e32 v2, v2, v5
	v_fmamk_f32 v2, v2, 0x3a800000, v250
	v_mul_f32_e32 v3, 0x4b800000, v2
	v_cmp_gt_f32_e64 s[40:41], s80, v2
	s_waitcnt vmcnt(2)
	v_mov_b32_e32 v170, v27
	v_mov_b32_e32 v171, v28
	v_cndmask_b32_e64 v2, v2, v3, s[40:41]
	v_mov_b32_e32 v27, v29
	v_mov_b32_e32 v172, v11
	v_mov_b32_e32 v173, v12
	v_rsq_f32_e32 v179, v2
	v_pk_add_f32 v[2:3], v[170:171], v[26:27]
	v_mov_b32_e32 v11, v13
	v_pk_add_f32 v[4:5], v[172:173], v[10:11]
	v_add_f32_e32 v2, v2, v3
	v_add_f32_e32 v2, v2, v4
	v_add_f32_e32 v2, v2, v5
	v_fmamk_f32 v2, v2, 0x3a800000, v250
	v_mul_f32_e32 v3, 0x4b800000, v2
	v_cmp_gt_f32_e64 s[42:43], s80, v2
	s_waitcnt vmcnt(0)
	v_mov_b32_e32 v174, v31
	v_mov_b32_e32 v175, v32
	v_cndmask_b32_e64 v2, v2, v3, s[42:43]
	v_mov_b32_e32 v31, v33
	v_mov_b32_e32 v180, v15
	v_mov_b32_e32 v181, v16
	v_rsq_f32_e32 v182, v2
	v_pk_add_f32 v[2:3], v[174:175], v[30:31]
	v_mov_b32_e32 v15, v17
	v_pk_add_f32 v[4:5], v[180:181], v[14:15]
	v_add_f32_e32 v2, v2, v3
	v_add_f32_e32 v2, v2, v4
	v_add_f32_e32 v2, v2, v5
	v_fmamk_f32 v2, v2, 0x3a800000, v250
	v_mul_f32_e32 v3, 0x4b800000, v2
	v_cmp_gt_f32_e64 s[44:45], s80, v2
	s_waitcnt vmcnt(6)
	v_add_u32_e32 v183, v178, v176
	s_waitcnt lgkmcnt(0)
	s_barrier
	v_cndmask_b32_e64 v2, v2, v3, s[44:45]
	v_rsq_f32_e32 v180, v2
	ds_read_b128 v[2:5], v183 offset:15360
	ds_read_b128 v[6:9], v183 offset:14336
	ds_read_b128 v[10:13], v183 offset:13312
	ds_read_b128 v[14:17], v183 offset:12288
	ds_read_b128 v[18:21], v183 offset:11264
	ds_read_b128 v[22:25], v183 offset:10240
	ds_read_b128 v[26:29], v183 offset:9216
	ds_read_b128 v[30:33], v183 offset:8192
	v_add3_u32 v178, s55, v177, v176
	ds_read_b128 v[162:165], v178 offset:3072
	ds_read_b128 v[166:169], v178 offset:2048
	ds_read_b128 v[170:173], v178 offset:1024
	ds_read_b128 v[174:177], v178
	v_rsq_f32_e32 v0, v0
	v_mul_f32_e32 v184, 0x45800000, v179
	v_mul_f32_e32 v185, 0x45800000, v182
	v_mul_f32_e32 v186, 0x45800000, v180
	v_mul_f32_e32 v181, 0x45800000, v0
	s_waitcnt lgkmcnt(0)
	v_mfma_f32_16x16x32_bf16 v[34:37], v[30:33], v[174:177], v[34:37]
	v_mfma_f32_16x16x32_bf16 v[38:41], v[30:33], v[170:173], v[38:41]
	v_mfma_f32_16x16x32_bf16 v[42:45], v[30:33], v[166:169], v[42:45]
	v_mfma_f32_16x16x32_bf16 v[30:33], v[30:33], v[162:165], v[46:49]
	v_mfma_f32_16x16x32_bf16 v[46:49], v[26:29], v[174:177], v[50:53]
	v_mfma_f32_16x16x32_bf16 v[50:53], v[26:29], v[170:173], v[54:57]
	v_mfma_f32_16x16x32_bf16 v[54:57], v[26:29], v[166:169], v[58:61]
	v_mfma_f32_16x16x32_bf16 v[58:61], v[26:29], v[162:165], v[62:65]
	v_mfma_f32_16x16x32_bf16 v[62:65], v[22:25], v[174:177], v[66:69]
	v_mfma_f32_16x16x32_bf16 v[66:69], v[22:25], v[170:173], v[70:73]
	v_mfma_f32_16x16x32_bf16 v[70:73], v[22:25], v[166:169], v[74:77]
	v_mfma_f32_16x16x32_bf16 v[74:77], v[22:25], v[162:165], v[78:81]
	v_mfma_f32_16x16x32_bf16 v[78:81], v[18:21], v[174:177], v[82:85]
	v_mfma_f32_16x16x32_bf16 v[82:85], v[18:21], v[170:173], v[86:89]
	v_mfma_f32_16x16x32_bf16 v[86:89], v[18:21], v[166:169], v[90:93]
	v_mfma_f32_16x16x32_bf16 v[18:21], v[18:21], v[162:165], v[94:97]
	v_mfma_f32_16x16x32_bf16 v[90:93], v[14:17], v[174:177], v[98:101]
	v_mfma_f32_16x16x32_bf16 v[94:97], v[14:17], v[170:173], v[102:105]
	v_mfma_f32_16x16x32_bf16 v[98:101], v[14:17], v[166:169], v[106:109]
	v_mfma_f32_16x16x32_bf16 v[14:17], v[14:17], v[162:165], v[110:113]
	v_mfma_f32_16x16x32_bf16 v[102:105], v[10:13], v[174:177], v[114:117]
	v_mfma_f32_16x16x32_bf16 v[106:109], v[10:13], v[170:173], v[118:121]
	v_mfma_f32_16x16x32_bf16 v[110:113], v[10:13], v[166:169], v[122:125]
	v_mfma_f32_16x16x32_bf16 v[10:13], v[10:13], v[162:165], v[126:129]
	v_mfma_f32_16x16x32_bf16 v[114:117], v[6:9], v[174:177], v[130:133]
	v_mfma_f32_16x16x32_bf16 v[118:121], v[6:9], v[170:173], v[134:137]
	v_mfma_f32_16x16x32_bf16 v[122:125], v[6:9], v[166:169], v[138:141]
	v_mfma_f32_16x16x32_bf16 v[6:9], v[6:9], v[162:165], v[142:145]
	v_mfma_f32_16x16x32_bf16 v[126:129], v[2:5], v[174:177], v[146:149]
	v_mfma_f32_16x16x32_bf16 v[130:133], v[2:5], v[170:173], v[150:153]
	v_mfma_f32_16x16x32_bf16 v[134:137], v[2:5], v[166:169], v[154:157]
	v_mfma_f32_16x16x32_bf16 v[2:5], v[2:5], v[162:165], v[158:161]
	s_waitcnt vmcnt(0)
	v_cndmask_b32_e32 v26, v0, v181, vcc
	v_cndmask_b32_e64 v24, v179, v184, s[40:41]
	v_cndmask_b32_e64 v22, v182, v185, s[42:43]
	v_cndmask_b32_e64 v0, v180, v186, s[44:45]
	s_waitcnt lgkmcnt(0)
	s_barrier
	ds_read_b128 v[138:141], v178 offset:24576
	ds_read_b128 v[142:145], v178 offset:25600
	ds_read_b128 v[146:149], v178 offset:26624
	ds_read_b128 v[150:153], v178 offset:27648
	ds_read_b128 v[154:157], v183 offset:32768
	ds_read_b128 v[158:161], v183 offset:33792
	ds_read_b128 v[162:165], v183 offset:34816
	ds_read_b128 v[166:169], v183 offset:35840
	ds_read_b128 v[170:173], v183 offset:36864
	ds_read_b128 v[174:177], v183 offset:37888
	ds_read_b128 v[178:181], v183 offset:38912
	ds_read_b128 v[182:185], v183 offset:39936
	s_waitcnt lgkmcnt(7)
	v_mfma_f32_16x16x32_bf16 v[34:37], v[154:157], v[138:141], v[34:37]
	v_mfma_f32_16x16x32_bf16 v[38:41], v[154:157], v[142:145], v[38:41]
	v_mfma_f32_16x16x32_bf16 v[42:45], v[154:157], v[146:149], v[42:45]
	v_mfma_f32_16x16x32_bf16 v[28:31], v[154:157], v[150:153], v[30:33]
	s_waitcnt lgkmcnt(6)
	v_mfma_f32_16x16x32_bf16 v[46:49], v[158:161], v[138:141], v[46:49]
	v_mfma_f32_16x16x32_bf16 v[50:53], v[158:161], v[142:145], v[50:53]
	v_mfma_f32_16x16x32_bf16 v[54:57], v[158:161], v[146:149], v[54:57]
	v_mfma_f32_16x16x32_bf16 v[58:61], v[158:161], v[150:153], v[58:61]
	s_waitcnt lgkmcnt(5)
	v_mfma_f32_16x16x32_bf16 v[62:65], v[162:165], v[138:141], v[62:65]
	v_mfma_f32_16x16x32_bf16 v[66:69], v[162:165], v[142:145], v[66:69]
	v_mfma_f32_16x16x32_bf16 v[70:73], v[162:165], v[146:149], v[70:73]
	v_mfma_f32_16x16x32_bf16 v[74:77], v[162:165], v[150:153], v[74:77]
	s_waitcnt lgkmcnt(4)
	v_mfma_f32_16x16x32_bf16 v[78:81], v[166:169], v[138:141], v[78:81]
	v_mfma_f32_16x16x32_bf16 v[82:85], v[166:169], v[142:145], v[82:85]
	v_mfma_f32_16x16x32_bf16 v[86:89], v[166:169], v[146:149], v[86:89]
	v_mfma_f32_16x16x32_bf16 v[154:157], v[166:169], v[150:153], v[18:21]
	s_waitcnt lgkmcnt(3)
	v_mfma_f32_16x16x32_bf16 v[90:93], v[170:173], v[138:141], v[90:93]
	v_mfma_f32_16x16x32_bf16 v[94:97], v[170:173], v[142:145], v[94:97]
	v_mfma_f32_16x16x32_bf16 v[98:101], v[170:173], v[146:149], v[98:101]
	v_mfma_f32_16x16x32_bf16 v[158:161], v[170:173], v[150:153], v[14:17]
	s_waitcnt lgkmcnt(2)
	v_mfma_f32_16x16x32_bf16 v[102:105], v[174:177], v[138:141], v[102:105]
	v_mfma_f32_16x16x32_bf16 v[106:109], v[174:177], v[142:145], v[106:109]
	v_mfma_f32_16x16x32_bf16 v[110:113], v[174:177], v[146:149], v[110:113]
	v_mfma_f32_16x16x32_bf16 v[162:165], v[174:177], v[150:153], v[10:13]
	s_waitcnt lgkmcnt(1)
	v_mfma_f32_16x16x32_bf16 v[114:117], v[178:181], v[138:141], v[114:117]
	v_mfma_f32_16x16x32_bf16 v[118:121], v[178:181], v[142:145], v[118:121]
	v_mfma_f32_16x16x32_bf16 v[122:125], v[178:181], v[146:149], v[122:125]
	v_mfma_f32_16x16x32_bf16 v[18:21], v[178:181], v[150:153], v[6:9]
	s_waitcnt lgkmcnt(0)
	v_mfma_f32_16x16x32_bf16 v[14:17], v[182:185], v[138:141], v[126:129]
	v_mfma_f32_16x16x32_bf16 v[10:13], v[182:185], v[142:145], v[130:133]
	v_mfma_f32_16x16x32_bf16 v[6:9], v[182:185], v[146:149], v[134:137]
	v_mfma_f32_16x16x32_bf16 v[2:5], v[182:185], v[150:153], v[2:5]
	v_mov_b32_e32 v23, v224
	s_movk_i32 s12, 0x210
	v_lshrrev_b32_e32 v32, 1, v23
	v_and_b32_e32 v27, 0x7fffff80, v23
	v_and_b32_e32 v32, 24, v32
	v_and_b32_e32 v25, 0x4f, v23
	v_lshl_or_b32 v27, v27, 1, v32
	v_pk_mul_f32 v[32:33], v[26:27], v[34:35] op_sel_hi:[0,1]
	v_pk_mul_f32 v[34:35], v[26:27], v[36:37] op_sel_hi:[0,1]
	v_mad_u32_u24 v25, v25, s12, v27
	v_cvt_pk_bf16_f32 v32, v32, v33
	v_cvt_pk_bf16_f32 v33, v34, v35
	v_pk_mul_f32 v[34:35], v[24:25], v[38:39] op_sel_hi:[0,1]
	v_pk_mul_f32 v[36:37], v[24:25], v[40:41] op_sel_hi:[0,1]
	v_cvt_pk_bf16_f32 v34, v34, v35
	v_cvt_pk_bf16_f32 v35, v36, v37
	v_pk_mul_f32 v[36:37], v[22:23], v[42:43] op_sel_hi:[0,1]
	v_pk_mul_f32 v[38:39], v[22:23], v[44:45] op_sel_hi:[0,1]
	v_pk_mul_f32 v[28:29], v[0:1], v[28:29] op_sel_hi:[0,1]
	v_pk_mul_f32 v[30:31], v[0:1], v[30:31] op_sel_hi:[0,1]
	v_cvt_pk_bf16_f32 v36, v36, v37
	v_cvt_pk_bf16_f32 v37, v38, v39
	v_cvt_pk_bf16_f32 v28, v28, v29
	v_cvt_pk_bf16_f32 v29, v30, v31
	v_pk_mul_f32 v[30:31], v[26:27], v[46:47] op_sel_hi:[0,1]
	v_pk_mul_f32 v[38:39], v[26:27], v[48:49] op_sel_hi:[0,1]
	v_cvt_pk_bf16_f32 v30, v30, v31
	v_cvt_pk_bf16_f32 v31, v38, v39
	s_barrier
	ds_write2_b64 v25, v[32:33], v[30:31] offset1:4
	v_pk_mul_f32 v[30:31], v[24:25], v[50:51] op_sel_hi:[0,1]
	v_pk_mul_f32 v[32:33], v[24:25], v[52:53] op_sel_hi:[0,1]
	v_cvt_pk_bf16_f32 v30, v30, v31
	v_cvt_pk_bf16_f32 v31, v32, v33
	v_add_u32_e32 v27, 0x2000, v25
	ds_write2_b64 v27, v[34:35], v[30:31] offset0:32 offset1:36
	v_pk_mul_f32 v[30:31], v[22:23], v[54:55] op_sel_hi:[0,1]
	v_pk_mul_f32 v[32:33], v[22:23], v[56:57] op_sel_hi:[0,1]
	v_cvt_pk_bf16_f32 v30, v30, v31
	v_cvt_pk_bf16_f32 v31, v32, v33
	v_add_u32_e32 v40, 0x4000, v25
	ds_write2_b64 v40, v[36:37], v[30:31] offset0:64 offset1:68
	v_pk_mul_f32 v[30:31], v[0:1], v[58:59] op_sel_hi:[0,1]
	v_pk_mul_f32 v[32:33], v[0:1], v[60:61] op_sel_hi:[0,1]
	v_cvt_pk_bf16_f32 v30, v30, v31
	v_cvt_pk_bf16_f32 v31, v32, v33
	v_add_u32_e32 v41, 0x6000, v25
	ds_write2_b64 v41, v[28:29], v[30:31] offset0:96 offset1:100
	v_pk_mul_f32 v[28:29], v[26:27], v[62:63] op_sel_hi:[0,1]
	v_pk_mul_f32 v[30:31], v[26:27], v[64:65] op_sel_hi:[0,1]
	v_cvt_pk_bf16_f32 v28, v28, v29
	v_cvt_pk_bf16_f32 v29, v30, v31
	v_pk_mul_f32 v[30:31], v[24:25], v[66:67] op_sel_hi:[0,1]
	v_pk_mul_f32 v[32:33], v[24:25], v[68:69] op_sel_hi:[0,1]
	v_cvt_pk_bf16_f32 v30, v30, v31
	v_cvt_pk_bf16_f32 v31, v32, v33
	v_pk_mul_f32 v[32:33], v[22:23], v[70:71] op_sel_hi:[0,1]
	v_pk_mul_f32 v[34:35], v[22:23], v[72:73] op_sel_hi:[0,1]
	v_cvt_pk_bf16_f32 v32, v32, v33
	v_cvt_pk_bf16_f32 v33, v34, v35
	v_pk_mul_f32 v[34:35], v[0:1], v[74:75] op_sel_hi:[0,1]
	v_pk_mul_f32 v[36:37], v[0:1], v[76:77] op_sel_hi:[0,1]
	v_cvt_pk_bf16_f32 v34, v34, v35
	v_cvt_pk_bf16_f32 v35, v36, v37
	v_pk_mul_f32 v[36:37], v[26:27], v[78:79] op_sel_hi:[0,1]
	v_pk_mul_f32 v[38:39], v[26:27], v[80:81] op_sel_hi:[0,1]
	v_cvt_pk_bf16_f32 v36, v36, v37
	v_cvt_pk_bf16_f32 v37, v38, v39
	ds_write2_b64 v25, v[28:29], v[36:37] offset0:8 offset1:12
	v_pk_mul_f32 v[28:29], v[24:25], v[82:83] op_sel_hi:[0,1]
	v_pk_mul_f32 v[36:37], v[24:25], v[84:85] op_sel_hi:[0,1]
	v_cvt_pk_bf16_f32 v28, v28, v29
	v_cvt_pk_bf16_f32 v29, v36, v37
	ds_write2_b64 v27, v[30:31], v[28:29] offset0:40 offset1:44
	v_pk_mul_f32 v[28:29], v[22:23], v[86:87] op_sel_hi:[0,1]
	v_pk_mul_f32 v[30:31], v[22:23], v[88:89] op_sel_hi:[0,1]
	v_cvt_pk_bf16_f32 v28, v28, v29
	v_cvt_pk_bf16_f32 v29, v30, v31
	ds_write2_b64 v40, v[32:33], v[28:29] offset0:72 offset1:76
	v_pk_mul_f32 v[28:29], v[0:1], v[154:155] op_sel_hi:[0,1]
	v_pk_mul_f32 v[30:31], v[0:1], v[156:157] op_sel_hi:[0,1]
	v_cvt_pk_bf16_f32 v28, v28, v29
	v_cvt_pk_bf16_f32 v29, v30, v31
	ds_write2_b64 v41, v[34:35], v[28:29] offset0:104 offset1:108
	v_pk_mul_f32 v[28:29], v[26:27], v[90:91] op_sel_hi:[0,1]
	v_pk_mul_f32 v[30:31], v[26:27], v[92:93] op_sel_hi:[0,1]
	v_cvt_pk_bf16_f32 v28, v28, v29
	v_cvt_pk_bf16_f32 v29, v30, v31
	v_pk_mul_f32 v[30:31], v[24:25], v[94:95] op_sel_hi:[0,1]
	v_pk_mul_f32 v[32:33], v[24:25], v[96:97] op_sel_hi:[0,1]
	v_cvt_pk_bf16_f32 v30, v30, v31
	v_cvt_pk_bf16_f32 v31, v32, v33
	v_pk_mul_f32 v[32:33], v[22:23], v[98:99] op_sel_hi:[0,1]
	v_pk_mul_f32 v[34:35], v[22:23], v[100:101] op_sel_hi:[0,1]
	v_cvt_pk_bf16_f32 v32, v32, v33
	v_cvt_pk_bf16_f32 v33, v34, v35
	v_pk_mul_f32 v[34:35], v[0:1], v[158:159] op_sel_hi:[0,1]
	v_pk_mul_f32 v[36:37], v[0:1], v[160:161] op_sel_hi:[0,1]
	v_cvt_pk_bf16_f32 v34, v34, v35
	v_cvt_pk_bf16_f32 v35, v36, v37
	v_pk_mul_f32 v[36:37], v[26:27], v[102:103] op_sel_hi:[0,1]
	v_pk_mul_f32 v[38:39], v[26:27], v[104:105] op_sel_hi:[0,1]
	v_cvt_pk_bf16_f32 v36, v36, v37
	v_cvt_pk_bf16_f32 v37, v38, v39
	ds_write2_b64 v25, v[28:29], v[36:37] offset0:16 offset1:20
	v_pk_mul_f32 v[28:29], v[24:25], v[106:107] op_sel_hi:[0,1]
	v_pk_mul_f32 v[36:37], v[24:25], v[108:109] op_sel_hi:[0,1]
	v_cvt_pk_bf16_f32 v28, v28, v29
	v_cvt_pk_bf16_f32 v29, v36, v37
	ds_write2_b64 v27, v[30:31], v[28:29] offset0:48 offset1:52
	v_pk_mul_f32 v[28:29], v[22:23], v[110:111] op_sel_hi:[0,1]
	v_pk_mul_f32 v[30:31], v[22:23], v[112:113] op_sel_hi:[0,1]
	v_cvt_pk_bf16_f32 v28, v28, v29
	v_cvt_pk_bf16_f32 v29, v30, v31
	ds_write2_b64 v40, v[32:33], v[28:29] offset0:80 offset1:84
	v_pk_mul_f32 v[28:29], v[0:1], v[162:163] op_sel_hi:[0,1]
	v_pk_mul_f32 v[30:31], v[0:1], v[164:165] op_sel_hi:[0,1]
	v_cvt_pk_bf16_f32 v28, v28, v29
	v_cvt_pk_bf16_f32 v29, v30, v31
	ds_write2_b64 v41, v[34:35], v[28:29] offset0:112 offset1:116
	v_pk_mul_f32 v[28:29], v[26:27], v[114:115] op_sel_hi:[0,1]
	v_pk_mul_f32 v[30:31], v[26:27], v[116:117] op_sel_hi:[0,1]
	v_pk_mul_f32 v[18:19], v[0:1], v[18:19] op_sel_hi:[0,1]
	v_pk_mul_f32 v[20:21], v[0:1], v[20:21] op_sel_hi:[0,1]
	v_pk_mul_f32 v[2:3], v[0:1], v[2:3] op_sel_hi:[0,1]
	v_pk_mul_f32 v[4:5], v[0:1], v[4:5] op_sel_hi:[0,1]
	v_lshlrev_b32_e32 v0, 3, v23
	v_cvt_pk_bf16_f32 v28, v28, v29
	v_cvt_pk_bf16_f32 v29, v30, v31
	v_pk_mul_f32 v[30:31], v[24:25], v[118:119] op_sel_hi:[0,1]
	v_pk_mul_f32 v[32:33], v[24:25], v[120:121] op_sel_hi:[0,1]
	v_cvt_pk_bf16_f32 v18, v18, v19
	v_cvt_pk_bf16_f32 v19, v20, v21
	v_cvt_pk_bf16_f32 v2, v2, v3
	v_cvt_pk_bf16_f32 v3, v4, v5
	v_and_b32_e32 v0, 0xf8, v0
	v_cvt_pk_bf16_f32 v30, v30, v31
	v_cvt_pk_bf16_f32 v31, v32, v33
	v_pk_mul_f32 v[32:33], v[22:23], v[122:123] op_sel_hi:[0,1]
	v_pk_mul_f32 v[34:35], v[22:23], v[124:125] op_sel_hi:[0,1]
	v_pk_mul_f32 v[14:15], v[26:27], v[14:15] op_sel_hi:[0,1]
	v_pk_mul_f32 v[16:17], v[26:27], v[16:17] op_sel_hi:[0,1]
	v_pk_mul_f32 v[10:11], v[24:25], v[10:11] op_sel_hi:[0,1]
	v_pk_mul_f32 v[12:13], v[24:25], v[12:13] op_sel_hi:[0,1]
	v_pk_mul_f32 v[6:7], v[22:23], v[6:7] op_sel_hi:[0,1]
	v_pk_mul_f32 v[8:9], v[22:23], v[8:9] op_sel_hi:[0,1]
	ds_write2_b64 v41, v[18:19], v[2:3] offset0:120 offset1:124
	v_or_b32_e32 v2, s54, v0
	s_movk_i32 s12, 0xa30
	v_cvt_pk_bf16_f32 v32, v32, v33
	v_cvt_pk_bf16_f32 v33, v34, v35
	v_cvt_pk_bf16_f32 v14, v14, v15
	v_cvt_pk_bf16_f32 v15, v16, v17
	v_cvt_pk_bf16_f32 v10, v10, v11
	v_cvt_pk_bf16_f32 v11, v12, v13
	v_cvt_pk_bf16_f32 v6, v6, v7
	v_cvt_pk_bf16_f32 v7, v8, v9
	v_cmp_gt_i32_e32 vcc, s12, v2
	ds_write2_b64 v25, v[28:29], v[14:15] offset0:24 offset1:28
	ds_write2_b64 v27, v[30:31], v[10:11] offset0:56 offset1:60
	ds_write2_b64 v40, v[32:33], v[6:7] offset0:88 offset1:92
	s_waitcnt lgkmcnt(0)
	s_barrier
	s_and_saveexec_b64 s[12:13], vcc
	s_cbranch_execz .LBB0_641
	v_ashrrev_i32_e32 v8, 5, v23
	v_lshlrev_b32_e32 v0, 1, v0
	s_movk_i32 s40, 0x210
	v_mad_u64_u32 v[6:7], s[40:41], v8, s40, v[0:1]
	ds_read_b128 v[2:5], v6
	v_add_u32_e32 v7, s57, v8
	v_mov_b64_e32 v[8:9], s[4:5]
	s_ashr_i32 s55, s54, 31
	v_mad_i64_i32 v[10:11], s[40:41], v7, s16, v[8:9]
	s_lshl_b64 s[40:41], s[54:55], 1
	s_nop 0
	v_lshl_add_u64 v[10:11], v[10:11], 0, s[40:41]
	v_lshl_add_u64 v[10:11], v[10:11], 0, v[0:1]
	s_waitcnt lgkmcnt(0)
	global_store_dwordx4 v[10:11], v[2:5], off
	ds_read_b128 v[2:5], v6 offset:4224
	v_add_u32_e32 v10, 8, v7
	v_mad_i64_i32 v[10:11], s[42:43], v10, s16, v[8:9]
	v_lshl_add_u64 v[10:11], v[10:11], 0, s[40:41]
	v_lshl_add_u64 v[10:11], v[10:11], 0, v[0:1]
	s_waitcnt lgkmcnt(0)
	global_store_dwordx4 v[10:11], v[2:5], off
	ds_read_b128 v[2:5], v6 offset:8448
	v_add_u32_e32 v10, 16, v7
	v_mad_i64_i32 v[10:11], s[42:43], v10, s16, v[8:9]
	v_lshl_add_u64 v[10:11], v[10:11], 0, s[40:41]
	v_lshl_add_u64 v[10:11], v[10:11], 0, v[0:1]
	s_waitcnt lgkmcnt(0)
	global_store_dwordx4 v[10:11], v[2:5], off
	ds_read_b128 v[2:5], v6 offset:12672
	v_add_u32_e32 v10, 24, v7
	v_mad_i64_i32 v[10:11], s[42:43], v10, s16, v[8:9]
	v_lshl_add_u64 v[10:11], v[10:11], 0, s[40:41]
	v_lshl_add_u64 v[10:11], v[10:11], 0, v[0:1]
	s_waitcnt lgkmcnt(0)
	global_store_dwordx4 v[10:11], v[2:5], off
	ds_read_b128 v[2:5], v6 offset:16896
	v_add_u32_e32 v10, 32, v7
	v_mad_i64_i32 v[10:11], s[42:43], v10, s16, v[8:9]
	v_lshl_add_u64 v[10:11], v[10:11], 0, s[40:41]
	v_lshl_add_u64 v[10:11], v[10:11], 0, v[0:1]
	s_waitcnt lgkmcnt(0)
	global_store_dwordx4 v[10:11], v[2:5], off
	ds_read_b128 v[2:5], v6 offset:21120
	v_add_u32_e32 v10, 40, v7
	v_mad_i64_i32 v[10:11], s[42:43], v10, s16, v[8:9]
	v_lshl_add_u64 v[10:11], v[10:11], 0, s[40:41]
	v_lshl_add_u64 v[10:11], v[10:11], 0, v[0:1]
	s_waitcnt lgkmcnt(0)
	global_store_dwordx4 v[10:11], v[2:5], off
	ds_read_b128 v[2:5], v6 offset:25344
	v_add_u32_e32 v10, 48, v7
	v_mad_i64_i32 v[10:11], s[42:43], v10, s16, v[8:9]
	v_lshl_add_u64 v[10:11], v[10:11], 0, s[40:41]
	v_lshl_add_u64 v[10:11], v[10:11], 0, v[0:1]
	s_waitcnt lgkmcnt(0)
	global_store_dwordx4 v[10:11], v[2:5], off
	ds_read_b128 v[2:5], v6 offset:29568
	v_add_u32_e32 v10, 56, v7
	v_mad_i64_i32 v[10:11], s[42:43], v10, s16, v[8:9]
	v_lshl_add_u64 v[10:11], v[10:11], 0, s[40:41]
	v_lshl_add_u64 v[10:11], v[10:11], 0, v[0:1]
	s_waitcnt lgkmcnt(0)
	global_store_dwordx4 v[10:11], v[2:5], off
	ds_read_b128 v[2:5], v6 offset:33792
	v_add_u32_e32 v10, 64, v7
	v_mad_i64_i32 v[10:11], s[42:43], v10, s16, v[8:9]
	v_lshl_add_u64 v[10:11], v[10:11], 0, s[40:41]
	v_lshl_add_u64 v[10:11], v[10:11], 0, v[0:1]
	s_waitcnt lgkmcnt(0)
	global_store_dwordx4 v[10:11], v[2:5], off
	ds_read_b128 v[2:5], v6 offset:38016
	v_add_u32_e32 v10, 0x48, v7
	v_mad_i64_i32 v[10:11], s[42:43], v10, s16, v[8:9]
	v_lshl_add_u64 v[10:11], v[10:11], 0, s[40:41]
	v_lshl_add_u64 v[10:11], v[10:11], 0, v[0:1]
	s_waitcnt lgkmcnt(0)
	global_store_dwordx4 v[10:11], v[2:5], off
	ds_read_b128 v[2:5], v6 offset:42240
	v_add_u32_e32 v10, 0x50, v7
	v_mad_i64_i32 v[10:11], s[42:43], v10, s16, v[8:9]
	v_lshl_add_u64 v[10:11], v[10:11], 0, s[40:41]
	v_lshl_add_u64 v[10:11], v[10:11], 0, v[0:1]
	s_waitcnt lgkmcnt(0)
	global_store_dwordx4 v[10:11], v[2:5], off
	ds_read_b128 v[2:5], v6 offset:46464
	v_add_u32_e32 v10, 0x58, v7
	v_mad_i64_i32 v[10:11], s[42:43], v10, s16, v[8:9]
	v_lshl_add_u64 v[10:11], v[10:11], 0, s[40:41]
	v_lshl_add_u64 v[10:11], v[10:11], 0, v[0:1]
	s_waitcnt lgkmcnt(0)
	global_store_dwordx4 v[10:11], v[2:5], off
	ds_read_b128 v[2:5], v6 offset:50688
	v_add_u32_e32 v10, 0x60, v7
	v_mad_i64_i32 v[10:11], s[42:43], v10, s16, v[8:9]
	v_lshl_add_u64 v[10:11], v[10:11], 0, s[40:41]
	v_lshl_add_u64 v[10:11], v[10:11], 0, v[0:1]
	s_waitcnt lgkmcnt(0)
	global_store_dwordx4 v[10:11], v[2:5], off
	ds_read_b128 v[2:5], v6 offset:54912
	v_add_u32_e32 v10, 0x68, v7
	v_mad_i64_i32 v[10:11], s[42:43], v10, s16, v[8:9]
	v_lshl_add_u64 v[10:11], v[10:11], 0, s[40:41]
	v_lshl_add_u64 v[10:11], v[10:11], 0, v[0:1]
	s_waitcnt lgkmcnt(0)
	global_store_dwordx4 v[10:11], v[2:5], off
	ds_read_b128 v[2:5], v6 offset:59136
	v_add_u32_e32 v10, 0x70, v7
	v_mad_i64_i32 v[10:11], s[42:43], v10, s16, v[8:9]
	v_lshl_add_u64 v[10:11], v[10:11], 0, s[40:41]
	v_lshl_add_u64 v[10:11], v[10:11], 0, v[0:1]
	s_waitcnt lgkmcnt(0)
	global_store_dwordx4 v[10:11], v[2:5], off
	ds_read_b128 v[2:5], v6 offset:63360
	v_add_u32_e32 v6, 0x78, v7
	v_mad_i64_i32 v[6:7], s[42:43], v6, s16, v[8:9]
	v_lshl_add_u64 v[6:7], v[6:7], 0, s[40:41]
	v_lshl_add_u64 v[6:7], v[6:7], 0, v[0:1]
	s_waitcnt lgkmcnt(0)
	global_store_dwordx4 v[6:7], v[2:5], off
	s_branch .LBB0_641
